# HG in-proj forget-gate epilogue: lbq quads loaded once per tile (31 reloads + vmcnt(0) drains removed); first-barrier counter scan batched
# baseline (speedup 1.0000x reference)
; __device__ __forceinline__ unsigned cvt_pk_bf16(float lo, float hi) { unsigned r; asm("v_cvt_pk_bf16_f32 %0, %1, %2" : "=v"(r) : "v"(lo), "v"(hi)); return r; }
;     __device__ __forceinline__ void operator()(const f32x4 (&acc)[2][2][4][2], const Unit& u, int wr, int wc, int fr, int fq) const {
;     ...
;                 } else if (type == 4) {
;                     float* rp = (float*)base + (size_t)row * ld + col0 + cl; bf16_t* kp = (bf16_t*)(proj + (size_t)MP * 10240) + (size_t)row * ld + col0 + cl;
; #pragma unroll
;                     for (int bj = 0; bj < 2; ++bj) { f32x4 lfv[2], kkv[2];
; #pragma unroll
;                         for (int n = 0; n < 2; ++n) { const f32x4 lbq = *(const f32x4*)(lbp + col0 + cl + bj * 128 + 4 * n);
; #pragma unroll
;                             for (int e = 0; e < 4; ++e) { const float z = fminf(fmaxf(acc[ai][bj][m][n][e], -30.f), 30.f); const float sg = __builtin_amdgcn_rcpf(1.f + __expf(-z)); const float oml = 1.f - lbq[e];
;                                 lfv[n][e] = __logf(lbq[e] + oml * sg); kkv[n][e] = oml * (1.f - sg); }
;                             *(f32x4*)(rp + bj * 128 + 4 * n) = lfv[n]; }
;                         u32x4 w; w.x = cvt_pk_bf16(kkv[0][0], kkv[0][1]); w.y = cvt_pk_bf16(kkv[0][2], kkv[0][3]); w.z = cvt_pk_bf16(kkv[1][0], kkv[1][1]); w.w = cvt_pk_bf16(kkv[1][2], kkv[1][3]);
;                         *(u32x4*)(kp + bj * 128) = w; }
.LBB0_704:
	v_lshlrev_b32_e32 v16, 2, v142
	v_lshl_add_u64 v[174:175], s[18:19], 0, v[16:17]
	s_and_b64 vcc, exec, s[26:27]
	s_cbranch_vccz .LBB0_706
	s_lshl_b32 s18, s59, 2
	s_mov_b32 s19, s12
	v_lshl_add_u64 v[130:131], v[144:145], 0, s[18:19]
	global_load_dwordx4 v[204:207], v[130:131], off
	global_load_dwordx4 v[208:211], v[130:131], off offset:16
	global_load_dwordx4 v[212:215], v[130:131], off offset:512
	global_load_dwordx4 v[216:219], v[130:131], off offset:528
	v_lshlrev_b64 v[132:133], 12, v[172:173]
	v_max_f32_e32 v16, v126, v126
	v_max_f32_e32 v169, v127, v127
	v_max_f32_e32 v128, v128, v128
	v_lshl_add_u64 v[126:127], v[174:175], 0, v[132:133]
	v_med3_f32 v16, v16, s38, v194
	v_med3_f32 v132, v169, s38, v194
	v_med3_f32 v128, v128, s38, v194
	v_mul_f32_e32 v16, 0xbfb8aa3b, v16
	v_mul_f32_e32 v132, 0xbfb8aa3b, v132
	v_mul_f32_e32 v128, 0xbfb8aa3b, v128
	v_exp_f32_e32 v16, v16
	v_exp_f32_e32 v132, v132
	v_exp_f32_e32 v128, v128
	v_max_f32_e32 v129, v129, v129
	v_med3_f32 v129, v129, s38, v194
	v_mul_f32_e32 v129, 0xbfb8aa3b, v129
	v_exp_f32_e32 v129, v129
	v_add_f32_e32 v16, 1.0, v16
	v_add_f32_e32 v169, 1.0, v132
	v_add_f32_e32 v132, 1.0, v128
	v_rcp_f32_e32 v128, v16
	v_rcp_f32_e32 v132, v132
	v_add_f32_e32 v181, 1.0, v129
	v_max_f32_e32 v124, v124, v124
	s_mov_b32 s5, s12
	v_max_f32_e32 v125, v125, v125
	v_med3_f32 v124, v124, s38, v194
	v_med3_f32 v125, v125, s38, v194
	v_mul_f32_e32 v124, 0xbfb8aa3b, v124
	v_mul_f32_e32 v125, 0xbfb8aa3b, v125
	s_waitcnt vmcnt(0)
	v_mov_b64_e32 v[176:177], v[204:205]
	v_mov_b64_e32 v[178:179], v[206:207]
	v_mov_b32_e32 v129, v176
	v_mov_b32_e32 v133, v178
	v_pk_add_f32 v[196:197], v[128:129], 1.0 op_sel_hi:[1,0] neg_lo:[1,0] neg_hi:[1,0]
	v_pk_add_f32 v[202:203], v[132:133], 1.0 op_sel_hi:[1,0] neg_lo:[1,0] neg_hi:[1,0]
	v_fma_f32 v16, v128, v197, v176
	v_rcp_f32_e32 v176, v169
	v_fma_f32 v128, v132, v203, v178
	v_rcp_f32_e32 v178, v181
	v_cmp_gt_f32_e32 vcc, s31, v16
	v_cmp_gt_f32_e64 s[44:45], s31, v128
	s_nop 0
	v_cndmask_b32_e64 v129, 0, 32, vcc
	v_cndmask_b32_e64 v132, 0, 32, s[44:45]
	v_ldexp_f32 v16, v16, v129
	v_ldexp_f32 v128, v128, v132
	v_log_f32_e32 v16, v16
	v_log_f32_e32 v182, v128
	v_pk_add_f32 v[128:129], v[176:177], 1.0 op_sel_hi:[1,0] neg_lo:[1,0] neg_hi:[1,0]
	v_pk_add_f32 v[132:133], v[178:179], 1.0 op_sel_hi:[1,0] neg_lo:[1,0] neg_hi:[1,0]
	v_fma_f32 v176, v176, v129, v177
	v_cndmask_b32_e32 v169, 0, v191, vcc
	v_fmac_f32_e32 v179, v178, v133
	v_cmp_gt_f32_e32 vcc, s31, v176
	v_cndmask_b32_e64 v181, 0, v191, s[44:45]
	v_cmp_gt_f32_e64 s[44:45], s31, v179
	v_cndmask_b32_e64 v177, 0, 32, vcc
	v_mul_f32_e32 v183, 0x3f317217, v16
	v_cndmask_b32_e64 v178, 0, 32, s[44:45]
	v_ldexp_f32 v176, v176, v177
	v_mul_f32_e32 v184, 0x3f317217, v182
	v_ldexp_f32 v178, v179, v178
	v_fma_f32 v183, v16, s36, -v183
	v_log_f32_e32 v185, v176
	v_fma_f32 v176, v182, s36, -v184
	v_log_f32_e32 v184, v178
	v_fmac_f32_e32 v183, 0x3377d1cf, v16
	v_cndmask_b32_e32 v177, 0, v191, vcc
	v_fmac_f32_e32 v176, 0x3377d1cf, v182
	v_fmac_f32_e32 v183, 0x3f317217, v16
	v_cmp_lt_f32_e64 vcc, |v16|, s37
	v_fmac_f32_e32 v176, 0x3f317217, v182
	v_cndmask_b32_e64 v179, 0, v191, s[44:45]
	v_cndmask_b32_e32 v16, v16, v183, vcc
	v_cmp_lt_f32_e64 vcc, |v182|, s37
	s_nop 1
	v_cndmask_b32_e32 v178, v182, v176, vcc
	v_sub_f32_e32 v176, v16, v169
	v_mul_f32_e32 v16, 0x3f317217, v185
	v_mul_f32_e32 v169, 0x3f317217, v184
	v_fma_f32 v16, v185, s36, -v16
	v_fma_f32 v169, v184, s36, -v169
	v_fmac_f32_e32 v16, 0x3377d1cf, v185
	v_fmac_f32_e32 v169, 0x3377d1cf, v184
	v_fmac_f32_e32 v16, 0x3f317217, v185
	v_cmp_lt_f32_e64 vcc, |v185|, s37
	v_fmac_f32_e32 v169, 0x3f317217, v184
	v_sub_f32_e32 v178, v178, v181
	v_cndmask_b32_e32 v16, v185, v16, vcc
	v_cmp_lt_f32_e64 vcc, |v184|, s37
	v_sub_f32_e32 v177, v16, v177
	v_max_f32_e32 v16, v122, v122
	v_cndmask_b32_e32 v169, v184, v169, vcc
	v_sub_f32_e32 v179, v169, v179
	global_store_dwordx4 v[126:127], v[176:179], off
	s_nop 0
	v_med3_f32 v16, v16, s38, v194
	v_lshlrev_b64 v[176:177], 11, v[172:173]
	v_max_f32_e32 v173, v123, v123
	v_lshl_add_u64 v[122:123], s[56:57], 0, v[176:177]
	v_med3_f32 v173, v173, s38, v194
	v_mov_b32_e32 v169, v17
	v_lshl_add_u64 v[122:123], v[122:123], 0, s[4:5]
	v_mul_f32_e32 v16, 0xbfb8aa3b, v16
	v_mul_f32_e32 v173, 0xbfb8aa3b, v173
	v_lshl_add_u64 v[176:177], v[122:123], 0, v[168:169]
	v_exp_f32_e32 v16, v16
	v_exp_f32_e32 v122, v173
	v_exp_f32_e32 v123, v124
	v_exp_f32_e32 v124, v125
	v_add_f32_e32 v16, 1.0, v16
	v_add_f32_e32 v169, 1.0, v122
	v_add_f32_e32 v122, 1.0, v123
	v_add_f32_e32 v173, 1.0, v124
	v_rcp_f32_e32 v124, v16
	v_rcp_f32_e32 v178, v122
	v_mul_f32_e32 v123, v202, v203
	v_mul_f32_e32 v125, v132, v133
	v_cvt_pk_bf16_f32 v123, v123, v125
	v_mul_f32_e32 v16, v196, v197
	v_mul_f32_e32 v122, v128, v129
	v_cvt_pk_bf16_f32 v122, v16, v122
	v_mov_b64_e32 v[182:183], v[208:209]
	v_mov_b64_e32 v[184:185], v[210:211]
	v_mov_b32_e32 v125, v182
	v_mov_b32_e32 v179, v184
	v_pk_add_f32 v[128:129], v[124:125], 1.0 op_sel_hi:[1,0] neg_lo:[1,0] neg_hi:[1,0]
	v_pk_add_f32 v[132:133], v[178:179], 1.0 op_sel_hi:[1,0] neg_lo:[1,0] neg_hi:[1,0]
	v_fma_f32 v16, v124, v129, v182
	v_rcp_f32_e32 v182, v169
	v_fma_f32 v124, v178, v133, v184
	v_rcp_f32_e32 v184, v173
	v_cmp_gt_f32_e32 vcc, s31, v16
	v_cmp_gt_f32_e64 s[44:45], s31, v124
	v_mul_f32_e32 v179, v128, v129
	v_cndmask_b32_e64 v125, 0, 32, vcc
	v_cndmask_b32_e64 v128, 0, 32, s[44:45]
	v_ldexp_f32 v16, v16, v125
	v_ldexp_f32 v124, v124, v128
	v_log_f32_e32 v16, v16
	v_log_f32_e32 v173, v124
	v_pk_add_f32 v[124:125], v[182:183], 1.0 op_sel_hi:[1,0] neg_lo:[1,0] neg_hi:[1,0]
; __device__ __forceinline__ unsigned cvt_pk_bf16(float lo, float hi) { unsigned r; asm("v_cvt_pk_bf16_f32 %0, %1, %2" : "=v"(r) : "v"(lo), "v"(hi)); return r; }
;     __device__ __forceinline__ void operator()(const f32x4 (&acc)[2][2][4][2], const Unit& u, int wr, int wc, int fr, int fq) const {
;     ...
;                     for (int bj = 0; bj < 2; ++bj) { f32x4 lfv[2], kkv[2];
; #pragma unroll
;                         for (int n = 0; n < 2; ++n) { const f32x4 lbq = *(const f32x4*)(lbp + col0 + cl + bj * 128 + 4 * n);
; #pragma unroll
;                             for (int e = 0; e < 4; ++e) { const float z = fminf(fmaxf(acc[ai][bj][m][n][e], -30.f), 30.f); const float sg = __builtin_amdgcn_rcpf(1.f + __expf(-z)); const float oml = 1.f - lbq[e];
;                                 lfv[n][e] = __logf(lbq[e] + oml * sg); kkv[n][e] = oml * (1.f - sg); }
;                             *(f32x4*)(rp + bj * 128 + 4 * n) = lfv[n]; }
;                         u32x4 w; w.x = cvt_pk_bf16(kkv[0][0], kkv[0][1]); w.y = cvt_pk_bf16(kkv[0][2], kkv[0][3]); w.z = cvt_pk_bf16(kkv[1][0], kkv[1][1]); w.w = cvt_pk_bf16(kkv[1][2], kkv[1][3]);
;                         *(u32x4*)(kp + bj * 128) = w; }
	v_pk_add_f32 v[128:129], v[184:185], 1.0 op_sel_hi:[1,0] neg_lo:[1,0] neg_hi:[1,0]
	v_fma_f32 v178, v182, v125, v183
	v_mul_f32_e32 v132, v132, v133
	v_cndmask_b32_e32 v133, 0, v191, vcc
	v_fmac_f32_e32 v185, v184, v129
	v_cmp_gt_f32_e32 vcc, s31, v178
	v_cndmask_b32_e64 v169, 0, v191, s[44:45]
	v_mul_f32_e32 v124, v124, v125
	v_mul_f32_e32 v125, v128, v129
	v_cndmask_b32_e64 v128, 0, 32, vcc
	v_cmp_gt_f32_e64 s[44:45], s31, v185
	v_cvt_pk_bf16_f32 v125, v132, v125
	v_mul_f32_e32 v132, 0x3f317217, v16
	v_ldexp_f32 v128, v178, v128
	v_cndmask_b32_e64 v129, 0, 32, s[44:45]
	v_cvt_pk_bf16_f32 v124, v179, v124
	v_mul_f32_e32 v179, 0x3f317217, v173
	v_ldexp_f32 v129, v185, v129
	v_fma_f32 v132, v16, s36, -v132
	v_log_f32_e32 v128, v128
	v_fma_f32 v179, v173, s36, -v179
	v_log_f32_e32 v129, v129
	v_fmac_f32_e32 v132, 0x3377d1cf, v16
	v_cndmask_b32_e32 v178, 0, v191, vcc
	v_fmac_f32_e32 v179, 0x3377d1cf, v173
	v_fmac_f32_e32 v132, 0x3f317217, v16
	v_cmp_lt_f32_e64 vcc, |v16|, s37
	v_fmac_f32_e32 v179, 0x3f317217, v173
	v_cndmask_b32_e64 v181, 0, v191, s[44:45]
	v_cndmask_b32_e32 v16, v16, v132, vcc
	v_cmp_lt_f32_e64 vcc, |v173|, s37
	v_sub_f32_e32 v182, v16, v133
	v_mul_f32_e32 v16, 0x3f317217, v128
	v_cndmask_b32_e32 v132, v173, v179, vcc
	v_sub_f32_e32 v184, v132, v169
	v_mul_f32_e32 v132, 0x3f317217, v129
	v_fma_f32 v16, v128, s36, -v16
	v_fma_f32 v132, v129, s36, -v132
	v_fmac_f32_e32 v16, 0x3377d1cf, v128
	v_fmac_f32_e32 v132, 0x3377d1cf, v129
	v_fmac_f32_e32 v16, 0x3f317217, v128
	v_cmp_lt_f32_e64 vcc, |v128|, s37
	v_fmac_f32_e32 v132, 0x3f317217, v129
	s_nop 0
	v_cndmask_b32_e32 v16, v128, v16, vcc
	v_cmp_lt_f32_e64 vcc, |v129|, s37
	v_sub_f32_e32 v183, v16, v178
	v_max_f32_e32 v16, v118, v118
	v_cndmask_b32_e32 v128, v129, v132, vcc
	v_sub_f32_e32 v185, v128, v181
	global_store_dwordx4 v[126:127], v[182:185], off offset:16
	global_store_dwordx4 v[176:177], v[122:125], off
	s_nop 0
	v_max_f32_e32 v118, v119, v119
	v_max_f32_e32 v119, v120, v120
	v_med3_f32 v16, v16, s38, v194
	v_max_f32_e32 v120, v121, v121
	v_med3_f32 v118, v118, s38, v194
	v_med3_f32 v119, v119, s38, v194
	v_mul_f32_e32 v16, 0xbfb8aa3b, v16
	v_med3_f32 v120, v120, s38, v194
	v_mul_f32_e32 v118, 0xbfb8aa3b, v118
	v_mul_f32_e32 v119, 0xbfb8aa3b, v119
	v_exp_f32_e32 v16, v16
	v_mul_f32_e32 v120, 0xbfb8aa3b, v120
	v_exp_f32_e32 v118, v118
	v_exp_f32_e32 v119, v119
	v_exp_f32_e32 v120, v120
	v_add_f32_e32 v16, 1.0, v16
	v_add_f32_e32 v169, 1.0, v118
	v_add_f32_e32 v119, 1.0, v119
	v_rcp_f32_e32 v118, v16
	v_add_f32_e32 v173, 1.0, v120
	v_rcp_f32_e32 v120, v119
	v_mov_b64_e32 v[122:123], v[212:213]
	v_mov_b64_e32 v[124:125], v[214:215]
	v_mov_b32_e32 v119, v122
	v_mov_b32_e32 v121, v124
	v_pk_add_f32 v[128:129], v[118:119], 1.0 op_sel_hi:[1,0] neg_lo:[1,0] neg_hi:[1,0]
	v_pk_add_f32 v[132:133], v[120:121], 1.0 op_sel_hi:[1,0] neg_lo:[1,0] neg_hi:[1,0]
	v_fma_f32 v16, v118, v129, v122
	v_rcp_f32_e32 v122, v169
	v_fma_f32 v118, v120, v133, v124
	v_rcp_f32_e32 v124, v173
	v_cmp_gt_f32_e32 vcc, s31, v16
	v_cmp_gt_f32_e64 s[44:45], s31, v118
	v_pk_add_f32 v[178:179], v[122:123], 1.0 op_sel_hi:[1,0] neg_lo:[1,0] neg_hi:[1,0]
	v_cndmask_b32_e64 v119, 0, 32, vcc
	v_cndmask_b32_e64 v120, 0, 32, s[44:45]
	v_ldexp_f32 v16, v16, v119
	v_ldexp_f32 v118, v118, v120
	v_log_f32_e32 v16, v16
	v_log_f32_e32 v118, v118
	v_pk_add_f32 v[182:183], v[124:125], 1.0 op_sel_hi:[1,0] neg_lo:[1,0] neg_hi:[1,0]
	v_fma_f32 v121, v122, v179, v123
	v_cndmask_b32_e32 v119, 0, v191, vcc
	v_fmac_f32_e32 v125, v124, v183
	v_cmp_gt_f32_e32 vcc, s31, v121
	v_cndmask_b32_e64 v120, 0, v191, s[44:45]
	v_cmp_gt_f32_e64 s[44:45], s31, v125
	v_cndmask_b32_e64 v122, 0, 32, vcc
	v_mul_f32_e32 v124, 0x3f317217, v16
	v_cndmask_b32_e64 v123, 0, 32, s[44:45]
	v_ldexp_f32 v121, v121, v122
	v_mul_f32_e32 v169, 0x3f317217, v118
	v_ldexp_f32 v123, v125, v123
	v_fma_f32 v124, v16, s36, -v124
	v_log_f32_e32 v121, v121
	v_fma_f32 v169, v118, s36, -v169
	v_log_f32_e32 v123, v123
	v_fmac_f32_e32 v124, 0x3377d1cf, v16
	v_cndmask_b32_e32 v122, 0, v191, vcc
	v_fmac_f32_e32 v169, 0x3377d1cf, v118
	v_fmac_f32_e32 v124, 0x3f317217, v16
	v_cmp_lt_f32_e64 vcc, |v16|, s37
	v_fmac_f32_e32 v169, 0x3f317217, v118
	v_cndmask_b32_e64 v125, 0, v191, s[44:45]
; __device__ __forceinline__ unsigned cvt_pk_bf16(float lo, float hi) { unsigned r; asm("v_cvt_pk_bf16_f32 %0, %1, %2" : "=v"(r) : "v"(lo), "v"(hi)); return r; }
;     __device__ __forceinline__ void operator()(const f32x4 (&acc)[2][2][4][2], const Unit& u, int wr, int wc, int fr, int fq) const {
;     ...
;                     for (int bj = 0; bj < 2; ++bj) { f32x4 lfv[2], kkv[2];
; #pragma unroll
;                         for (int n = 0; n < 2; ++n) { const f32x4 lbq = *(const f32x4*)(lbp + col0 + cl + bj * 128 + 4 * n);
; #pragma unroll
;                             for (int e = 0; e < 4; ++e) { const float z = fminf(fmaxf(acc[ai][bj][m][n][e], -30.f), 30.f); const float sg = __builtin_amdgcn_rcpf(1.f + __expf(-z)); const float oml = 1.f - lbq[e];
;                                 lfv[n][e] = __logf(lbq[e] + oml * sg); kkv[n][e] = oml * (1.f - sg); }
;                             *(f32x4*)(rp + bj * 128 + 4 * n) = lfv[n]; }
;                         u32x4 w; w.x = cvt_pk_bf16(kkv[0][0], kkv[0][1]); w.y = cvt_pk_bf16(kkv[0][2], kkv[0][3]); w.z = cvt_pk_bf16(kkv[1][0], kkv[1][1]); w.w = cvt_pk_bf16(kkv[1][2], kkv[1][3]);
;                         *(u32x4*)(kp + bj * 128) = w; }
	v_cndmask_b32_e32 v16, v16, v124, vcc
	v_cmp_lt_f32_e64 vcc, |v118|, s37
	s_nop 1
	v_cndmask_b32_e32 v124, v118, v169, vcc
	v_sub_f32_e32 v118, v16, v119
	v_mul_f32_e32 v16, 0x3f317217, v121
	v_mul_f32_e32 v119, 0x3f317217, v123
	v_fma_f32 v16, v121, s36, -v16
	v_fma_f32 v119, v123, s36, -v119
	v_fmac_f32_e32 v16, 0x3377d1cf, v121
	v_fmac_f32_e32 v119, 0x3377d1cf, v123
	v_fmac_f32_e32 v16, 0x3f317217, v121
	v_cmp_lt_f32_e64 vcc, |v121|, s37
	v_fmac_f32_e32 v119, 0x3f317217, v123
	v_sub_f32_e32 v120, v124, v120
	v_cndmask_b32_e32 v16, v121, v16, vcc
	v_cmp_lt_f32_e64 vcc, |v123|, s37
	s_nop 1
	v_cndmask_b32_e32 v121, v123, v119, vcc
	v_sub_f32_e32 v119, v16, v122
	v_sub_f32_e32 v121, v121, v125
	global_store_dwordx4 v[126:127], v[118:121], off offset:512
	s_nop 0
	v_max_f32_e32 v16, v114, v114
	v_max_f32_e32 v114, v115, v115
	v_max_f32_e32 v115, v116, v116
	v_max_f32_e32 v116, v117, v117
	v_med3_f32 v16, v16, s38, v194
	v_med3_f32 v115, v115, s38, v194
	v_med3_f32 v114, v114, s38, v194
	v_med3_f32 v116, v116, s38, v194
	v_mul_f32_e32 v16, 0xbfb8aa3b, v16
	v_mul_f32_e32 v115, 0xbfb8aa3b, v115
	v_mul_f32_e32 v114, 0xbfb8aa3b, v114
	v_mul_f32_e32 v116, 0xbfb8aa3b, v116
	v_exp_f32_e32 v16, v16
	v_exp_f32_e32 v115, v115
	v_exp_f32_e32 v114, v114
	v_exp_f32_e32 v116, v116
	v_add_f32_e32 v16, 1.0, v16
	v_add_f32_e32 v115, 1.0, v115
	v_add_f32_e32 v169, 1.0, v114
	v_add_f32_e32 v173, 1.0, v116
	v_rcp_f32_e32 v114, v16
	v_rcp_f32_e32 v116, v115
	v_mul_f32_e32 v115, v132, v133
	v_mul_f32_e32 v117, v178, v179
	v_mul_f32_e32 v16, v128, v129
	v_mul_f32_e32 v122, v182, v183
	v_cvt_pk_bf16_f32 v130, v16, v117
	v_cvt_pk_bf16_f32 v131, v115, v122
	v_mov_b64_e32 v[118:119], v[216:217]
	v_mov_b64_e32 v[120:121], v[218:219]
	v_mov_b32_e32 v115, v118
	v_mov_b32_e32 v117, v120
	v_pk_add_f32 v[122:123], v[114:115], 1.0 op_sel_hi:[1,0] neg_lo:[1,0] neg_hi:[1,0]
	v_pk_add_f32 v[124:125], v[116:117], 1.0 op_sel_hi:[1,0] neg_lo:[1,0] neg_hi:[1,0]
	v_fma_f32 v16, v114, v123, v118
	v_rcp_f32_e32 v118, v169
	v_fma_f32 v114, v116, v125, v120
	v_rcp_f32_e32 v120, v173
	v_cmp_gt_f32_e32 vcc, s31, v16
	v_cmp_gt_f32_e64 s[44:45], s31, v114
	v_mul_f32_e32 v122, v122, v123
	v_cndmask_b32_e64 v115, 0, 32, vcc
	v_cndmask_b32_e64 v116, 0, 32, s[44:45]
	v_ldexp_f32 v16, v16, v115
	v_ldexp_f32 v114, v114, v116
	v_log_f32_e32 v16, v16
	v_log_f32_e32 v128, v114
	v_pk_add_f32 v[114:115], v[118:119], 1.0 op_sel_hi:[1,0] neg_lo:[1,0] neg_hi:[1,0]
	v_pk_add_f32 v[116:117], v[120:121], 1.0 op_sel_hi:[1,0] neg_lo:[1,0] neg_hi:[1,0]
	v_fma_f32 v118, v118, v115, v119
	v_mul_f32_e32 v123, v124, v125
	v_cndmask_b32_e32 v124, 0, v191, vcc
	v_fmac_f32_e32 v121, v120, v117
	v_cmp_gt_f32_e32 vcc, s31, v118
	v_cndmask_b32_e64 v125, 0, v191, s[44:45]
	v_mul_f32_e32 v114, v114, v115
	v_cndmask_b32_e64 v115, 0, 32, vcc
	v_cmp_gt_f32_e64 s[44:45], s31, v121
	v_mul_f32_e32 v119, v116, v117
	v_cvt_pk_bf16_f32 v132, v122, v114
	v_mul_f32_e32 v114, 0x3f317217, v16
	v_cndmask_b32_e64 v116, 0, 32, s[44:45]
	v_ldexp_f32 v115, v118, v115
	v_ldexp_f32 v116, v121, v116
	v_fma_f32 v114, v16, s36, -v114
	v_log_f32_e32 v115, v115
	v_mul_f32_e32 v118, 0x3f317217, v128
	v_log_f32_e32 v121, v116
	v_fmac_f32_e32 v114, 0x3377d1cf, v16
	v_cndmask_b32_e32 v117, 0, v191, vcc
	v_fma_f32 v118, v128, s36, -v118
	v_fmac_f32_e32 v114, 0x3f317217, v16
	v_cmp_lt_f32_e64 vcc, |v16|, s37
	v_fmac_f32_e32 v118, 0x3377d1cf, v128
	v_fmac_f32_e32 v118, 0x3f317217, v128
	v_cndmask_b32_e32 v16, v16, v114, vcc
	v_cmp_lt_f32_e64 vcc, |v128|, s37
	v_sub_f32_e32 v114, v16, v124
	v_mul_f32_e32 v16, 0x3f317217, v115
	v_cndmask_b32_e32 v116, v128, v118, vcc
	v_mul_f32_e32 v118, 0x3f317217, v121
	v_fma_f32 v16, v115, s36, -v16
	v_fma_f32 v118, v121, s36, -v118
	v_fmac_f32_e32 v16, 0x3377d1cf, v115
	v_fmac_f32_e32 v118, 0x3377d1cf, v121
	v_fmac_f32_e32 v16, 0x3f317217, v115
	v_cmp_lt_f32_e64 vcc, |v115|, s37
	v_fmac_f32_e32 v118, 0x3f317217, v121
	v_cndmask_b32_e64 v120, 0, v191, s[44:45]
	v_cndmask_b32_e32 v16, v115, v16, vcc
	v_cmp_lt_f32_e64 vcc, |v121|, s37
	v_sub_f32_e32 v116, v116, v125
	v_sub_f32_e32 v115, v16, v117
	v_cndmask_b32_e32 v118, v121, v118, vcc
	v_sub_f32_e32 v117, v118, v120
	global_store_dwordx4 v[126:127], v[114:117], off offset:528
	v_cvt_pk_bf16_f32 v133, v123, v119

; __device__ __forceinline__ unsigned cvt_pk_bf16(float lo, float hi) { unsigned r; asm("v_cvt_pk_bf16_f32 %0, %1, %2" : "=v"(r) : "v"(lo), "v"(hi)); return r; }
;     __device__ __forceinline__ void operator()(const f32x4 (&acc)[2][2][4][2], const Unit& u, int wr, int wc, int fr, int fq) const {
;     ...
;                 } else if (type == 4) {
;                     float* rp = (float*)base + (size_t)row * ld + col0 + cl; bf16_t* kp = (bf16_t*)(proj + (size_t)MP * 10240) + (size_t)row * ld + col0 + cl;
; #pragma unroll
;                     for (int bj = 0; bj < 2; ++bj) { f32x4 lfv[2], kkv[2];
; #pragma unroll
;                         for (int n = 0; n < 2; ++n) { const f32x4 lbq = *(const f32x4*)(lbp + col0 + cl + bj * 128 + 4 * n);
; #pragma unroll
;                             for (int e = 0; e < 4; ++e) { const float z = fminf(fmaxf(acc[ai][bj][m][n][e], -30.f), 30.f); const float sg = __builtin_amdgcn_rcpf(1.f + __expf(-z)); const float oml = 1.f - lbq[e];
;                                 lfv[n][e] = __logf(lbq[e] + oml * sg); kkv[n][e] = oml * (1.f - sg); }
;                             *(f32x4*)(rp + bj * 128 + 4 * n) = lfv[n]; }
;                         u32x4 w; w.x = cvt_pk_bf16(kkv[0][0], kkv[0][1]); w.y = cvt_pk_bf16(kkv[0][2], kkv[0][3]); w.z = cvt_pk_bf16(kkv[1][0], kkv[1][1]); w.w = cvt_pk_bf16(kkv[1][2], kkv[1][3]);
;                         *(u32x4*)(kp + bj * 128) = w; }
.LBB0_712:
	s_and_b64 vcc, exec, s[18:19]
	s_cbranch_vccz .LBB0_714
	s_lshl_b32 s18, s59, 2
	s_mov_b32 s19, s12
	v_lshl_add_u64 v[114:115], v[144:145], 0, s[18:19]
	s_nop 0
	v_lshlrev_b64 v[122:123], 12, v[120:121]
	v_max_f32_e32 v16, v110, v110
	v_max_f32_e32 v124, v111, v111
	v_max_f32_e32 v112, v112, v112
	v_lshl_add_u64 v[110:111], v[174:175], 0, v[122:123]
	v_med3_f32 v16, v16, s38, v194
	v_med3_f32 v122, v124, s38, v194
	v_med3_f32 v112, v112, s38, v194
	v_mul_f32_e32 v16, 0xbfb8aa3b, v16
	v_mul_f32_e32 v122, 0xbfb8aa3b, v122
	v_mul_f32_e32 v112, 0xbfb8aa3b, v112
	v_exp_f32_e32 v16, v16
	v_exp_f32_e32 v122, v122
	v_exp_f32_e32 v112, v112
	v_max_f32_e32 v113, v113, v113
	v_med3_f32 v113, v113, s38, v194
	v_mul_f32_e32 v113, 0xbfb8aa3b, v113
	v_exp_f32_e32 v113, v113
	v_add_f32_e32 v16, 1.0, v16
	v_add_f32_e32 v124, 1.0, v122
	v_add_f32_e32 v122, 1.0, v112
	v_rcp_f32_e32 v112, v16
	v_rcp_f32_e32 v122, v122
	v_add_f32_e32 v125, 1.0, v113
	v_max_f32_e32 v108, v108, v108
	s_mov_b32 s5, s12
	v_max_f32_e32 v109, v109, v109
	v_med3_f32 v108, v108, s38, v194
	v_mov_b32_e32 v169, v17
	v_med3_f32 v109, v109, s38, v194
	v_mul_f32_e32 v108, 0xbfb8aa3b, v108
	v_mul_f32_e32 v109, 0xbfb8aa3b, v109
	v_mov_b64_e32 v[116:117], v[204:205]
	v_mov_b64_e32 v[118:119], v[206:207]
	v_mov_b32_e32 v113, v116
	v_mov_b32_e32 v123, v118
	v_pk_add_f32 v[126:127], v[112:113], 1.0 op_sel_hi:[1,0] neg_lo:[1,0] neg_hi:[1,0]
	v_pk_add_f32 v[128:129], v[122:123], 1.0 op_sel_hi:[1,0] neg_lo:[1,0] neg_hi:[1,0]
	v_fma_f32 v16, v112, v127, v116
	v_rcp_f32_e32 v116, v124
	v_fma_f32 v112, v122, v129, v118
	v_rcp_f32_e32 v118, v125
	v_cmp_gt_f32_e32 vcc, s31, v16
	v_cmp_gt_f32_e64 s[46:47], s31, v112
	v_pk_add_f32 v[130:131], v[118:119], 1.0 op_sel_hi:[1,0] neg_lo:[1,0] neg_hi:[1,0]
	v_cndmask_b32_e64 v113, 0, 32, vcc
	v_cndmask_b32_e64 v122, 0, 32, s[46:47]
	v_ldexp_f32 v16, v16, v113
	v_ldexp_f32 v112, v112, v122
	v_log_f32_e32 v16, v16
	v_log_f32_e32 v124, v112
	v_pk_add_f32 v[112:113], v[116:117], 1.0 op_sel_hi:[1,0] neg_lo:[1,0] neg_hi:[1,0]
	v_cndmask_b32_e32 v123, 0, v191, vcc
	v_fma_f32 v116, v116, v113, v117
	v_fmac_f32_e32 v119, v118, v131
	v_cmp_gt_f32_e32 vcc, s31, v116
	v_cndmask_b32_e64 v122, 0, v191, s[46:47]
	v_cmp_gt_f32_e64 s[46:47], s31, v119
	v_cndmask_b32_e64 v117, 0, 32, vcc
	v_mul_f32_e32 v125, 0x3f317217, v16
	v_cndmask_b32_e64 v118, 0, 32, s[46:47]
	v_ldexp_f32 v116, v116, v117
	v_mul_f32_e32 v132, 0x3f317217, v124
	v_ldexp_f32 v118, v119, v118
	v_fma_f32 v125, v16, s36, -v125
	v_log_f32_e32 v133, v116
	v_fma_f32 v116, v124, s36, -v132
	v_log_f32_e32 v132, v118
	v_fmac_f32_e32 v125, 0x3377d1cf, v16
	v_cndmask_b32_e32 v117, 0, v191, vcc
	v_fmac_f32_e32 v116, 0x3377d1cf, v124
	v_fmac_f32_e32 v125, 0x3f317217, v16
	v_cmp_lt_f32_e64 vcc, |v16|, s37
	v_fmac_f32_e32 v116, 0x3f317217, v124
	v_cndmask_b32_e64 v119, 0, v191, s[46:47]
	v_cndmask_b32_e32 v16, v16, v125, vcc
	v_cmp_lt_f32_e64 vcc, |v124|, s37
	s_nop 1
	v_cndmask_b32_e32 v118, v124, v116, vcc
	v_sub_f32_e32 v116, v16, v123
	v_mul_f32_e32 v16, 0x3f317217, v133
	v_sub_f32_e32 v118, v118, v122
	v_mul_f32_e32 v122, 0x3f317217, v132
	v_fma_f32 v16, v133, s36, -v16
	v_fma_f32 v122, v132, s36, -v122
	v_fmac_f32_e32 v16, 0x3377d1cf, v133
	v_fmac_f32_e32 v122, 0x3377d1cf, v132
	v_fmac_f32_e32 v16, 0x3f317217, v133
	v_cmp_lt_f32_e64 vcc, |v133|, s37
	v_fmac_f32_e32 v122, 0x3f317217, v132
	s_nop 0
	v_cndmask_b32_e32 v16, v133, v16, vcc
	v_cmp_lt_f32_e64 vcc, |v132|, s37
	v_sub_f32_e32 v117, v16, v117
	v_max_f32_e32 v16, v106, v106
	v_cndmask_b32_e32 v122, v132, v122, vcc
	v_sub_f32_e32 v119, v122, v119
	global_store_dwordx4 v[110:111], v[116:119], off
	s_nop 0
	v_med3_f32 v16, v16, s38, v194
	v_lshlrev_b64 v[116:117], 11, v[120:121]
	v_max_f32_e32 v118, v107, v107
	v_lshl_add_u64 v[106:107], s[56:57], 0, v[116:117]
	v_med3_f32 v116, v118, s38, v194
	v_lshl_add_u64 v[106:107], v[106:107], 0, s[4:5]
	v_mul_f32_e32 v16, 0xbfb8aa3b, v16
	v_mul_f32_e32 v116, 0xbfb8aa3b, v116
	v_lshl_add_u64 v[118:119], v[106:107], 0, v[168:169]
	v_exp_f32_e32 v16, v16
	v_exp_f32_e32 v106, v116
	v_exp_f32_e32 v107, v108
	v_exp_f32_e32 v108, v109
	v_add_f32_e32 v16, 1.0, v16
	v_add_f32_e32 v132, 1.0, v106
	v_add_f32_e32 v106, 1.0, v107
	v_add_f32_e32 v133, 1.0, v108
	v_rcp_f32_e32 v108, v16
	v_rcp_f32_e32 v116, v106
	v_mul_f32_e32 v107, v128, v129
	v_mul_f32_e32 v109, v130, v131
	v_cvt_pk_bf16_f32 v107, v107, v109
	v_mul_f32_e32 v16, v126, v127
	v_mul_f32_e32 v106, v112, v113
	v_cvt_pk_bf16_f32 v106, v16, v106
	v_mov_b64_e32 v[122:123], v[208:209]
	v_mov_b64_e32 v[124:125], v[210:211]
	v_mov_b32_e32 v109, v122
	v_mov_b32_e32 v117, v124
	v_pk_add_f32 v[112:113], v[108:109], 1.0 op_sel_hi:[1,0] neg_lo:[1,0] neg_hi:[1,0]
	v_pk_add_f32 v[120:121], v[116:117], 1.0 op_sel_hi:[1,0] neg_lo:[1,0] neg_hi:[1,0]
	v_fma_f32 v16, v108, v113, v122
	v_rcp_f32_e32 v122, v132
	v_fma_f32 v108, v116, v121, v124
	v_rcp_f32_e32 v124, v133
	v_cmp_gt_f32_e32 vcc, s31, v16
	v_cmp_gt_f32_e64 s[46:47], s31, v108
	v_mul_f32_e32 v117, v112, v113
	v_cndmask_b32_e64 v109, 0, 32, vcc
	v_cndmask_b32_e64 v112, 0, 32, s[46:47]
	v_ldexp_f32 v16, v16, v109
	v_ldexp_f32 v108, v108, v112
	v_log_f32_e32 v16, v16
	v_log_f32_e32 v126, v108
	v_pk_add_f32 v[108:109], v[122:123], 1.0 op_sel_hi:[1,0] neg_lo:[1,0] neg_hi:[1,0]
	v_pk_add_f32 v[112:113], v[124:125], 1.0 op_sel_hi:[1,0] neg_lo:[1,0] neg_hi:[1,0]
	v_fma_f32 v122, v122, v109, v123
	v_mul_f32_e32 v116, v120, v121
	v_cndmask_b32_e32 v120, 0, v191, vcc
	v_fmac_f32_e32 v125, v124, v113
	v_cmp_gt_f32_e32 vcc, s31, v122
	v_cndmask_b32_e64 v121, 0, v191, s[46:47]
	v_mul_f32_e32 v108, v108, v109
	v_mul_f32_e32 v109, v112, v113
; __device__ __forceinline__ unsigned cvt_pk_bf16(float lo, float hi) { unsigned r; asm("v_cvt_pk_bf16_f32 %0, %1, %2" : "=v"(r) : "v"(lo), "v"(hi)); return r; }
;     __device__ __forceinline__ void operator()(const f32x4 (&acc)[2][2][4][2], const Unit& u, int wr, int wc, int fr, int fq) const {
;     ...
;                     for (int bj = 0; bj < 2; ++bj) { f32x4 lfv[2], kkv[2];
; #pragma unroll
;                         for (int n = 0; n < 2; ++n) { const f32x4 lbq = *(const f32x4*)(lbp + col0 + cl + bj * 128 + 4 * n);
; #pragma unroll
;                             for (int e = 0; e < 4; ++e) { const float z = fminf(fmaxf(acc[ai][bj][m][n][e], -30.f), 30.f); const float sg = __builtin_amdgcn_rcpf(1.f + __expf(-z)); const float oml = 1.f - lbq[e];
;                                 lfv[n][e] = __logf(lbq[e] + oml * sg); kkv[n][e] = oml * (1.f - sg); }
;                             *(f32x4*)(rp + bj * 128 + 4 * n) = lfv[n]; }
;                         u32x4 w; w.x = cvt_pk_bf16(kkv[0][0], kkv[0][1]); w.y = cvt_pk_bf16(kkv[0][2], kkv[0][3]); w.z = cvt_pk_bf16(kkv[1][0], kkv[1][1]); w.w = cvt_pk_bf16(kkv[1][2], kkv[1][3]);
;                         *(u32x4*)(kp + bj * 128) = w; }
	v_cndmask_b32_e64 v112, 0, 32, vcc
	v_cmp_gt_f32_e64 s[46:47], s31, v125
	v_cvt_pk_bf16_f32 v109, v116, v109
	v_mul_f32_e32 v116, 0x3f317217, v16
	v_ldexp_f32 v112, v122, v112
	v_cndmask_b32_e64 v113, 0, 32, s[46:47]
	v_mul_f32_e32 v122, 0x3f317217, v126
	v_ldexp_f32 v113, v125, v113
	v_fma_f32 v116, v16, s36, -v116
	v_log_f32_e32 v112, v112
	v_fma_f32 v122, v126, s36, -v122
	v_log_f32_e32 v113, v113
	v_fmac_f32_e32 v116, 0x3377d1cf, v16
	v_cvt_pk_bf16_f32 v108, v117, v108
	v_cndmask_b32_e32 v117, 0, v191, vcc
	v_fmac_f32_e32 v122, 0x3377d1cf, v126
	v_fmac_f32_e32 v116, 0x3f317217, v16
	v_cmp_lt_f32_e64 vcc, |v16|, s37
	v_fmac_f32_e32 v122, 0x3f317217, v126
	v_cndmask_b32_e64 v123, 0, v191, s[46:47]
	v_cndmask_b32_e32 v16, v16, v116, vcc
	v_cmp_lt_f32_e64 vcc, |v126|, s37
	v_sub_f32_e32 v120, v16, v120
	v_mul_f32_e32 v16, 0x3f317217, v112
	v_cndmask_b32_e32 v116, v126, v122, vcc
	v_sub_f32_e32 v122, v116, v121
	v_mul_f32_e32 v116, 0x3f317217, v113
	v_fma_f32 v16, v112, s36, -v16
	v_fma_f32 v116, v113, s36, -v116
	v_fmac_f32_e32 v16, 0x3377d1cf, v112
	v_fmac_f32_e32 v116, 0x3377d1cf, v113
	v_fmac_f32_e32 v16, 0x3f317217, v112
	v_cmp_lt_f32_e64 vcc, |v112|, s37
	v_fmac_f32_e32 v116, 0x3f317217, v113
	s_nop 0
	v_cndmask_b32_e32 v16, v112, v16, vcc
	v_cmp_lt_f32_e64 vcc, |v113|, s37
	v_sub_f32_e32 v121, v16, v117
	v_max_f32_e32 v16, v102, v102
	v_cndmask_b32_e32 v112, v113, v116, vcc
	v_sub_f32_e32 v123, v112, v123
	global_store_dwordx4 v[110:111], v[120:123], off offset:16
	global_store_dwordx4 v[118:119], v[106:109], off
	s_nop 0
	v_max_f32_e32 v102, v103, v103
	v_max_f32_e32 v103, v104, v104
	v_med3_f32 v16, v16, s38, v194
	v_max_f32_e32 v104, v105, v105
	v_med3_f32 v102, v102, s38, v194
	v_med3_f32 v103, v103, s38, v194
	v_mul_f32_e32 v16, 0xbfb8aa3b, v16
	v_med3_f32 v104, v104, s38, v194
	v_mul_f32_e32 v102, 0xbfb8aa3b, v102
	v_mul_f32_e32 v103, 0xbfb8aa3b, v103
	v_exp_f32_e32 v16, v16
	v_mul_f32_e32 v104, 0xbfb8aa3b, v104
	v_exp_f32_e32 v102, v102
	v_exp_f32_e32 v103, v103
	v_exp_f32_e32 v104, v104
	v_add_f32_e32 v16, 1.0, v16
	v_add_f32_e32 v120, 1.0, v102
	v_add_f32_e32 v103, 1.0, v103
	v_rcp_f32_e32 v102, v16
	v_add_f32_e32 v121, 1.0, v104
	v_rcp_f32_e32 v104, v103
	v_mov_b64_e32 v[106:107], v[212:213]
	v_mov_b64_e32 v[108:109], v[214:215]
	v_mov_b32_e32 v103, v106
	v_mov_b32_e32 v105, v108
	v_pk_add_f32 v[112:113], v[102:103], 1.0 op_sel_hi:[1,0] neg_lo:[1,0] neg_hi:[1,0]
	v_pk_add_f32 v[116:117], v[104:105], 1.0 op_sel_hi:[1,0] neg_lo:[1,0] neg_hi:[1,0]
	v_fma_f32 v16, v102, v113, v106
	v_rcp_f32_e32 v106, v120
	v_fma_f32 v102, v104, v117, v108
	v_rcp_f32_e32 v108, v121
	v_cmp_gt_f32_e32 vcc, s31, v16
	v_cmp_gt_f32_e64 s[46:47], s31, v102
	v_pk_add_f32 v[120:121], v[106:107], 1.0 op_sel_hi:[1,0] neg_lo:[1,0] neg_hi:[1,0]
	v_cndmask_b32_e64 v103, 0, 32, vcc
	v_cndmask_b32_e64 v104, 0, 32, s[46:47]
	v_ldexp_f32 v16, v16, v103
	v_ldexp_f32 v102, v102, v104
	v_log_f32_e32 v16, v16
	v_log_f32_e32 v102, v102
	v_pk_add_f32 v[122:123], v[108:109], 1.0 op_sel_hi:[1,0] neg_lo:[1,0] neg_hi:[1,0]
	v_fma_f32 v105, v106, v121, v107
	v_cndmask_b32_e32 v103, 0, v191, vcc
	v_fmac_f32_e32 v109, v108, v123
	v_cmp_gt_f32_e32 vcc, s31, v105
	v_cndmask_b32_e64 v104, 0, v191, s[46:47]
	v_cmp_gt_f32_e64 s[46:47], s31, v109
	v_cndmask_b32_e64 v106, 0, 32, vcc
	v_mul_f32_e32 v108, 0x3f317217, v16
	v_cndmask_b32_e64 v107, 0, 32, s[46:47]
	v_ldexp_f32 v105, v105, v106
	v_mul_f32_e32 v124, 0x3f317217, v102
	v_ldexp_f32 v107, v109, v107
	v_fma_f32 v108, v16, s36, -v108
	v_log_f32_e32 v105, v105
	v_fma_f32 v124, v102, s36, -v124
	v_log_f32_e32 v107, v107
	v_fmac_f32_e32 v108, 0x3377d1cf, v16
	v_cndmask_b32_e32 v106, 0, v191, vcc
	v_fmac_f32_e32 v124, 0x3377d1cf, v102
	v_fmac_f32_e32 v108, 0x3f317217, v16
	v_cmp_lt_f32_e64 vcc, |v16|, s37
	v_fmac_f32_e32 v124, 0x3f317217, v102
	v_cndmask_b32_e64 v109, 0, v191, s[46:47]
	v_cndmask_b32_e32 v16, v16, v108, vcc
	v_cmp_lt_f32_e64 vcc, |v102|, s37
	s_nop 1
	v_cndmask_b32_e32 v108, v102, v124, vcc
	v_sub_f32_e32 v102, v16, v103
; __device__ __forceinline__ unsigned cvt_pk_bf16(float lo, float hi) { unsigned r; asm("v_cvt_pk_bf16_f32 %0, %1, %2" : "=v"(r) : "v"(lo), "v"(hi)); return r; }
;     __device__ __forceinline__ void operator()(const f32x4 (&acc)[2][2][4][2], const Unit& u, int wr, int wc, int fr, int fq) const {
;     ...
;                     for (int bj = 0; bj < 2; ++bj) { f32x4 lfv[2], kkv[2];
; #pragma unroll
;                         for (int n = 0; n < 2; ++n) { const f32x4 lbq = *(const f32x4*)(lbp + col0 + cl + bj * 128 + 4 * n);
; #pragma unroll
;                             for (int e = 0; e < 4; ++e) { const float z = fminf(fmaxf(acc[ai][bj][m][n][e], -30.f), 30.f); const float sg = __builtin_amdgcn_rcpf(1.f + __expf(-z)); const float oml = 1.f - lbq[e];
;                                 lfv[n][e] = __logf(lbq[e] + oml * sg); kkv[n][e] = oml * (1.f - sg); }
;                             *(f32x4*)(rp + bj * 128 + 4 * n) = lfv[n]; }
;                         u32x4 w; w.x = cvt_pk_bf16(kkv[0][0], kkv[0][1]); w.y = cvt_pk_bf16(kkv[0][2], kkv[0][3]); w.z = cvt_pk_bf16(kkv[1][0], kkv[1][1]); w.w = cvt_pk_bf16(kkv[1][2], kkv[1][3]);
;                         *(u32x4*)(kp + bj * 128) = w; }
	v_mul_f32_e32 v16, 0x3f317217, v105
	v_mul_f32_e32 v103, 0x3f317217, v107
	v_fma_f32 v16, v105, s36, -v16
	v_fma_f32 v103, v107, s36, -v103
	v_fmac_f32_e32 v16, 0x3377d1cf, v105
	v_fmac_f32_e32 v103, 0x3377d1cf, v107
	v_fmac_f32_e32 v16, 0x3f317217, v105
	v_cmp_lt_f32_e64 vcc, |v105|, s37
	v_fmac_f32_e32 v103, 0x3f317217, v107
	v_sub_f32_e32 v104, v108, v104
	v_cndmask_b32_e32 v16, v105, v16, vcc
	v_cmp_lt_f32_e64 vcc, |v107|, s37
	s_nop 1
	v_cndmask_b32_e32 v105, v107, v103, vcc
	v_sub_f32_e32 v103, v16, v106
	v_sub_f32_e32 v105, v105, v109
	global_store_dwordx4 v[110:111], v[102:105], off offset:512
	s_nop 0
	v_max_f32_e32 v16, v98, v98
	v_max_f32_e32 v98, v99, v99
	v_max_f32_e32 v99, v100, v100
	v_max_f32_e32 v100, v101, v101
	v_med3_f32 v16, v16, s38, v194
	v_med3_f32 v99, v99, s38, v194
	v_med3_f32 v98, v98, s38, v194
	v_med3_f32 v100, v100, s38, v194
	v_mul_f32_e32 v16, 0xbfb8aa3b, v16
	v_mul_f32_e32 v99, 0xbfb8aa3b, v99
	v_mul_f32_e32 v98, 0xbfb8aa3b, v98
	v_mul_f32_e32 v100, 0xbfb8aa3b, v100
	v_exp_f32_e32 v16, v16
	v_exp_f32_e32 v99, v99
	v_exp_f32_e32 v98, v98
	v_exp_f32_e32 v100, v100
	v_add_f32_e32 v16, 1.0, v16
	v_add_f32_e32 v99, 1.0, v99
	v_add_f32_e32 v124, 1.0, v98
	v_add_f32_e32 v125, 1.0, v100
	v_rcp_f32_e32 v98, v16
	v_rcp_f32_e32 v100, v99
	v_mul_f32_e32 v99, v116, v117
	v_mul_f32_e32 v101, v120, v121
	v_mul_f32_e32 v16, v112, v113
	v_mul_f32_e32 v106, v122, v123
	v_cvt_pk_bf16_f32 v114, v16, v101
	v_cvt_pk_bf16_f32 v115, v99, v106
	v_mov_b64_e32 v[102:103], v[216:217]
	v_mov_b64_e32 v[104:105], v[218:219]
	v_mov_b32_e32 v99, v102
	v_mov_b32_e32 v101, v104
	v_pk_add_f32 v[106:107], v[98:99], 1.0 op_sel_hi:[1,0] neg_lo:[1,0] neg_hi:[1,0]
	v_pk_add_f32 v[108:109], v[100:101], 1.0 op_sel_hi:[1,0] neg_lo:[1,0] neg_hi:[1,0]
	v_fma_f32 v16, v98, v107, v102
	v_rcp_f32_e32 v102, v124
	v_fma_f32 v98, v100, v109, v104
	v_rcp_f32_e32 v104, v125
	v_cmp_gt_f32_e32 vcc, s31, v16
	v_cmp_gt_f32_e64 s[46:47], s31, v98
	v_mul_f32_e32 v106, v106, v107
	v_cndmask_b32_e64 v99, 0, 32, vcc
	v_cndmask_b32_e64 v100, 0, 32, s[46:47]
	v_ldexp_f32 v16, v16, v99
	v_ldexp_f32 v98, v98, v100
	v_log_f32_e32 v16, v16
	v_log_f32_e32 v112, v98
	v_pk_add_f32 v[98:99], v[102:103], 1.0 op_sel_hi:[1,0] neg_lo:[1,0] neg_hi:[1,0]
	v_pk_add_f32 v[100:101], v[104:105], 1.0 op_sel_hi:[1,0] neg_lo:[1,0] neg_hi:[1,0]
	v_fma_f32 v102, v102, v99, v103
	v_mul_f32_e32 v107, v108, v109
	v_cndmask_b32_e32 v108, 0, v191, vcc
	v_fmac_f32_e32 v105, v104, v101
	v_cmp_gt_f32_e32 vcc, s31, v102
	v_cndmask_b32_e64 v109, 0, v191, s[46:47]
	v_mul_f32_e32 v98, v98, v99
	v_cndmask_b32_e64 v99, 0, 32, vcc
	v_cmp_gt_f32_e64 s[46:47], s31, v105
	v_mul_f32_e32 v103, v100, v101
	v_cvt_pk_bf16_f32 v116, v106, v98
	v_mul_f32_e32 v98, 0x3f317217, v16
	v_cndmask_b32_e64 v100, 0, 32, s[46:47]
	v_ldexp_f32 v99, v102, v99
	v_ldexp_f32 v100, v105, v100
	v_fma_f32 v98, v16, s36, -v98
	v_log_f32_e32 v99, v99
	v_mul_f32_e32 v102, 0x3f317217, v112
	v_log_f32_e32 v105, v100
	v_fmac_f32_e32 v98, 0x3377d1cf, v16
	v_cndmask_b32_e32 v101, 0, v191, vcc
	v_fma_f32 v102, v112, s36, -v102
	v_fmac_f32_e32 v98, 0x3f317217, v16
	v_cmp_lt_f32_e64 vcc, |v16|, s37
	v_fmac_f32_e32 v102, 0x3377d1cf, v112
	v_fmac_f32_e32 v102, 0x3f317217, v112
	v_cndmask_b32_e32 v16, v16, v98, vcc
	v_cmp_lt_f32_e64 vcc, |v112|, s37
	v_sub_f32_e32 v98, v16, v108
	v_mul_f32_e32 v16, 0x3f317217, v99
	v_cndmask_b32_e32 v100, v112, v102, vcc
	v_mul_f32_e32 v102, 0x3f317217, v105
	v_fma_f32 v16, v99, s36, -v16
	v_fma_f32 v102, v105, s36, -v102
	v_fmac_f32_e32 v16, 0x3377d1cf, v99
	v_fmac_f32_e32 v102, 0x3377d1cf, v105
	v_fmac_f32_e32 v16, 0x3f317217, v99
	v_cmp_lt_f32_e64 vcc, |v99|, s37
	v_fmac_f32_e32 v102, 0x3f317217, v105
	v_cndmask_b32_e64 v104, 0, v191, s[46:47]
	v_cndmask_b32_e32 v16, v99, v16, vcc
	v_cmp_lt_f32_e64 vcc, |v105|, s37
	v_sub_f32_e32 v100, v100, v109
	v_sub_f32_e32 v99, v16, v101
	v_cndmask_b32_e32 v102, v105, v102, vcc
	v_sub_f32_e32 v101, v102, v104
	global_store_dwordx4 v[110:111], v[98:101], off offset:528
	v_cvt_pk_bf16_f32 v117, v107, v103

; __device__ __forceinline__ unsigned cvt_pk_bf16(float lo, float hi) { unsigned r; asm("v_cvt_pk_bf16_f32 %0, %1, %2" : "=v"(r) : "v"(lo), "v"(hi)); return r; }
;     __device__ __forceinline__ void operator()(const f32x4 (&acc)[2][2][4][2], const Unit& u, int wr, int wc, int fr, int fq) const {
;     ...
;                 } else if (type == 4) {
;                     float* rp = (float*)base + (size_t)row * ld + col0 + cl; bf16_t* kp = (bf16_t*)(proj + (size_t)MP * 10240) + (size_t)row * ld + col0 + cl;
; #pragma unroll
;                     for (int bj = 0; bj < 2; ++bj) { f32x4 lfv[2], kkv[2];
; #pragma unroll
;                         for (int n = 0; n < 2; ++n) { const f32x4 lbq = *(const f32x4*)(lbp + col0 + cl + bj * 128 + 4 * n);
; #pragma unroll
;                             for (int e = 0; e < 4; ++e) { const float z = fminf(fmaxf(acc[ai][bj][m][n][e], -30.f), 30.f); const float sg = __builtin_amdgcn_rcpf(1.f + __expf(-z)); const float oml = 1.f - lbq[e];
;                                 lfv[n][e] = __logf(lbq[e] + oml * sg); kkv[n][e] = oml * (1.f - sg); }
;                             *(f32x4*)(rp + bj * 128 + 4 * n) = lfv[n]; }
;                         u32x4 w; w.x = cvt_pk_bf16(kkv[0][0], kkv[0][1]); w.y = cvt_pk_bf16(kkv[0][2], kkv[0][3]); w.z = cvt_pk_bf16(kkv[1][0], kkv[1][1]); w.w = cvt_pk_bf16(kkv[1][2], kkv[1][3]);
;                         *(u32x4*)(kp + bj * 128) = w; }
.LBB0_720:
	s_and_b64 vcc, exec, s[18:19]
	s_cbranch_vccz .LBB0_722
	s_lshl_b32 s18, s59, 2
	s_mov_b32 s19, s12
	v_lshl_add_u64 v[98:99], v[144:145], 0, s[18:19]
	s_nop 0
	v_lshlrev_b64 v[106:107], 12, v[104:105]
	v_max_f32_e32 v16, v94, v94
	v_max_f32_e32 v108, v95, v95
	v_max_f32_e32 v96, v96, v96
	v_lshl_add_u64 v[94:95], v[174:175], 0, v[106:107]
	v_med3_f32 v16, v16, s38, v194
	v_med3_f32 v106, v108, s38, v194
	v_med3_f32 v96, v96, s38, v194
	v_mul_f32_e32 v16, 0xbfb8aa3b, v16
	v_mul_f32_e32 v106, 0xbfb8aa3b, v106
	v_mul_f32_e32 v96, 0xbfb8aa3b, v96
	v_exp_f32_e32 v16, v16
	v_exp_f32_e32 v106, v106
	v_exp_f32_e32 v96, v96
	v_max_f32_e32 v97, v97, v97
	v_med3_f32 v97, v97, s38, v194
	v_mul_f32_e32 v97, 0xbfb8aa3b, v97
	v_exp_f32_e32 v97, v97
	v_add_f32_e32 v16, 1.0, v16
	v_add_f32_e32 v108, 1.0, v106
	v_add_f32_e32 v106, 1.0, v96
	v_rcp_f32_e32 v96, v16
	v_rcp_f32_e32 v106, v106
	v_add_f32_e32 v109, 1.0, v97
	v_max_f32_e32 v92, v92, v92
	s_mov_b32 s5, s12
	v_max_f32_e32 v93, v93, v93
	v_med3_f32 v92, v92, s38, v194
	v_mov_b32_e32 v169, v17
	v_med3_f32 v93, v93, s38, v194
	v_mul_f32_e32 v92, 0xbfb8aa3b, v92
	v_mul_f32_e32 v93, 0xbfb8aa3b, v93
	v_mov_b64_e32 v[100:101], v[204:205]
	v_mov_b64_e32 v[102:103], v[206:207]
	v_mov_b32_e32 v97, v100
	v_mov_b32_e32 v107, v102
	v_pk_add_f32 v[110:111], v[96:97], 1.0 op_sel_hi:[1,0] neg_lo:[1,0] neg_hi:[1,0]
	v_pk_add_f32 v[112:113], v[106:107], 1.0 op_sel_hi:[1,0] neg_lo:[1,0] neg_hi:[1,0]
	v_fma_f32 v16, v96, v111, v100
	v_rcp_f32_e32 v100, v108
	v_fma_f32 v96, v106, v113, v102
	v_rcp_f32_e32 v102, v109
	v_cmp_gt_f32_e32 vcc, s31, v16
	v_cmp_gt_f32_e64 s[46:47], s31, v96
	v_pk_add_f32 v[114:115], v[102:103], 1.0 op_sel_hi:[1,0] neg_lo:[1,0] neg_hi:[1,0]
	v_cndmask_b32_e64 v97, 0, 32, vcc
	v_cndmask_b32_e64 v106, 0, 32, s[46:47]
	v_ldexp_f32 v16, v16, v97
	v_ldexp_f32 v96, v96, v106
	v_log_f32_e32 v16, v16
	v_log_f32_e32 v108, v96
	v_pk_add_f32 v[96:97], v[100:101], 1.0 op_sel_hi:[1,0] neg_lo:[1,0] neg_hi:[1,0]
	v_cndmask_b32_e32 v107, 0, v191, vcc
	v_fma_f32 v100, v100, v97, v101
	v_fmac_f32_e32 v103, v102, v115
	v_cmp_gt_f32_e32 vcc, s31, v100
	v_cndmask_b32_e64 v106, 0, v191, s[46:47]
	v_cmp_gt_f32_e64 s[46:47], s31, v103
	v_cndmask_b32_e64 v101, 0, 32, vcc
	v_mul_f32_e32 v109, 0x3f317217, v16
	v_cndmask_b32_e64 v102, 0, 32, s[46:47]
	v_ldexp_f32 v100, v100, v101
	v_mul_f32_e32 v116, 0x3f317217, v108
	v_ldexp_f32 v102, v103, v102
	v_fma_f32 v109, v16, s36, -v109
	v_log_f32_e32 v117, v100
	v_fma_f32 v100, v108, s36, -v116
	v_log_f32_e32 v116, v102
	v_fmac_f32_e32 v109, 0x3377d1cf, v16
	v_cndmask_b32_e32 v101, 0, v191, vcc
	v_fmac_f32_e32 v100, 0x3377d1cf, v108
	v_fmac_f32_e32 v109, 0x3f317217, v16
	v_cmp_lt_f32_e64 vcc, |v16|, s37
	v_fmac_f32_e32 v100, 0x3f317217, v108
	v_cndmask_b32_e64 v103, 0, v191, s[46:47]
	v_cndmask_b32_e32 v16, v16, v109, vcc
	v_cmp_lt_f32_e64 vcc, |v108|, s37
	s_nop 1
	v_cndmask_b32_e32 v102, v108, v100, vcc
	v_sub_f32_e32 v100, v16, v107
	v_mul_f32_e32 v16, 0x3f317217, v117
	v_sub_f32_e32 v102, v102, v106
	v_mul_f32_e32 v106, 0x3f317217, v116
	v_fma_f32 v16, v117, s36, -v16
	v_fma_f32 v106, v116, s36, -v106
	v_fmac_f32_e32 v16, 0x3377d1cf, v117
	v_fmac_f32_e32 v106, 0x3377d1cf, v116
	v_fmac_f32_e32 v16, 0x3f317217, v117
	v_cmp_lt_f32_e64 vcc, |v117|, s37
	v_fmac_f32_e32 v106, 0x3f317217, v116
	s_nop 0
	v_cndmask_b32_e32 v16, v117, v16, vcc
	v_cmp_lt_f32_e64 vcc, |v116|, s37
	v_sub_f32_e32 v101, v16, v101
	v_max_f32_e32 v16, v90, v90
	v_cndmask_b32_e32 v106, v116, v106, vcc
	v_sub_f32_e32 v103, v106, v103
	global_store_dwordx4 v[94:95], v[100:103], off
	s_nop 0
	v_med3_f32 v16, v16, s38, v194
	v_lshlrev_b64 v[100:101], 11, v[104:105]
	v_max_f32_e32 v102, v91, v91
	v_lshl_add_u64 v[90:91], s[56:57], 0, v[100:101]
	v_med3_f32 v100, v102, s38, v194
	v_lshl_add_u64 v[90:91], v[90:91], 0, s[4:5]
	v_mul_f32_e32 v16, 0xbfb8aa3b, v16
	v_mul_f32_e32 v100, 0xbfb8aa3b, v100
	v_lshl_add_u64 v[102:103], v[90:91], 0, v[168:169]
	v_exp_f32_e32 v16, v16
	v_exp_f32_e32 v90, v100
	v_exp_f32_e32 v91, v92
	v_exp_f32_e32 v92, v93
	v_add_f32_e32 v16, 1.0, v16
	v_add_f32_e32 v116, 1.0, v90
	v_add_f32_e32 v90, 1.0, v91
	v_add_f32_e32 v117, 1.0, v92
	v_rcp_f32_e32 v92, v16
	v_rcp_f32_e32 v100, v90
	v_mul_f32_e32 v91, v112, v113
	v_mul_f32_e32 v93, v114, v115
	v_cvt_pk_bf16_f32 v91, v91, v93
	v_mul_f32_e32 v16, v110, v111
	v_mul_f32_e32 v90, v96, v97
	v_cvt_pk_bf16_f32 v90, v16, v90
	v_mov_b64_e32 v[106:107], v[208:209]
	v_mov_b64_e32 v[108:109], v[210:211]
	v_mov_b32_e32 v93, v106
	v_mov_b32_e32 v101, v108
	v_pk_add_f32 v[96:97], v[92:93], 1.0 op_sel_hi:[1,0] neg_lo:[1,0] neg_hi:[1,0]
	v_pk_add_f32 v[104:105], v[100:101], 1.0 op_sel_hi:[1,0] neg_lo:[1,0] neg_hi:[1,0]
	v_fma_f32 v16, v92, v97, v106
	v_rcp_f32_e32 v106, v116
	v_fma_f32 v92, v100, v105, v108
	v_rcp_f32_e32 v108, v117
	v_cmp_gt_f32_e32 vcc, s31, v16
	v_cmp_gt_f32_e64 s[46:47], s31, v92
	v_mul_f32_e32 v101, v96, v97
	v_cndmask_b32_e64 v93, 0, 32, vcc
	v_cndmask_b32_e64 v96, 0, 32, s[46:47]
	v_ldexp_f32 v16, v16, v93
	v_ldexp_f32 v92, v92, v96
	v_log_f32_e32 v16, v16
	v_log_f32_e32 v110, v92
	v_pk_add_f32 v[92:93], v[106:107], 1.0 op_sel_hi:[1,0] neg_lo:[1,0] neg_hi:[1,0]
	v_pk_add_f32 v[96:97], v[108:109], 1.0 op_sel_hi:[1,0] neg_lo:[1,0] neg_hi:[1,0]
	v_fma_f32 v106, v106, v93, v107
	v_mul_f32_e32 v100, v104, v105
	v_cndmask_b32_e32 v104, 0, v191, vcc
	v_fmac_f32_e32 v109, v108, v97
	v_cmp_gt_f32_e32 vcc, s31, v106
	v_cndmask_b32_e64 v105, 0, v191, s[46:47]
	v_mul_f32_e32 v92, v92, v93
	v_mul_f32_e32 v93, v96, v97
	v_cndmask_b32_e64 v96, 0, 32, vcc
	v_cmp_gt_f32_e64 s[46:47], s31, v109
	v_cvt_pk_bf16_f32 v93, v100, v93
; __device__ __forceinline__ unsigned cvt_pk_bf16(float lo, float hi) { unsigned r; asm("v_cvt_pk_bf16_f32 %0, %1, %2" : "=v"(r) : "v"(lo), "v"(hi)); return r; }
;     __device__ __forceinline__ void operator()(const f32x4 (&acc)[2][2][4][2], const Unit& u, int wr, int wc, int fr, int fq) const {
;     ...
;                 } else if (type == 4) {
;                     float* rp = (float*)base + (size_t)row * ld + col0 + cl; bf16_t* kp = (bf16_t*)(proj + (size_t)MP * 10240) + (size_t)row * ld + col0 + cl;
; #pragma unroll
;                     for (int bj = 0; bj < 2; ++bj) { f32x4 lfv[2], kkv[2];
; #pragma unroll
;                         for (int n = 0; n < 2; ++n) { const f32x4 lbq = *(const f32x4*)(lbp + col0 + cl + bj * 128 + 4 * n);
; #pragma unroll
;                             for (int e = 0; e < 4; ++e) { const float z = fminf(fmaxf(acc[ai][bj][m][n][e], -30.f), 30.f); const float sg = __builtin_amdgcn_rcpf(1.f + __expf(-z)); const float oml = 1.f - lbq[e];
;                                 lfv[n][e] = __logf(lbq[e] + oml * sg); kkv[n][e] = oml * (1.f - sg); }
;                             *(f32x4*)(rp + bj * 128 + 4 * n) = lfv[n]; }
;                         u32x4 w; w.x = cvt_pk_bf16(kkv[0][0], kkv[0][1]); w.y = cvt_pk_bf16(kkv[0][2], kkv[0][3]); w.z = cvt_pk_bf16(kkv[1][0], kkv[1][1]); w.w = cvt_pk_bf16(kkv[1][2], kkv[1][3]);
;                         *(u32x4*)(kp + bj * 128) = w; }
	v_mul_f32_e32 v100, 0x3f317217, v16
	v_ldexp_f32 v96, v106, v96
	v_cndmask_b32_e64 v97, 0, 32, s[46:47]
	v_mul_f32_e32 v106, 0x3f317217, v110
	v_ldexp_f32 v97, v109, v97
	v_fma_f32 v100, v16, s36, -v100
	v_log_f32_e32 v96, v96
	v_fma_f32 v106, v110, s36, -v106
	v_log_f32_e32 v97, v97
	v_fmac_f32_e32 v100, 0x3377d1cf, v16
	v_cvt_pk_bf16_f32 v92, v101, v92
	v_cndmask_b32_e32 v101, 0, v191, vcc
	v_fmac_f32_e32 v106, 0x3377d1cf, v110
	v_fmac_f32_e32 v100, 0x3f317217, v16
	v_cmp_lt_f32_e64 vcc, |v16|, s37
	v_fmac_f32_e32 v106, 0x3f317217, v110
	v_cndmask_b32_e64 v107, 0, v191, s[46:47]
	v_cndmask_b32_e32 v16, v16, v100, vcc
	v_cmp_lt_f32_e64 vcc, |v110|, s37
	v_sub_f32_e32 v104, v16, v104
	v_mul_f32_e32 v16, 0x3f317217, v96
	v_cndmask_b32_e32 v100, v110, v106, vcc
	v_sub_f32_e32 v106, v100, v105
	v_mul_f32_e32 v100, 0x3f317217, v97
	v_fma_f32 v16, v96, s36, -v16
	v_fma_f32 v100, v97, s36, -v100
	v_fmac_f32_e32 v16, 0x3377d1cf, v96
	v_fmac_f32_e32 v100, 0x3377d1cf, v97
	v_fmac_f32_e32 v16, 0x3f317217, v96
	v_cmp_lt_f32_e64 vcc, |v96|, s37
	v_fmac_f32_e32 v100, 0x3f317217, v97
	s_nop 0
	v_cndmask_b32_e32 v16, v96, v16, vcc
	v_cmp_lt_f32_e64 vcc, |v97|, s37
	v_sub_f32_e32 v105, v16, v101
	v_max_f32_e32 v16, v86, v86
	v_cndmask_b32_e32 v96, v97, v100, vcc
	v_sub_f32_e32 v107, v96, v107
	global_store_dwordx4 v[94:95], v[104:107], off offset:16
	global_store_dwordx4 v[102:103], v[90:93], off
	s_nop 0
	v_max_f32_e32 v86, v87, v87
	v_max_f32_e32 v87, v88, v88
	v_med3_f32 v16, v16, s38, v194
	v_max_f32_e32 v88, v89, v89
	v_med3_f32 v86, v86, s38, v194
	v_med3_f32 v87, v87, s38, v194
	v_mul_f32_e32 v16, 0xbfb8aa3b, v16
	v_med3_f32 v88, v88, s38, v194
	v_mul_f32_e32 v86, 0xbfb8aa3b, v86
	v_mul_f32_e32 v87, 0xbfb8aa3b, v87
	v_exp_f32_e32 v16, v16
	v_mul_f32_e32 v88, 0xbfb8aa3b, v88
	v_exp_f32_e32 v86, v86
	v_exp_f32_e32 v87, v87
	v_exp_f32_e32 v88, v88
	v_add_f32_e32 v16, 1.0, v16
	v_add_f32_e32 v104, 1.0, v86
	v_add_f32_e32 v87, 1.0, v87
	v_rcp_f32_e32 v86, v16
	v_add_f32_e32 v105, 1.0, v88
	v_rcp_f32_e32 v88, v87
	v_mov_b64_e32 v[90:91], v[212:213]
	v_mov_b64_e32 v[92:93], v[214:215]
	v_mov_b32_e32 v87, v90
	v_mov_b32_e32 v89, v92
	v_pk_add_f32 v[96:97], v[86:87], 1.0 op_sel_hi:[1,0] neg_lo:[1,0] neg_hi:[1,0]
	v_pk_add_f32 v[100:101], v[88:89], 1.0 op_sel_hi:[1,0] neg_lo:[1,0] neg_hi:[1,0]
	v_fma_f32 v16, v86, v97, v90
	v_rcp_f32_e32 v90, v104
	v_fma_f32 v86, v88, v101, v92
	v_rcp_f32_e32 v92, v105
	v_cmp_gt_f32_e32 vcc, s31, v16
	v_cmp_gt_f32_e64 s[46:47], s31, v86
	v_pk_add_f32 v[104:105], v[90:91], 1.0 op_sel_hi:[1,0] neg_lo:[1,0] neg_hi:[1,0]
	v_cndmask_b32_e64 v87, 0, 32, vcc
	v_cndmask_b32_e64 v88, 0, 32, s[46:47]
	v_ldexp_f32 v16, v16, v87
	v_ldexp_f32 v86, v86, v88
	v_log_f32_e32 v16, v16
	v_log_f32_e32 v86, v86
	v_pk_add_f32 v[106:107], v[92:93], 1.0 op_sel_hi:[1,0] neg_lo:[1,0] neg_hi:[1,0]
	v_fma_f32 v89, v90, v105, v91
	v_cndmask_b32_e32 v87, 0, v191, vcc
	v_fmac_f32_e32 v93, v92, v107
	v_cmp_gt_f32_e32 vcc, s31, v89
	v_cndmask_b32_e64 v88, 0, v191, s[46:47]
	v_cmp_gt_f32_e64 s[46:47], s31, v93
	v_cndmask_b32_e64 v90, 0, 32, vcc
	v_mul_f32_e32 v92, 0x3f317217, v16
	v_cndmask_b32_e64 v91, 0, 32, s[46:47]
	v_ldexp_f32 v89, v89, v90
	v_mul_f32_e32 v108, 0x3f317217, v86
	v_ldexp_f32 v91, v93, v91
	v_fma_f32 v92, v16, s36, -v92
	v_log_f32_e32 v89, v89
	v_fma_f32 v108, v86, s36, -v108
	v_log_f32_e32 v91, v91
	v_fmac_f32_e32 v92, 0x3377d1cf, v16
	v_cndmask_b32_e32 v90, 0, v191, vcc
	v_fmac_f32_e32 v108, 0x3377d1cf, v86
	v_fmac_f32_e32 v92, 0x3f317217, v16
	v_cmp_lt_f32_e64 vcc, |v16|, s37
	v_fmac_f32_e32 v108, 0x3f317217, v86
	v_cndmask_b32_e64 v93, 0, v191, s[46:47]
	v_cndmask_b32_e32 v16, v16, v92, vcc
	v_cmp_lt_f32_e64 vcc, |v86|, s37
	s_nop 1
	v_cndmask_b32_e32 v92, v86, v108, vcc
	v_sub_f32_e32 v86, v16, v87
	v_mul_f32_e32 v16, 0x3f317217, v89
	v_mul_f32_e32 v87, 0x3f317217, v91
; __device__ __forceinline__ unsigned cvt_pk_bf16(float lo, float hi) { unsigned r; asm("v_cvt_pk_bf16_f32 %0, %1, %2" : "=v"(r) : "v"(lo), "v"(hi)); return r; }
;     __device__ __forceinline__ void operator()(const f32x4 (&acc)[2][2][4][2], const Unit& u, int wr, int wc, int fr, int fq) const {
;     ...
;                 } else if (type == 4) {
;                     float* rp = (float*)base + (size_t)row * ld + col0 + cl; bf16_t* kp = (bf16_t*)(proj + (size_t)MP * 10240) + (size_t)row * ld + col0 + cl;
; #pragma unroll
;                     for (int bj = 0; bj < 2; ++bj) { f32x4 lfv[2], kkv[2];
; #pragma unroll
;                         for (int n = 0; n < 2; ++n) { const f32x4 lbq = *(const f32x4*)(lbp + col0 + cl + bj * 128 + 4 * n);
; #pragma unroll
;                             for (int e = 0; e < 4; ++e) { const float z = fminf(fmaxf(acc[ai][bj][m][n][e], -30.f), 30.f); const float sg = __builtin_amdgcn_rcpf(1.f + __expf(-z)); const float oml = 1.f - lbq[e];
;                                 lfv[n][e] = __logf(lbq[e] + oml * sg); kkv[n][e] = oml * (1.f - sg); }
;                             *(f32x4*)(rp + bj * 128 + 4 * n) = lfv[n]; }
;                         u32x4 w; w.x = cvt_pk_bf16(kkv[0][0], kkv[0][1]); w.y = cvt_pk_bf16(kkv[0][2], kkv[0][3]); w.z = cvt_pk_bf16(kkv[1][0], kkv[1][1]); w.w = cvt_pk_bf16(kkv[1][2], kkv[1][3]);
;                         *(u32x4*)(kp + bj * 128) = w; }
	v_fma_f32 v16, v89, s36, -v16
	v_fma_f32 v87, v91, s36, -v87
	v_fmac_f32_e32 v16, 0x3377d1cf, v89
	v_fmac_f32_e32 v87, 0x3377d1cf, v91
	v_fmac_f32_e32 v16, 0x3f317217, v89
	v_cmp_lt_f32_e64 vcc, |v89|, s37
	v_fmac_f32_e32 v87, 0x3f317217, v91
	v_sub_f32_e32 v88, v92, v88
	v_cndmask_b32_e32 v16, v89, v16, vcc
	v_cmp_lt_f32_e64 vcc, |v91|, s37
	s_nop 1
	v_cndmask_b32_e32 v89, v91, v87, vcc
	v_sub_f32_e32 v87, v16, v90
	v_sub_f32_e32 v89, v89, v93
	global_store_dwordx4 v[94:95], v[86:89], off offset:512
	s_nop 0
	v_max_f32_e32 v16, v82, v82
	v_max_f32_e32 v82, v83, v83
	v_max_f32_e32 v83, v84, v84
	v_max_f32_e32 v84, v85, v85
	v_med3_f32 v16, v16, s38, v194
	v_med3_f32 v83, v83, s38, v194
	v_med3_f32 v82, v82, s38, v194
	v_med3_f32 v84, v84, s38, v194
	v_mul_f32_e32 v16, 0xbfb8aa3b, v16
	v_mul_f32_e32 v83, 0xbfb8aa3b, v83
	v_mul_f32_e32 v82, 0xbfb8aa3b, v82
	v_mul_f32_e32 v84, 0xbfb8aa3b, v84
	v_exp_f32_e32 v16, v16
	v_exp_f32_e32 v83, v83
	v_exp_f32_e32 v82, v82
	v_exp_f32_e32 v84, v84
	v_add_f32_e32 v16, 1.0, v16
	v_add_f32_e32 v83, 1.0, v83
	v_add_f32_e32 v108, 1.0, v82
	v_add_f32_e32 v109, 1.0, v84
	v_rcp_f32_e32 v82, v16
	v_rcp_f32_e32 v84, v83
	v_mul_f32_e32 v83, v100, v101
	v_mul_f32_e32 v85, v104, v105
	v_mul_f32_e32 v16, v96, v97
	v_mul_f32_e32 v90, v106, v107
	v_cvt_pk_bf16_f32 v98, v16, v85
	v_cvt_pk_bf16_f32 v99, v83, v90
	v_mov_b64_e32 v[86:87], v[216:217]
	v_mov_b64_e32 v[88:89], v[218:219]
	v_mov_b32_e32 v83, v86
	v_mov_b32_e32 v85, v88
	v_pk_add_f32 v[90:91], v[82:83], 1.0 op_sel_hi:[1,0] neg_lo:[1,0] neg_hi:[1,0]
	v_pk_add_f32 v[92:93], v[84:85], 1.0 op_sel_hi:[1,0] neg_lo:[1,0] neg_hi:[1,0]
	v_fma_f32 v16, v82, v91, v86
	v_rcp_f32_e32 v86, v108
	v_fma_f32 v82, v84, v93, v88
	v_rcp_f32_e32 v88, v109
	v_cmp_gt_f32_e32 vcc, s31, v16
	v_cmp_gt_f32_e64 s[46:47], s31, v82
	v_mul_f32_e32 v90, v90, v91
	v_cndmask_b32_e64 v83, 0, 32, vcc
	v_cndmask_b32_e64 v84, 0, 32, s[46:47]
	v_ldexp_f32 v16, v16, v83
	v_ldexp_f32 v82, v82, v84
	v_log_f32_e32 v16, v16
	v_log_f32_e32 v96, v82
	v_pk_add_f32 v[82:83], v[86:87], 1.0 op_sel_hi:[1,0] neg_lo:[1,0] neg_hi:[1,0]
	v_pk_add_f32 v[84:85], v[88:89], 1.0 op_sel_hi:[1,0] neg_lo:[1,0] neg_hi:[1,0]
	v_fma_f32 v86, v86, v83, v87
	v_mul_f32_e32 v91, v92, v93
	v_cndmask_b32_e32 v92, 0, v191, vcc
	v_fmac_f32_e32 v89, v88, v85
	v_cmp_gt_f32_e32 vcc, s31, v86
	v_cndmask_b32_e64 v93, 0, v191, s[46:47]
	v_mul_f32_e32 v82, v82, v83
	v_cndmask_b32_e64 v83, 0, 32, vcc
	v_cmp_gt_f32_e64 s[46:47], s31, v89
	v_mul_f32_e32 v87, v84, v85
	v_cvt_pk_bf16_f32 v100, v90, v82
	v_mul_f32_e32 v82, 0x3f317217, v16
	v_cndmask_b32_e64 v84, 0, 32, s[46:47]
	v_ldexp_f32 v83, v86, v83
	v_ldexp_f32 v84, v89, v84
	v_fma_f32 v82, v16, s36, -v82
	v_log_f32_e32 v83, v83
	v_mul_f32_e32 v86, 0x3f317217, v96
	v_log_f32_e32 v89, v84
	v_fmac_f32_e32 v82, 0x3377d1cf, v16
	v_cndmask_b32_e32 v85, 0, v191, vcc
	v_fma_f32 v86, v96, s36, -v86
	v_fmac_f32_e32 v82, 0x3f317217, v16
	v_cmp_lt_f32_e64 vcc, |v16|, s37
	v_fmac_f32_e32 v86, 0x3377d1cf, v96
	v_fmac_f32_e32 v86, 0x3f317217, v96
	v_cndmask_b32_e32 v16, v16, v82, vcc
	v_cmp_lt_f32_e64 vcc, |v96|, s37
	v_sub_f32_e32 v82, v16, v92
	v_mul_f32_e32 v16, 0x3f317217, v83
	v_cndmask_b32_e32 v84, v96, v86, vcc
	v_mul_f32_e32 v86, 0x3f317217, v89
	v_fma_f32 v16, v83, s36, -v16
	v_fma_f32 v86, v89, s36, -v86
	v_fmac_f32_e32 v16, 0x3377d1cf, v83
	v_fmac_f32_e32 v86, 0x3377d1cf, v89
	v_fmac_f32_e32 v16, 0x3f317217, v83
	v_cmp_lt_f32_e64 vcc, |v83|, s37
	v_fmac_f32_e32 v86, 0x3f317217, v89
	v_cndmask_b32_e64 v88, 0, v191, s[46:47]
	v_cndmask_b32_e32 v16, v83, v16, vcc
	v_cmp_lt_f32_e64 vcc, |v89|, s37
	v_sub_f32_e32 v84, v84, v93
	v_sub_f32_e32 v83, v16, v85
	v_cndmask_b32_e32 v86, v89, v86, vcc
	v_sub_f32_e32 v85, v86, v88
	global_store_dwordx4 v[94:95], v[82:85], off offset:528
	v_cvt_pk_bf16_f32 v101, v91, v87

; __device__ __forceinline__ unsigned cvt_pk_bf16(float lo, float hi) { unsigned r; asm("v_cvt_pk_bf16_f32 %0, %1, %2" : "=v"(r) : "v"(lo), "v"(hi)); return r; }
;     __device__ __forceinline__ void operator()(const f32x4 (&acc)[2][2][4][2], const Unit& u, int wr, int wc, int fr, int fq) const {
;     ...
;                 } else if (type == 4) {
;                     float* rp = (float*)base + (size_t)row * ld + col0 + cl; bf16_t* kp = (bf16_t*)(proj + (size_t)MP * 10240) + (size_t)row * ld + col0 + cl;
; #pragma unroll
;                     for (int bj = 0; bj < 2; ++bj) { f32x4 lfv[2], kkv[2];
; #pragma unroll
;                         for (int n = 0; n < 2; ++n) { const f32x4 lbq = *(const f32x4*)(lbp + col0 + cl + bj * 128 + 4 * n);
; #pragma unroll
;                             for (int e = 0; e < 4; ++e) { const float z = fminf(fmaxf(acc[ai][bj][m][n][e], -30.f), 30.f); const float sg = __builtin_amdgcn_rcpf(1.f + __expf(-z)); const float oml = 1.f - lbq[e];
;                                 lfv[n][e] = __logf(lbq[e] + oml * sg); kkv[n][e] = oml * (1.f - sg); }
;                             *(f32x4*)(rp + bj * 128 + 4 * n) = lfv[n]; }
;                         u32x4 w; w.x = cvt_pk_bf16(kkv[0][0], kkv[0][1]); w.y = cvt_pk_bf16(kkv[0][2], kkv[0][3]); w.z = cvt_pk_bf16(kkv[1][0], kkv[1][1]); w.w = cvt_pk_bf16(kkv[1][2], kkv[1][3]);
;                         *(u32x4*)(kp + bj * 128) = w; }
.LBB0_728:
	s_and_b64 vcc, exec, s[18:19]
	s_cbranch_vccz .LBB0_730
	s_lshl_b32 s18, s59, 2
	s_mov_b32 s19, s12
	v_lshl_add_u64 v[82:83], v[144:145], 0, s[18:19]
	s_nop 0
	v_lshlrev_b64 v[90:91], 12, v[88:89]
	v_max_f32_e32 v16, v78, v78
	v_max_f32_e32 v92, v79, v79
	v_max_f32_e32 v80, v80, v80
	v_lshl_add_u64 v[78:79], v[174:175], 0, v[90:91]
	v_med3_f32 v16, v16, s38, v194
	v_med3_f32 v90, v92, s38, v194
	v_med3_f32 v80, v80, s38, v194
	v_mul_f32_e32 v16, 0xbfb8aa3b, v16
	v_mul_f32_e32 v90, 0xbfb8aa3b, v90
	v_mul_f32_e32 v80, 0xbfb8aa3b, v80
	v_exp_f32_e32 v16, v16
	v_exp_f32_e32 v90, v90
	v_exp_f32_e32 v80, v80
	v_max_f32_e32 v81, v81, v81
	v_med3_f32 v81, v81, s38, v194
	v_mul_f32_e32 v81, 0xbfb8aa3b, v81
	v_exp_f32_e32 v81, v81
	v_add_f32_e32 v16, 1.0, v16
	v_add_f32_e32 v92, 1.0, v90
	v_add_f32_e32 v90, 1.0, v80
	v_rcp_f32_e32 v80, v16
	v_rcp_f32_e32 v90, v90
	v_add_f32_e32 v93, 1.0, v81
	v_max_f32_e32 v76, v76, v76
	s_mov_b32 s5, s12
	v_max_f32_e32 v77, v77, v77
	v_med3_f32 v76, v76, s38, v194
	v_mov_b32_e32 v169, v17
	v_med3_f32 v77, v77, s38, v194
	v_mul_f32_e32 v76, 0xbfb8aa3b, v76
	v_mul_f32_e32 v77, 0xbfb8aa3b, v77
	v_mov_b64_e32 v[84:85], v[204:205]
	v_mov_b64_e32 v[86:87], v[206:207]
	v_mov_b32_e32 v81, v84
	v_mov_b32_e32 v91, v86
	v_pk_add_f32 v[94:95], v[80:81], 1.0 op_sel_hi:[1,0] neg_lo:[1,0] neg_hi:[1,0]
	v_pk_add_f32 v[96:97], v[90:91], 1.0 op_sel_hi:[1,0] neg_lo:[1,0] neg_hi:[1,0]
	v_fma_f32 v16, v80, v95, v84
	v_rcp_f32_e32 v84, v92
	v_fma_f32 v80, v90, v97, v86
	v_rcp_f32_e32 v86, v93
	v_cmp_gt_f32_e32 vcc, s31, v16
	v_cmp_gt_f32_e64 s[46:47], s31, v80
	v_pk_add_f32 v[98:99], v[86:87], 1.0 op_sel_hi:[1,0] neg_lo:[1,0] neg_hi:[1,0]
	v_cndmask_b32_e64 v81, 0, 32, vcc
	v_cndmask_b32_e64 v90, 0, 32, s[46:47]
	v_ldexp_f32 v16, v16, v81
	v_ldexp_f32 v80, v80, v90
	v_log_f32_e32 v16, v16
	v_log_f32_e32 v92, v80
	v_pk_add_f32 v[80:81], v[84:85], 1.0 op_sel_hi:[1,0] neg_lo:[1,0] neg_hi:[1,0]
	v_cndmask_b32_e32 v91, 0, v191, vcc
	v_fma_f32 v84, v84, v81, v85
	v_fmac_f32_e32 v87, v86, v99
	v_cmp_gt_f32_e32 vcc, s31, v84
	v_cndmask_b32_e64 v90, 0, v191, s[46:47]
	v_cmp_gt_f32_e64 s[46:47], s31, v87
	v_cndmask_b32_e64 v85, 0, 32, vcc
	v_mul_f32_e32 v93, 0x3f317217, v16
	v_cndmask_b32_e64 v86, 0, 32, s[46:47]
	v_ldexp_f32 v84, v84, v85
	v_mul_f32_e32 v100, 0x3f317217, v92
	v_ldexp_f32 v86, v87, v86
	v_fma_f32 v93, v16, s36, -v93
	v_log_f32_e32 v101, v84
	v_fma_f32 v84, v92, s36, -v100
	v_log_f32_e32 v100, v86
	v_fmac_f32_e32 v93, 0x3377d1cf, v16
	v_cndmask_b32_e32 v85, 0, v191, vcc
	v_fmac_f32_e32 v84, 0x3377d1cf, v92
	v_fmac_f32_e32 v93, 0x3f317217, v16
	v_cmp_lt_f32_e64 vcc, |v16|, s37
	v_fmac_f32_e32 v84, 0x3f317217, v92
	v_cndmask_b32_e64 v87, 0, v191, s[46:47]
	v_cndmask_b32_e32 v16, v16, v93, vcc
	v_cmp_lt_f32_e64 vcc, |v92|, s37
	s_nop 1
	v_cndmask_b32_e32 v86, v92, v84, vcc
	v_sub_f32_e32 v84, v16, v91
	v_mul_f32_e32 v16, 0x3f317217, v101
	v_sub_f32_e32 v86, v86, v90
	v_mul_f32_e32 v90, 0x3f317217, v100
	v_fma_f32 v16, v101, s36, -v16
	v_fma_f32 v90, v100, s36, -v90
	v_fmac_f32_e32 v16, 0x3377d1cf, v101
	v_fmac_f32_e32 v90, 0x3377d1cf, v100
	v_fmac_f32_e32 v16, 0x3f317217, v101
	v_cmp_lt_f32_e64 vcc, |v101|, s37
	v_fmac_f32_e32 v90, 0x3f317217, v100
	s_nop 0
	v_cndmask_b32_e32 v16, v101, v16, vcc
	v_cmp_lt_f32_e64 vcc, |v100|, s37
	v_sub_f32_e32 v85, v16, v85
	v_max_f32_e32 v16, v74, v74
	v_cndmask_b32_e32 v90, v100, v90, vcc
	v_sub_f32_e32 v87, v90, v87
	global_store_dwordx4 v[78:79], v[84:87], off
	s_nop 0
	v_med3_f32 v16, v16, s38, v194
	v_lshlrev_b64 v[84:85], 11, v[88:89]
	v_max_f32_e32 v86, v75, v75
	v_lshl_add_u64 v[74:75], s[56:57], 0, v[84:85]
	v_med3_f32 v84, v86, s38, v194
	v_lshl_add_u64 v[74:75], v[74:75], 0, s[4:5]
	v_mul_f32_e32 v16, 0xbfb8aa3b, v16
	v_mul_f32_e32 v84, 0xbfb8aa3b, v84
	v_lshl_add_u64 v[86:87], v[74:75], 0, v[168:169]
	v_exp_f32_e32 v16, v16
	v_exp_f32_e32 v74, v84
	v_exp_f32_e32 v75, v76
	v_exp_f32_e32 v76, v77
	v_add_f32_e32 v16, 1.0, v16
	v_add_f32_e32 v100, 1.0, v74
	v_add_f32_e32 v74, 1.0, v75
	v_add_f32_e32 v101, 1.0, v76
	v_rcp_f32_e32 v76, v16
	v_rcp_f32_e32 v84, v74
	v_mul_f32_e32 v75, v96, v97
	v_mul_f32_e32 v77, v98, v99
	v_cvt_pk_bf16_f32 v75, v75, v77
	v_mul_f32_e32 v16, v94, v95
	v_mul_f32_e32 v74, v80, v81
	v_cvt_pk_bf16_f32 v74, v16, v74
	v_mov_b64_e32 v[90:91], v[208:209]
	v_mov_b64_e32 v[92:93], v[210:211]
	v_mov_b32_e32 v77, v90
	v_mov_b32_e32 v85, v92
	v_pk_add_f32 v[80:81], v[76:77], 1.0 op_sel_hi:[1,0] neg_lo:[1,0] neg_hi:[1,0]
	v_pk_add_f32 v[88:89], v[84:85], 1.0 op_sel_hi:[1,0] neg_lo:[1,0] neg_hi:[1,0]
	v_fma_f32 v16, v76, v81, v90
	v_rcp_f32_e32 v90, v100
	v_fma_f32 v76, v84, v89, v92
	v_rcp_f32_e32 v92, v101
	v_cmp_gt_f32_e32 vcc, s31, v16
	v_cmp_gt_f32_e64 s[46:47], s31, v76
	v_mul_f32_e32 v85, v80, v81
	v_cndmask_b32_e64 v77, 0, 32, vcc
	v_cndmask_b32_e64 v80, 0, 32, s[46:47]
	v_ldexp_f32 v16, v16, v77
	v_ldexp_f32 v76, v76, v80
	v_log_f32_e32 v16, v16
	v_log_f32_e32 v94, v76
	v_pk_add_f32 v[76:77], v[90:91], 1.0 op_sel_hi:[1,0] neg_lo:[1,0] neg_hi:[1,0]
	v_pk_add_f32 v[80:81], v[92:93], 1.0 op_sel_hi:[1,0] neg_lo:[1,0] neg_hi:[1,0]
	v_fma_f32 v90, v90, v77, v91
	v_mul_f32_e32 v84, v88, v89
	v_cndmask_b32_e32 v88, 0, v191, vcc
	v_fmac_f32_e32 v93, v92, v81
	v_cmp_gt_f32_e32 vcc, s31, v90
	v_cndmask_b32_e64 v89, 0, v191, s[46:47]
	v_mul_f32_e32 v76, v76, v77
	v_mul_f32_e32 v77, v80, v81
	v_cndmask_b32_e64 v80, 0, 32, vcc
	v_cmp_gt_f32_e64 s[46:47], s31, v93
	v_cvt_pk_bf16_f32 v77, v84, v77
	v_mul_f32_e32 v84, 0x3f317217, v16
	v_ldexp_f32 v80, v90, v80
	v_cndmask_b32_e64 v81, 0, 32, s[46:47]
	v_mul_f32_e32 v90, 0x3f317217, v94
	v_ldexp_f32 v81, v93, v81
; __device__ __forceinline__ unsigned cvt_pk_bf16(float lo, float hi) { unsigned r; asm("v_cvt_pk_bf16_f32 %0, %1, %2" : "=v"(r) : "v"(lo), "v"(hi)); return r; }
;     __device__ __forceinline__ void operator()(const f32x4 (&acc)[2][2][4][2], const Unit& u, int wr, int wc, int fr, int fq) const {
;     ...
;                 } else if (type == 4) {
;                     float* rp = (float*)base + (size_t)row * ld + col0 + cl; bf16_t* kp = (bf16_t*)(proj + (size_t)MP * 10240) + (size_t)row * ld + col0 + cl;
; #pragma unroll
;                     for (int bj = 0; bj < 2; ++bj) { f32x4 lfv[2], kkv[2];
; #pragma unroll
;                         for (int n = 0; n < 2; ++n) { const f32x4 lbq = *(const f32x4*)(lbp + col0 + cl + bj * 128 + 4 * n);
; #pragma unroll
;                             for (int e = 0; e < 4; ++e) { const float z = fminf(fmaxf(acc[ai][bj][m][n][e], -30.f), 30.f); const float sg = __builtin_amdgcn_rcpf(1.f + __expf(-z)); const float oml = 1.f - lbq[e];
;                                 lfv[n][e] = __logf(lbq[e] + oml * sg); kkv[n][e] = oml * (1.f - sg); }
;                             *(f32x4*)(rp + bj * 128 + 4 * n) = lfv[n]; }
;                         u32x4 w; w.x = cvt_pk_bf16(kkv[0][0], kkv[0][1]); w.y = cvt_pk_bf16(kkv[0][2], kkv[0][3]); w.z = cvt_pk_bf16(kkv[1][0], kkv[1][1]); w.w = cvt_pk_bf16(kkv[1][2], kkv[1][3]);
;                         *(u32x4*)(kp + bj * 128) = w; }
	v_fma_f32 v84, v16, s36, -v84
	v_log_f32_e32 v80, v80
	v_fma_f32 v90, v94, s36, -v90
	v_log_f32_e32 v81, v81
	v_fmac_f32_e32 v84, 0x3377d1cf, v16
	v_cvt_pk_bf16_f32 v76, v85, v76
	v_cndmask_b32_e32 v85, 0, v191, vcc
	v_fmac_f32_e32 v90, 0x3377d1cf, v94
	v_fmac_f32_e32 v84, 0x3f317217, v16
	v_cmp_lt_f32_e64 vcc, |v16|, s37
	v_fmac_f32_e32 v90, 0x3f317217, v94
	v_cndmask_b32_e64 v91, 0, v191, s[46:47]
	v_cndmask_b32_e32 v16, v16, v84, vcc
	v_cmp_lt_f32_e64 vcc, |v94|, s37
	v_sub_f32_e32 v88, v16, v88
	v_mul_f32_e32 v16, 0x3f317217, v80
	v_cndmask_b32_e32 v84, v94, v90, vcc
	v_sub_f32_e32 v90, v84, v89
	v_mul_f32_e32 v84, 0x3f317217, v81
	v_fma_f32 v16, v80, s36, -v16
	v_fma_f32 v84, v81, s36, -v84
	v_fmac_f32_e32 v16, 0x3377d1cf, v80
	v_fmac_f32_e32 v84, 0x3377d1cf, v81
	v_fmac_f32_e32 v16, 0x3f317217, v80
	v_cmp_lt_f32_e64 vcc, |v80|, s37
	v_fmac_f32_e32 v84, 0x3f317217, v81
	s_nop 0
	v_cndmask_b32_e32 v16, v80, v16, vcc
	v_cmp_lt_f32_e64 vcc, |v81|, s37
	v_sub_f32_e32 v89, v16, v85
	v_max_f32_e32 v16, v70, v70
	v_cndmask_b32_e32 v80, v81, v84, vcc
	v_sub_f32_e32 v91, v80, v91
	global_store_dwordx4 v[78:79], v[88:91], off offset:16
	global_store_dwordx4 v[86:87], v[74:77], off
	s_nop 0
	v_max_f32_e32 v70, v71, v71
	v_max_f32_e32 v71, v72, v72
	v_med3_f32 v16, v16, s38, v194
	v_max_f32_e32 v72, v73, v73
	v_med3_f32 v70, v70, s38, v194
	v_med3_f32 v71, v71, s38, v194
	v_mul_f32_e32 v16, 0xbfb8aa3b, v16
	v_med3_f32 v72, v72, s38, v194
	v_mul_f32_e32 v70, 0xbfb8aa3b, v70
	v_mul_f32_e32 v71, 0xbfb8aa3b, v71
	v_exp_f32_e32 v16, v16
	v_mul_f32_e32 v72, 0xbfb8aa3b, v72
	v_exp_f32_e32 v70, v70
	v_exp_f32_e32 v71, v71
	v_exp_f32_e32 v72, v72
	v_add_f32_e32 v16, 1.0, v16
	v_add_f32_e32 v88, 1.0, v70
	v_add_f32_e32 v71, 1.0, v71
	v_rcp_f32_e32 v70, v16
	v_add_f32_e32 v89, 1.0, v72
	v_rcp_f32_e32 v72, v71
	v_mov_b64_e32 v[74:75], v[212:213]
	v_mov_b64_e32 v[76:77], v[214:215]
	v_mov_b32_e32 v71, v74
	v_mov_b32_e32 v73, v76
	v_pk_add_f32 v[80:81], v[70:71], 1.0 op_sel_hi:[1,0] neg_lo:[1,0] neg_hi:[1,0]
	v_pk_add_f32 v[84:85], v[72:73], 1.0 op_sel_hi:[1,0] neg_lo:[1,0] neg_hi:[1,0]
	v_fma_f32 v16, v70, v81, v74
	v_rcp_f32_e32 v74, v88
	v_fma_f32 v70, v72, v85, v76
	v_rcp_f32_e32 v76, v89
	v_cmp_gt_f32_e32 vcc, s31, v16
	v_cmp_gt_f32_e64 s[46:47], s31, v70
	v_pk_add_f32 v[88:89], v[74:75], 1.0 op_sel_hi:[1,0] neg_lo:[1,0] neg_hi:[1,0]
	v_cndmask_b32_e64 v71, 0, 32, vcc
	v_cndmask_b32_e64 v72, 0, 32, s[46:47]
	v_ldexp_f32 v16, v16, v71
	v_ldexp_f32 v70, v70, v72
	v_log_f32_e32 v16, v16
	v_log_f32_e32 v70, v70
	v_pk_add_f32 v[90:91], v[76:77], 1.0 op_sel_hi:[1,0] neg_lo:[1,0] neg_hi:[1,0]
	v_fma_f32 v73, v74, v89, v75
	v_cndmask_b32_e32 v71, 0, v191, vcc
	v_fmac_f32_e32 v77, v76, v91
	v_cmp_gt_f32_e32 vcc, s31, v73
	v_cndmask_b32_e64 v72, 0, v191, s[46:47]
	v_cmp_gt_f32_e64 s[46:47], s31, v77
	v_cndmask_b32_e64 v74, 0, 32, vcc
	v_mul_f32_e32 v76, 0x3f317217, v16
	v_cndmask_b32_e64 v75, 0, 32, s[46:47]
	v_ldexp_f32 v73, v73, v74
	v_mul_f32_e32 v92, 0x3f317217, v70
	v_ldexp_f32 v75, v77, v75
	v_fma_f32 v76, v16, s36, -v76
	v_log_f32_e32 v73, v73
	v_fma_f32 v92, v70, s36, -v92
	v_log_f32_e32 v75, v75
	v_fmac_f32_e32 v76, 0x3377d1cf, v16
	v_cndmask_b32_e32 v74, 0, v191, vcc
	v_fmac_f32_e32 v92, 0x3377d1cf, v70
	v_fmac_f32_e32 v76, 0x3f317217, v16
	v_cmp_lt_f32_e64 vcc, |v16|, s37
	v_fmac_f32_e32 v92, 0x3f317217, v70
	v_cndmask_b32_e64 v77, 0, v191, s[46:47]
	v_cndmask_b32_e32 v16, v16, v76, vcc
	v_cmp_lt_f32_e64 vcc, |v70|, s37
	s_nop 1
	v_cndmask_b32_e32 v76, v70, v92, vcc
	v_sub_f32_e32 v70, v16, v71
	v_mul_f32_e32 v16, 0x3f317217, v73
	v_mul_f32_e32 v71, 0x3f317217, v75
	v_fma_f32 v16, v73, s36, -v16
	v_fma_f32 v71, v75, s36, -v71
	v_fmac_f32_e32 v16, 0x3377d1cf, v73
; __device__ __forceinline__ unsigned cvt_pk_bf16(float lo, float hi) { unsigned r; asm("v_cvt_pk_bf16_f32 %0, %1, %2" : "=v"(r) : "v"(lo), "v"(hi)); return r; }
;     __device__ __forceinline__ void operator()(const f32x4 (&acc)[2][2][4][2], const Unit& u, int wr, int wc, int fr, int fq) const {
;     ...
;                 } else if (type == 4) {
;                     float* rp = (float*)base + (size_t)row * ld + col0 + cl; bf16_t* kp = (bf16_t*)(proj + (size_t)MP * 10240) + (size_t)row * ld + col0 + cl;
; #pragma unroll
;                     for (int bj = 0; bj < 2; ++bj) { f32x4 lfv[2], kkv[2];
; #pragma unroll
;                         for (int n = 0; n < 2; ++n) { const f32x4 lbq = *(const f32x4*)(lbp + col0 + cl + bj * 128 + 4 * n);
; #pragma unroll
;                             for (int e = 0; e < 4; ++e) { const float z = fminf(fmaxf(acc[ai][bj][m][n][e], -30.f), 30.f); const float sg = __builtin_amdgcn_rcpf(1.f + __expf(-z)); const float oml = 1.f - lbq[e];
;                                 lfv[n][e] = __logf(lbq[e] + oml * sg); kkv[n][e] = oml * (1.f - sg); }
;                             *(f32x4*)(rp + bj * 128 + 4 * n) = lfv[n]; }
;                         u32x4 w; w.x = cvt_pk_bf16(kkv[0][0], kkv[0][1]); w.y = cvt_pk_bf16(kkv[0][2], kkv[0][3]); w.z = cvt_pk_bf16(kkv[1][0], kkv[1][1]); w.w = cvt_pk_bf16(kkv[1][2], kkv[1][3]);
;                         *(u32x4*)(kp + bj * 128) = w; }
	v_fmac_f32_e32 v71, 0x3377d1cf, v75
	v_fmac_f32_e32 v16, 0x3f317217, v73
	v_cmp_lt_f32_e64 vcc, |v73|, s37
	v_fmac_f32_e32 v71, 0x3f317217, v75
	v_sub_f32_e32 v72, v76, v72
	v_cndmask_b32_e32 v16, v73, v16, vcc
	v_cmp_lt_f32_e64 vcc, |v75|, s37
	s_nop 1
	v_cndmask_b32_e32 v73, v75, v71, vcc
	v_sub_f32_e32 v71, v16, v74
	v_sub_f32_e32 v73, v73, v77
	global_store_dwordx4 v[78:79], v[70:73], off offset:512
	s_nop 0
	v_max_f32_e32 v16, v66, v66
	v_max_f32_e32 v66, v67, v67
	v_max_f32_e32 v67, v68, v68
	v_max_f32_e32 v68, v69, v69
	v_med3_f32 v16, v16, s38, v194
	v_med3_f32 v67, v67, s38, v194
	v_med3_f32 v66, v66, s38, v194
	v_med3_f32 v68, v68, s38, v194
	v_mul_f32_e32 v16, 0xbfb8aa3b, v16
	v_mul_f32_e32 v67, 0xbfb8aa3b, v67
	v_mul_f32_e32 v66, 0xbfb8aa3b, v66
	v_mul_f32_e32 v68, 0xbfb8aa3b, v68
	v_exp_f32_e32 v16, v16
	v_exp_f32_e32 v67, v67
	v_exp_f32_e32 v66, v66
	v_exp_f32_e32 v68, v68
	v_add_f32_e32 v16, 1.0, v16
	v_add_f32_e32 v67, 1.0, v67
	v_add_f32_e32 v92, 1.0, v66
	v_add_f32_e32 v93, 1.0, v68
	v_rcp_f32_e32 v66, v16
	v_rcp_f32_e32 v68, v67
	v_mul_f32_e32 v67, v84, v85
	v_mul_f32_e32 v69, v88, v89
	v_mul_f32_e32 v16, v80, v81
	v_mul_f32_e32 v74, v90, v91
	v_cvt_pk_bf16_f32 v82, v16, v69
	v_cvt_pk_bf16_f32 v83, v67, v74
	v_mov_b64_e32 v[70:71], v[216:217]
	v_mov_b64_e32 v[72:73], v[218:219]
	v_mov_b32_e32 v67, v70
	v_mov_b32_e32 v69, v72
	v_pk_add_f32 v[74:75], v[66:67], 1.0 op_sel_hi:[1,0] neg_lo:[1,0] neg_hi:[1,0]
	v_pk_add_f32 v[76:77], v[68:69], 1.0 op_sel_hi:[1,0] neg_lo:[1,0] neg_hi:[1,0]
	v_fma_f32 v16, v66, v75, v70
	v_rcp_f32_e32 v70, v92
	v_fma_f32 v66, v68, v77, v72
	v_rcp_f32_e32 v72, v93
	v_cmp_gt_f32_e32 vcc, s31, v16
	v_cmp_gt_f32_e64 s[46:47], s31, v66
	v_mul_f32_e32 v74, v74, v75
	v_cndmask_b32_e64 v67, 0, 32, vcc
	v_cndmask_b32_e64 v68, 0, 32, s[46:47]
	v_ldexp_f32 v16, v16, v67
	v_ldexp_f32 v66, v66, v68
	v_log_f32_e32 v16, v16
	v_log_f32_e32 v80, v66
	v_pk_add_f32 v[66:67], v[70:71], 1.0 op_sel_hi:[1,0] neg_lo:[1,0] neg_hi:[1,0]
	v_pk_add_f32 v[68:69], v[72:73], 1.0 op_sel_hi:[1,0] neg_lo:[1,0] neg_hi:[1,0]
	v_fma_f32 v70, v70, v67, v71
	v_mul_f32_e32 v75, v76, v77
	v_cndmask_b32_e32 v76, 0, v191, vcc
	v_fmac_f32_e32 v73, v72, v69
	v_cmp_gt_f32_e32 vcc, s31, v70
	v_cndmask_b32_e64 v77, 0, v191, s[46:47]
	v_mul_f32_e32 v66, v66, v67
	v_cndmask_b32_e64 v67, 0, 32, vcc
	v_cmp_gt_f32_e64 s[46:47], s31, v73
	v_mul_f32_e32 v71, v68, v69
	v_cvt_pk_bf16_f32 v84, v74, v66
	v_mul_f32_e32 v66, 0x3f317217, v16
	v_cndmask_b32_e64 v68, 0, 32, s[46:47]
	v_ldexp_f32 v67, v70, v67
	v_ldexp_f32 v68, v73, v68
	v_fma_f32 v66, v16, s36, -v66
	v_log_f32_e32 v67, v67
	v_mul_f32_e32 v70, 0x3f317217, v80
	v_log_f32_e32 v73, v68
	v_fmac_f32_e32 v66, 0x3377d1cf, v16
	v_cndmask_b32_e32 v69, 0, v191, vcc
	v_fma_f32 v70, v80, s36, -v70
	v_fmac_f32_e32 v66, 0x3f317217, v16
	v_cmp_lt_f32_e64 vcc, |v16|, s37
	v_fmac_f32_e32 v70, 0x3377d1cf, v80
	v_fmac_f32_e32 v70, 0x3f317217, v80
	v_cndmask_b32_e32 v16, v16, v66, vcc
	v_cmp_lt_f32_e64 vcc, |v80|, s37
	v_sub_f32_e32 v66, v16, v76
	v_mul_f32_e32 v16, 0x3f317217, v67
	v_cndmask_b32_e32 v68, v80, v70, vcc
	v_mul_f32_e32 v70, 0x3f317217, v73
	v_fma_f32 v16, v67, s36, -v16
	v_fma_f32 v70, v73, s36, -v70
	v_fmac_f32_e32 v16, 0x3377d1cf, v67
	v_fmac_f32_e32 v70, 0x3377d1cf, v73
	v_fmac_f32_e32 v16, 0x3f317217, v67
	v_cmp_lt_f32_e64 vcc, |v67|, s37
	v_fmac_f32_e32 v70, 0x3f317217, v73
	v_cndmask_b32_e64 v72, 0, v191, s[46:47]
	v_cndmask_b32_e32 v16, v67, v16, vcc
	v_cmp_lt_f32_e64 vcc, |v73|, s37
	v_sub_f32_e32 v68, v68, v77
	v_sub_f32_e32 v67, v16, v69
	v_cndmask_b32_e32 v70, v73, v70, vcc
	v_sub_f32_e32 v69, v70, v72
	global_store_dwordx4 v[78:79], v[66:69], off offset:528
	v_cvt_pk_bf16_f32 v85, v75, v71

; __device__ __forceinline__ unsigned cvt_pk_bf16(float lo, float hi) { unsigned r; asm("v_cvt_pk_bf16_f32 %0, %1, %2" : "=v"(r) : "v"(lo), "v"(hi)); return r; }
;     __device__ __forceinline__ void operator()(const f32x4 (&acc)[2][2][4][2], const Unit& u, int wr, int wc, int fr, int fq) const {
;     ...
;                 } else if (type == 4) {
;                     float* rp = (float*)base + (size_t)row * ld + col0 + cl; bf16_t* kp = (bf16_t*)(proj + (size_t)MP * 10240) + (size_t)row * ld + col0 + cl;
; #pragma unroll
;                     for (int bj = 0; bj < 2; ++bj) { f32x4 lfv[2], kkv[2];
; #pragma unroll
;                         for (int n = 0; n < 2; ++n) { const f32x4 lbq = *(const f32x4*)(lbp + col0 + cl + bj * 128 + 4 * n);
; #pragma unroll
;                             for (int e = 0; e < 4; ++e) { const float z = fminf(fmaxf(acc[ai][bj][m][n][e], -30.f), 30.f); const float sg = __builtin_amdgcn_rcpf(1.f + __expf(-z)); const float oml = 1.f - lbq[e];
;                                 lfv[n][e] = __logf(lbq[e] + oml * sg); kkv[n][e] = oml * (1.f - sg); }
;                             *(f32x4*)(rp + bj * 128 + 4 * n) = lfv[n]; }
;                         u32x4 w; w.x = cvt_pk_bf16(kkv[0][0], kkv[0][1]); w.y = cvt_pk_bf16(kkv[0][2], kkv[0][3]); w.z = cvt_pk_bf16(kkv[1][0], kkv[1][1]); w.w = cvt_pk_bf16(kkv[1][2], kkv[1][3]);
;                         *(u32x4*)(kp + bj * 128) = w; }
.LBB0_736:
	s_and_b64 vcc, exec, s[18:19]
	s_cbranch_vccz .LBB0_738
	s_lshl_b32 s18, s59, 2
	s_mov_b32 s19, s12
	v_lshl_add_u64 v[66:67], v[144:145], 0, s[18:19]
	s_nop 0
	v_lshlrev_b64 v[74:75], 12, v[72:73]
	v_max_f32_e32 v16, v62, v62
	v_max_f32_e32 v76, v63, v63
	v_max_f32_e32 v64, v64, v64
	v_lshl_add_u64 v[62:63], v[174:175], 0, v[74:75]
	v_med3_f32 v16, v16, s38, v194
	v_med3_f32 v74, v76, s38, v194
	v_med3_f32 v64, v64, s38, v194
	v_mul_f32_e32 v16, 0xbfb8aa3b, v16
	v_mul_f32_e32 v74, 0xbfb8aa3b, v74
	v_mul_f32_e32 v64, 0xbfb8aa3b, v64
	v_exp_f32_e32 v16, v16
	v_exp_f32_e32 v74, v74
	v_exp_f32_e32 v64, v64
	v_max_f32_e32 v65, v65, v65
	v_med3_f32 v65, v65, s38, v194
	v_mul_f32_e32 v65, 0xbfb8aa3b, v65
	v_exp_f32_e32 v65, v65
	v_add_f32_e32 v16, 1.0, v16
	v_add_f32_e32 v76, 1.0, v74
	v_add_f32_e32 v74, 1.0, v64
	v_rcp_f32_e32 v64, v16
	v_rcp_f32_e32 v74, v74
	v_add_f32_e32 v77, 1.0, v65
	v_max_f32_e32 v60, v60, v60
	s_mov_b32 s5, s12
	v_max_f32_e32 v61, v61, v61
	v_med3_f32 v60, v60, s38, v194
	v_mov_b32_e32 v169, v17
	v_med3_f32 v61, v61, s38, v194
	v_mul_f32_e32 v60, 0xbfb8aa3b, v60
	v_mul_f32_e32 v61, 0xbfb8aa3b, v61
	v_mov_b64_e32 v[68:69], v[204:205]
	v_mov_b64_e32 v[70:71], v[206:207]
	v_mov_b32_e32 v65, v68
	v_mov_b32_e32 v75, v70
	v_pk_add_f32 v[78:79], v[64:65], 1.0 op_sel_hi:[1,0] neg_lo:[1,0] neg_hi:[1,0]
	v_pk_add_f32 v[80:81], v[74:75], 1.0 op_sel_hi:[1,0] neg_lo:[1,0] neg_hi:[1,0]
	v_fma_f32 v16, v64, v79, v68
	v_rcp_f32_e32 v68, v76
	v_fma_f32 v64, v74, v81, v70
	v_rcp_f32_e32 v70, v77
	v_cmp_gt_f32_e32 vcc, s31, v16
	v_cmp_gt_f32_e64 s[46:47], s31, v64
	v_pk_add_f32 v[82:83], v[70:71], 1.0 op_sel_hi:[1,0] neg_lo:[1,0] neg_hi:[1,0]
	v_cndmask_b32_e64 v65, 0, 32, vcc
	v_cndmask_b32_e64 v74, 0, 32, s[46:47]
	v_ldexp_f32 v16, v16, v65
	v_ldexp_f32 v64, v64, v74
	v_log_f32_e32 v16, v16
	v_log_f32_e32 v76, v64
	v_pk_add_f32 v[64:65], v[68:69], 1.0 op_sel_hi:[1,0] neg_lo:[1,0] neg_hi:[1,0]
	v_cndmask_b32_e32 v75, 0, v191, vcc
	v_fma_f32 v68, v68, v65, v69
	v_fmac_f32_e32 v71, v70, v83
	v_cmp_gt_f32_e32 vcc, s31, v68
	v_cndmask_b32_e64 v74, 0, v191, s[46:47]
	v_cmp_gt_f32_e64 s[46:47], s31, v71
	v_cndmask_b32_e64 v69, 0, 32, vcc
	v_mul_f32_e32 v77, 0x3f317217, v16
	v_cndmask_b32_e64 v70, 0, 32, s[46:47]
	v_ldexp_f32 v68, v68, v69
	v_mul_f32_e32 v84, 0x3f317217, v76
	v_ldexp_f32 v70, v71, v70
	v_fma_f32 v77, v16, s36, -v77
	v_log_f32_e32 v85, v68
	v_fma_f32 v68, v76, s36, -v84
	v_log_f32_e32 v84, v70
	v_fmac_f32_e32 v77, 0x3377d1cf, v16
	v_cndmask_b32_e32 v69, 0, v191, vcc
	v_fmac_f32_e32 v68, 0x3377d1cf, v76
	v_fmac_f32_e32 v77, 0x3f317217, v16
	v_cmp_lt_f32_e64 vcc, |v16|, s37
	v_fmac_f32_e32 v68, 0x3f317217, v76
	v_cndmask_b32_e64 v71, 0, v191, s[46:47]
	v_cndmask_b32_e32 v16, v16, v77, vcc
	v_cmp_lt_f32_e64 vcc, |v76|, s37
	s_nop 1
	v_cndmask_b32_e32 v70, v76, v68, vcc
	v_sub_f32_e32 v68, v16, v75
	v_mul_f32_e32 v16, 0x3f317217, v85
	v_sub_f32_e32 v70, v70, v74
	v_mul_f32_e32 v74, 0x3f317217, v84
	v_fma_f32 v16, v85, s36, -v16
	v_fma_f32 v74, v84, s36, -v74
	v_fmac_f32_e32 v16, 0x3377d1cf, v85
	v_fmac_f32_e32 v74, 0x3377d1cf, v84
	v_fmac_f32_e32 v16, 0x3f317217, v85
	v_cmp_lt_f32_e64 vcc, |v85|, s37
	v_fmac_f32_e32 v74, 0x3f317217, v84
	s_nop 0
	v_cndmask_b32_e32 v16, v85, v16, vcc
	v_cmp_lt_f32_e64 vcc, |v84|, s37
	v_sub_f32_e32 v69, v16, v69
	v_max_f32_e32 v16, v58, v58
	v_cndmask_b32_e32 v74, v84, v74, vcc
	v_sub_f32_e32 v71, v74, v71
	global_store_dwordx4 v[62:63], v[68:71], off
	s_nop 0
	v_med3_f32 v16, v16, s38, v194
	v_lshlrev_b64 v[68:69], 11, v[72:73]
	v_max_f32_e32 v70, v59, v59
	v_lshl_add_u64 v[58:59], s[56:57], 0, v[68:69]
	v_med3_f32 v68, v70, s38, v194
	v_lshl_add_u64 v[58:59], v[58:59], 0, s[4:5]
	v_mul_f32_e32 v16, 0xbfb8aa3b, v16
	v_mul_f32_e32 v68, 0xbfb8aa3b, v68
	v_lshl_add_u64 v[70:71], v[58:59], 0, v[168:169]
	v_exp_f32_e32 v16, v16
	v_exp_f32_e32 v58, v68
	v_exp_f32_e32 v59, v60
	v_exp_f32_e32 v60, v61
	v_add_f32_e32 v16, 1.0, v16
	v_add_f32_e32 v84, 1.0, v58
	v_add_f32_e32 v58, 1.0, v59
	v_add_f32_e32 v85, 1.0, v60
	v_rcp_f32_e32 v60, v16
	v_rcp_f32_e32 v68, v58
	v_mul_f32_e32 v59, v80, v81
	v_mul_f32_e32 v61, v82, v83
	v_cvt_pk_bf16_f32 v59, v59, v61
	v_mul_f32_e32 v16, v78, v79
	v_mul_f32_e32 v58, v64, v65
	v_cvt_pk_bf16_f32 v58, v16, v58
	v_mov_b64_e32 v[74:75], v[208:209]
	v_mov_b64_e32 v[76:77], v[210:211]
	v_mov_b32_e32 v61, v74
	v_mov_b32_e32 v69, v76
	v_pk_add_f32 v[64:65], v[60:61], 1.0 op_sel_hi:[1,0] neg_lo:[1,0] neg_hi:[1,0]
	v_pk_add_f32 v[72:73], v[68:69], 1.0 op_sel_hi:[1,0] neg_lo:[1,0] neg_hi:[1,0]
	v_fma_f32 v16, v60, v65, v74
	v_rcp_f32_e32 v74, v84
	v_fma_f32 v60, v68, v73, v76
	v_rcp_f32_e32 v76, v85
	v_cmp_gt_f32_e32 vcc, s31, v16
	v_cmp_gt_f32_e64 s[46:47], s31, v60
	v_mul_f32_e32 v69, v64, v65
	v_cndmask_b32_e64 v61, 0, 32, vcc
	v_cndmask_b32_e64 v64, 0, 32, s[46:47]
	v_ldexp_f32 v16, v16, v61
	v_ldexp_f32 v60, v60, v64
	v_log_f32_e32 v16, v16
	v_log_f32_e32 v78, v60
	v_pk_add_f32 v[60:61], v[74:75], 1.0 op_sel_hi:[1,0] neg_lo:[1,0] neg_hi:[1,0]
	v_pk_add_f32 v[64:65], v[76:77], 1.0 op_sel_hi:[1,0] neg_lo:[1,0] neg_hi:[1,0]
	v_fma_f32 v74, v74, v61, v75
	v_mul_f32_e32 v68, v72, v73
	v_cndmask_b32_e32 v72, 0, v191, vcc
	v_fmac_f32_e32 v77, v76, v65
	v_cmp_gt_f32_e32 vcc, s31, v74
	v_cndmask_b32_e64 v73, 0, v191, s[46:47]
	v_mul_f32_e32 v60, v60, v61
	v_mul_f32_e32 v61, v64, v65
	v_cndmask_b32_e64 v64, 0, 32, vcc
	v_cmp_gt_f32_e64 s[46:47], s31, v77
	v_cvt_pk_bf16_f32 v61, v68, v61
	v_mul_f32_e32 v68, 0x3f317217, v16
	v_ldexp_f32 v64, v74, v64
	v_cndmask_b32_e64 v65, 0, 32, s[46:47]
	v_mul_f32_e32 v74, 0x3f317217, v78
	v_ldexp_f32 v65, v77, v65
	v_fma_f32 v68, v16, s36, -v68
; __device__ __forceinline__ unsigned cvt_pk_bf16(float lo, float hi) { unsigned r; asm("v_cvt_pk_bf16_f32 %0, %1, %2" : "=v"(r) : "v"(lo), "v"(hi)); return r; }
;     __device__ __forceinline__ void operator()(const f32x4 (&acc)[2][2][4][2], const Unit& u, int wr, int wc, int fr, int fq) const {
;     ...
;                 } else if (type == 4) {
;                     float* rp = (float*)base + (size_t)row * ld + col0 + cl; bf16_t* kp = (bf16_t*)(proj + (size_t)MP * 10240) + (size_t)row * ld + col0 + cl;
; #pragma unroll
;                     for (int bj = 0; bj < 2; ++bj) { f32x4 lfv[2], kkv[2];
; #pragma unroll
;                         for (int n = 0; n < 2; ++n) { const f32x4 lbq = *(const f32x4*)(lbp + col0 + cl + bj * 128 + 4 * n);
; #pragma unroll
;                             for (int e = 0; e < 4; ++e) { const float z = fminf(fmaxf(acc[ai][bj][m][n][e], -30.f), 30.f); const float sg = __builtin_amdgcn_rcpf(1.f + __expf(-z)); const float oml = 1.f - lbq[e];
;                                 lfv[n][e] = __logf(lbq[e] + oml * sg); kkv[n][e] = oml * (1.f - sg); }
;                             *(f32x4*)(rp + bj * 128 + 4 * n) = lfv[n]; }
;                         u32x4 w; w.x = cvt_pk_bf16(kkv[0][0], kkv[0][1]); w.y = cvt_pk_bf16(kkv[0][2], kkv[0][3]); w.z = cvt_pk_bf16(kkv[1][0], kkv[1][1]); w.w = cvt_pk_bf16(kkv[1][2], kkv[1][3]);
;                         *(u32x4*)(kp + bj * 128) = w; }
	v_log_f32_e32 v64, v64
	v_fma_f32 v74, v78, s36, -v74
	v_log_f32_e32 v65, v65
	v_fmac_f32_e32 v68, 0x3377d1cf, v16
	v_cvt_pk_bf16_f32 v60, v69, v60
	v_cndmask_b32_e32 v69, 0, v191, vcc
	v_fmac_f32_e32 v74, 0x3377d1cf, v78
	v_fmac_f32_e32 v68, 0x3f317217, v16
	v_cmp_lt_f32_e64 vcc, |v16|, s37
	v_fmac_f32_e32 v74, 0x3f317217, v78
	v_cndmask_b32_e64 v75, 0, v191, s[46:47]
	v_cndmask_b32_e32 v16, v16, v68, vcc
	v_cmp_lt_f32_e64 vcc, |v78|, s37
	v_sub_f32_e32 v72, v16, v72
	v_mul_f32_e32 v16, 0x3f317217, v64
	v_cndmask_b32_e32 v68, v78, v74, vcc
	v_sub_f32_e32 v74, v68, v73
	v_mul_f32_e32 v68, 0x3f317217, v65
	v_fma_f32 v16, v64, s36, -v16
	v_fma_f32 v68, v65, s36, -v68
	v_fmac_f32_e32 v16, 0x3377d1cf, v64
	v_fmac_f32_e32 v68, 0x3377d1cf, v65
	v_fmac_f32_e32 v16, 0x3f317217, v64
	v_cmp_lt_f32_e64 vcc, |v64|, s37
	v_fmac_f32_e32 v68, 0x3f317217, v65
	s_nop 0
	v_cndmask_b32_e32 v16, v64, v16, vcc
	v_cmp_lt_f32_e64 vcc, |v65|, s37
	v_sub_f32_e32 v73, v16, v69
	v_max_f32_e32 v16, v54, v54
	v_cndmask_b32_e32 v64, v65, v68, vcc
	v_sub_f32_e32 v75, v64, v75
	global_store_dwordx4 v[62:63], v[72:75], off offset:16
	global_store_dwordx4 v[70:71], v[58:61], off
	s_nop 0
	v_max_f32_e32 v54, v55, v55
	v_max_f32_e32 v55, v56, v56
	v_med3_f32 v16, v16, s38, v194
	v_max_f32_e32 v56, v57, v57
	v_med3_f32 v54, v54, s38, v194
	v_med3_f32 v55, v55, s38, v194
	v_mul_f32_e32 v16, 0xbfb8aa3b, v16
	v_med3_f32 v56, v56, s38, v194
	v_mul_f32_e32 v54, 0xbfb8aa3b, v54
	v_mul_f32_e32 v55, 0xbfb8aa3b, v55
	v_exp_f32_e32 v16, v16
	v_mul_f32_e32 v56, 0xbfb8aa3b, v56
	v_exp_f32_e32 v54, v54
	v_exp_f32_e32 v55, v55
	v_exp_f32_e32 v56, v56
	v_add_f32_e32 v16, 1.0, v16
	v_add_f32_e32 v72, 1.0, v54
	v_add_f32_e32 v55, 1.0, v55
	v_rcp_f32_e32 v54, v16
	v_add_f32_e32 v73, 1.0, v56
	v_rcp_f32_e32 v56, v55
	v_mov_b64_e32 v[58:59], v[212:213]
	v_mov_b64_e32 v[60:61], v[214:215]
	v_mov_b32_e32 v55, v58
	v_mov_b32_e32 v57, v60
	v_pk_add_f32 v[64:65], v[54:55], 1.0 op_sel_hi:[1,0] neg_lo:[1,0] neg_hi:[1,0]
	v_pk_add_f32 v[68:69], v[56:57], 1.0 op_sel_hi:[1,0] neg_lo:[1,0] neg_hi:[1,0]
	v_fma_f32 v16, v54, v65, v58
	v_rcp_f32_e32 v58, v72
	v_fma_f32 v54, v56, v69, v60
	v_rcp_f32_e32 v60, v73
	v_cmp_gt_f32_e32 vcc, s31, v16
	v_cmp_gt_f32_e64 s[46:47], s31, v54
	v_pk_add_f32 v[72:73], v[58:59], 1.0 op_sel_hi:[1,0] neg_lo:[1,0] neg_hi:[1,0]
	v_cndmask_b32_e64 v55, 0, 32, vcc
	v_cndmask_b32_e64 v56, 0, 32, s[46:47]
	v_ldexp_f32 v16, v16, v55
	v_ldexp_f32 v54, v54, v56
	v_log_f32_e32 v16, v16
	v_log_f32_e32 v54, v54
	v_pk_add_f32 v[74:75], v[60:61], 1.0 op_sel_hi:[1,0] neg_lo:[1,0] neg_hi:[1,0]
	v_fma_f32 v57, v58, v73, v59
	v_cndmask_b32_e32 v55, 0, v191, vcc
	v_fmac_f32_e32 v61, v60, v75
	v_cmp_gt_f32_e32 vcc, s31, v57
	v_cndmask_b32_e64 v56, 0, v191, s[46:47]
	v_cmp_gt_f32_e64 s[46:47], s31, v61
	v_cndmask_b32_e64 v58, 0, 32, vcc
	v_mul_f32_e32 v60, 0x3f317217, v16
	v_cndmask_b32_e64 v59, 0, 32, s[46:47]
	v_ldexp_f32 v57, v57, v58
	v_mul_f32_e32 v76, 0x3f317217, v54
	v_ldexp_f32 v59, v61, v59
	v_fma_f32 v60, v16, s36, -v60
	v_log_f32_e32 v57, v57
	v_fma_f32 v76, v54, s36, -v76
	v_log_f32_e32 v59, v59
	v_fmac_f32_e32 v60, 0x3377d1cf, v16
	v_cndmask_b32_e32 v58, 0, v191, vcc
	v_fmac_f32_e32 v76, 0x3377d1cf, v54
	v_fmac_f32_e32 v60, 0x3f317217, v16
	v_cmp_lt_f32_e64 vcc, |v16|, s37
	v_fmac_f32_e32 v76, 0x3f317217, v54
	v_cndmask_b32_e64 v61, 0, v191, s[46:47]
	v_cndmask_b32_e32 v16, v16, v60, vcc
	v_cmp_lt_f32_e64 vcc, |v54|, s37
	s_nop 1
	v_cndmask_b32_e32 v60, v54, v76, vcc
	v_sub_f32_e32 v54, v16, v55
	v_mul_f32_e32 v16, 0x3f317217, v57
	v_mul_f32_e32 v55, 0x3f317217, v59
	v_fma_f32 v16, v57, s36, -v16
	v_fma_f32 v55, v59, s36, -v55
	v_fmac_f32_e32 v16, 0x3377d1cf, v57
; __device__ __forceinline__ unsigned cvt_pk_bf16(float lo, float hi) { unsigned r; asm("v_cvt_pk_bf16_f32 %0, %1, %2" : "=v"(r) : "v"(lo), "v"(hi)); return r; }
;     __device__ __forceinline__ void operator()(const f32x4 (&acc)[2][2][4][2], const Unit& u, int wr, int wc, int fr, int fq) const {
;     ...
;                 } else if (type == 4) {
;                     float* rp = (float*)base + (size_t)row * ld + col0 + cl; bf16_t* kp = (bf16_t*)(proj + (size_t)MP * 10240) + (size_t)row * ld + col0 + cl;
; #pragma unroll
;                     for (int bj = 0; bj < 2; ++bj) { f32x4 lfv[2], kkv[2];
; #pragma unroll
;                         for (int n = 0; n < 2; ++n) { const f32x4 lbq = *(const f32x4*)(lbp + col0 + cl + bj * 128 + 4 * n);
; #pragma unroll
;                             for (int e = 0; e < 4; ++e) { const float z = fminf(fmaxf(acc[ai][bj][m][n][e], -30.f), 30.f); const float sg = __builtin_amdgcn_rcpf(1.f + __expf(-z)); const float oml = 1.f - lbq[e];
;                                 lfv[n][e] = __logf(lbq[e] + oml * sg); kkv[n][e] = oml * (1.f - sg); }
;                             *(f32x4*)(rp + bj * 128 + 4 * n) = lfv[n]; }
;                         u32x4 w; w.x = cvt_pk_bf16(kkv[0][0], kkv[0][1]); w.y = cvt_pk_bf16(kkv[0][2], kkv[0][3]); w.z = cvt_pk_bf16(kkv[1][0], kkv[1][1]); w.w = cvt_pk_bf16(kkv[1][2], kkv[1][3]);
;                         *(u32x4*)(kp + bj * 128) = w; }
	v_fmac_f32_e32 v55, 0x3377d1cf, v59
	v_fmac_f32_e32 v16, 0x3f317217, v57
	v_cmp_lt_f32_e64 vcc, |v57|, s37
	v_fmac_f32_e32 v55, 0x3f317217, v59
	v_sub_f32_e32 v56, v60, v56
	v_cndmask_b32_e32 v16, v57, v16, vcc
	v_cmp_lt_f32_e64 vcc, |v59|, s37
	s_nop 1
	v_cndmask_b32_e32 v57, v59, v55, vcc
	v_sub_f32_e32 v55, v16, v58
	v_sub_f32_e32 v57, v57, v61
	global_store_dwordx4 v[62:63], v[54:57], off offset:512
	s_nop 0
	v_max_f32_e32 v16, v50, v50
	v_max_f32_e32 v50, v51, v51
	v_max_f32_e32 v51, v52, v52
	v_max_f32_e32 v52, v53, v53
	v_med3_f32 v16, v16, s38, v194
	v_med3_f32 v51, v51, s38, v194
	v_med3_f32 v50, v50, s38, v194
	v_med3_f32 v52, v52, s38, v194
	v_mul_f32_e32 v16, 0xbfb8aa3b, v16
	v_mul_f32_e32 v51, 0xbfb8aa3b, v51
	v_mul_f32_e32 v50, 0xbfb8aa3b, v50
	v_mul_f32_e32 v52, 0xbfb8aa3b, v52
	v_exp_f32_e32 v16, v16
	v_exp_f32_e32 v51, v51
	v_exp_f32_e32 v50, v50
	v_exp_f32_e32 v52, v52
	v_add_f32_e32 v16, 1.0, v16
	v_add_f32_e32 v51, 1.0, v51
	v_add_f32_e32 v76, 1.0, v50
	v_add_f32_e32 v77, 1.0, v52
	v_rcp_f32_e32 v50, v16
	v_rcp_f32_e32 v52, v51
	v_mul_f32_e32 v51, v68, v69
	v_mul_f32_e32 v53, v72, v73
	v_mul_f32_e32 v16, v64, v65
	v_mul_f32_e32 v58, v74, v75
	v_cvt_pk_bf16_f32 v66, v16, v53
	v_cvt_pk_bf16_f32 v67, v51, v58
	v_mov_b64_e32 v[54:55], v[216:217]
	v_mov_b64_e32 v[56:57], v[218:219]
	v_mov_b32_e32 v51, v54
	v_mov_b32_e32 v53, v56
	v_pk_add_f32 v[58:59], v[50:51], 1.0 op_sel_hi:[1,0] neg_lo:[1,0] neg_hi:[1,0]
	v_pk_add_f32 v[60:61], v[52:53], 1.0 op_sel_hi:[1,0] neg_lo:[1,0] neg_hi:[1,0]
	v_fma_f32 v16, v50, v59, v54
	v_rcp_f32_e32 v54, v76
	v_fma_f32 v50, v52, v61, v56
	v_rcp_f32_e32 v56, v77
	v_cmp_gt_f32_e32 vcc, s31, v16
	v_cmp_gt_f32_e64 s[46:47], s31, v50
	v_mul_f32_e32 v58, v58, v59
	v_cndmask_b32_e64 v51, 0, 32, vcc
	v_cndmask_b32_e64 v52, 0, 32, s[46:47]
	v_ldexp_f32 v16, v16, v51
	v_ldexp_f32 v50, v50, v52
	v_log_f32_e32 v16, v16
	v_log_f32_e32 v64, v50
	v_pk_add_f32 v[50:51], v[54:55], 1.0 op_sel_hi:[1,0] neg_lo:[1,0] neg_hi:[1,0]
	v_pk_add_f32 v[52:53], v[56:57], 1.0 op_sel_hi:[1,0] neg_lo:[1,0] neg_hi:[1,0]
	v_fma_f32 v54, v54, v51, v55
	v_mul_f32_e32 v59, v60, v61
	v_cndmask_b32_e32 v60, 0, v191, vcc
	v_fmac_f32_e32 v57, v56, v53
	v_cmp_gt_f32_e32 vcc, s31, v54
	v_cndmask_b32_e64 v61, 0, v191, s[46:47]
	v_mul_f32_e32 v50, v50, v51
	v_cndmask_b32_e64 v51, 0, 32, vcc
	v_cmp_gt_f32_e64 s[46:47], s31, v57
	v_mul_f32_e32 v55, v52, v53
	v_cvt_pk_bf16_f32 v68, v58, v50
	v_mul_f32_e32 v50, 0x3f317217, v16
	v_cndmask_b32_e64 v52, 0, 32, s[46:47]
	v_ldexp_f32 v51, v54, v51
	v_ldexp_f32 v52, v57, v52
	v_fma_f32 v50, v16, s36, -v50
	v_log_f32_e32 v51, v51
	v_mul_f32_e32 v54, 0x3f317217, v64
	v_log_f32_e32 v57, v52
	v_fmac_f32_e32 v50, 0x3377d1cf, v16
	v_cndmask_b32_e32 v53, 0, v191, vcc
	v_fma_f32 v54, v64, s36, -v54
	v_fmac_f32_e32 v50, 0x3f317217, v16
	v_cmp_lt_f32_e64 vcc, |v16|, s37
	v_fmac_f32_e32 v54, 0x3377d1cf, v64
	v_fmac_f32_e32 v54, 0x3f317217, v64
	v_cndmask_b32_e32 v16, v16, v50, vcc
	v_cmp_lt_f32_e64 vcc, |v64|, s37
	v_sub_f32_e32 v50, v16, v60
	v_mul_f32_e32 v16, 0x3f317217, v51
	v_cndmask_b32_e32 v52, v64, v54, vcc
	v_mul_f32_e32 v54, 0x3f317217, v57
	v_fma_f32 v16, v51, s36, -v16
	v_fma_f32 v54, v57, s36, -v54
	v_fmac_f32_e32 v16, 0x3377d1cf, v51
	v_fmac_f32_e32 v54, 0x3377d1cf, v57
	v_fmac_f32_e32 v16, 0x3f317217, v51
	v_cmp_lt_f32_e64 vcc, |v51|, s37
	v_fmac_f32_e32 v54, 0x3f317217, v57
	v_cndmask_b32_e64 v56, 0, v191, s[46:47]
	v_cndmask_b32_e32 v16, v51, v16, vcc
	v_cmp_lt_f32_e64 vcc, |v57|, s37
	v_sub_f32_e32 v52, v52, v61
	v_sub_f32_e32 v51, v16, v53
	v_cndmask_b32_e32 v54, v57, v54, vcc
	v_sub_f32_e32 v53, v54, v56
	global_store_dwordx4 v[62:63], v[50:53], off offset:528
	v_cvt_pk_bf16_f32 v69, v59, v55

; __device__ __forceinline__ unsigned cvt_pk_bf16(float lo, float hi) { unsigned r; asm("v_cvt_pk_bf16_f32 %0, %1, %2" : "=v"(r) : "v"(lo), "v"(hi)); return r; }
;     __device__ __forceinline__ void operator()(const f32x4 (&acc)[2][2][4][2], const Unit& u, int wr, int wc, int fr, int fq) const {
;     ...
;                 } else if (type == 4) {
;                     float* rp = (float*)base + (size_t)row * ld + col0 + cl; bf16_t* kp = (bf16_t*)(proj + (size_t)MP * 10240) + (size_t)row * ld + col0 + cl;
; #pragma unroll
;                     for (int bj = 0; bj < 2; ++bj) { f32x4 lfv[2], kkv[2];
; #pragma unroll
;                         for (int n = 0; n < 2; ++n) { const f32x4 lbq = *(const f32x4*)(lbp + col0 + cl + bj * 128 + 4 * n);
; #pragma unroll
;                             for (int e = 0; e < 4; ++e) { const float z = fminf(fmaxf(acc[ai][bj][m][n][e], -30.f), 30.f); const float sg = __builtin_amdgcn_rcpf(1.f + __expf(-z)); const float oml = 1.f - lbq[e];
;                                 lfv[n][e] = __logf(lbq[e] + oml * sg); kkv[n][e] = oml * (1.f - sg); }
;                             *(f32x4*)(rp + bj * 128 + 4 * n) = lfv[n]; }
;                         u32x4 w; w.x = cvt_pk_bf16(kkv[0][0], kkv[0][1]); w.y = cvt_pk_bf16(kkv[0][2], kkv[0][3]); w.z = cvt_pk_bf16(kkv[1][0], kkv[1][1]); w.w = cvt_pk_bf16(kkv[1][2], kkv[1][3]);
;                         *(u32x4*)(kp + bj * 128) = w; }
.LBB0_744:
	s_and_b64 vcc, exec, s[18:19]
	s_cbranch_vccz .LBB0_746
	s_lshl_b32 s18, s59, 2
	s_mov_b32 s19, s12
	v_lshl_add_u64 v[56:57], v[144:145], 0, s[18:19]
	s_nop 0
	v_max_f32_e32 v16, v46, v46
	v_max_f32_e32 v46, v47, v47
	v_max_f32_e32 v47, v48, v48
	v_med3_f32 v16, v16, s38, v194
	v_max_f32_e32 v48, v49, v49
	v_med3_f32 v46, v46, s38, v194
	v_med3_f32 v47, v47, s38, v194
	v_mul_f32_e32 v16, 0xbfb8aa3b, v16
	v_med3_f32 v48, v48, s38, v194
	v_mul_f32_e32 v46, 0xbfb8aa3b, v46
	v_mul_f32_e32 v47, 0xbfb8aa3b, v47
	v_exp_f32_e32 v16, v16
	v_mul_f32_e32 v48, 0xbfb8aa3b, v48
	v_exp_f32_e32 v46, v46
	v_exp_f32_e32 v47, v47
	v_exp_f32_e32 v48, v48
	v_add_f32_e32 v16, 1.0, v16
	v_add_f32_e32 v58, 1.0, v46
	v_add_f32_e32 v47, 1.0, v47
	v_rcp_f32_e32 v46, v16
	v_add_f32_e32 v59, 1.0, v48
	v_rcp_f32_e32 v48, v47
	v_lshlrev_b64 v[54:55], 12, v[60:61]
	v_lshl_add_u64 v[54:55], v[174:175], 0, v[54:55]
	v_max_f32_e32 v44, v44, v44
	s_mov_b32 s5, s12
	v_max_f32_e32 v45, v45, v45
	v_med3_f32 v44, v44, s38, v194
	v_mov_b32_e32 v169, v17
	v_med3_f32 v45, v45, s38, v194
	v_mul_f32_e32 v44, 0xbfb8aa3b, v44
	v_mul_f32_e32 v45, 0xbfb8aa3b, v45
	v_mov_b64_e32 v[50:51], v[204:205]
	v_mov_b64_e32 v[52:53], v[206:207]
	v_mov_b32_e32 v47, v50
	v_mov_b32_e32 v49, v52
	v_pk_add_f32 v[62:63], v[46:47], 1.0 op_sel_hi:[1,0] neg_lo:[1,0] neg_hi:[1,0]
	v_pk_add_f32 v[64:65], v[48:49], 1.0 op_sel_hi:[1,0] neg_lo:[1,0] neg_hi:[1,0]
	v_fma_f32 v16, v46, v63, v50
	v_rcp_f32_e32 v50, v58
	v_fma_f32 v46, v48, v65, v52
	v_rcp_f32_e32 v52, v59
	v_cmp_gt_f32_e32 vcc, s31, v16
	v_cmp_gt_f32_e64 s[46:47], s31, v46
	v_pk_add_f32 v[66:67], v[50:51], 1.0 op_sel_hi:[1,0] neg_lo:[1,0] neg_hi:[1,0]
	v_cndmask_b32_e64 v47, 0, 32, vcc
	v_cndmask_b32_e64 v48, 0, 32, s[46:47]
	v_ldexp_f32 v16, v16, v47
	v_ldexp_f32 v46, v46, v48
	v_log_f32_e32 v16, v16
	v_log_f32_e32 v46, v46
	v_pk_add_f32 v[68:69], v[52:53], 1.0 op_sel_hi:[1,0] neg_lo:[1,0] neg_hi:[1,0]
	v_fma_f32 v49, v50, v67, v51
	v_cndmask_b32_e32 v47, 0, v191, vcc
	v_fmac_f32_e32 v53, v52, v69
	v_cmp_gt_f32_e32 vcc, s31, v49
	v_cndmask_b32_e64 v48, 0, v191, s[46:47]
	v_cmp_gt_f32_e64 s[46:47], s31, v53
	v_cndmask_b32_e64 v50, 0, 32, vcc
	v_mul_f32_e32 v52, 0x3f317217, v16
	v_cndmask_b32_e64 v51, 0, 32, s[46:47]
	v_ldexp_f32 v49, v49, v50
	v_mul_f32_e32 v58, 0x3f317217, v46
	v_ldexp_f32 v51, v53, v51
	v_fma_f32 v52, v16, s36, -v52
	v_log_f32_e32 v49, v49
	v_fma_f32 v58, v46, s36, -v58
	v_log_f32_e32 v51, v51
	v_fmac_f32_e32 v52, 0x3377d1cf, v16
	v_cndmask_b32_e32 v50, 0, v191, vcc
	v_fmac_f32_e32 v58, 0x3377d1cf, v46
	v_fmac_f32_e32 v52, 0x3f317217, v16
	v_cmp_lt_f32_e64 vcc, |v16|, s37
	v_fmac_f32_e32 v58, 0x3f317217, v46
	v_cndmask_b32_e64 v53, 0, v191, s[46:47]
	v_cndmask_b32_e32 v16, v16, v52, vcc
	v_cmp_lt_f32_e64 vcc, |v46|, s37
	s_nop 1
	v_cndmask_b32_e32 v52, v46, v58, vcc
	v_sub_f32_e32 v46, v16, v47
	v_mul_f32_e32 v16, 0x3f317217, v49
	v_mul_f32_e32 v47, 0x3f317217, v51
	v_fma_f32 v16, v49, s36, -v16
	v_fma_f32 v47, v51, s36, -v47
	v_fmac_f32_e32 v16, 0x3377d1cf, v49
	v_fmac_f32_e32 v47, 0x3377d1cf, v51
	v_fmac_f32_e32 v16, 0x3f317217, v49
	v_cmp_lt_f32_e64 vcc, |v49|, s37
	v_fmac_f32_e32 v47, 0x3f317217, v51
	v_sub_f32_e32 v48, v52, v48
	v_cndmask_b32_e32 v16, v49, v16, vcc
	v_cmp_lt_f32_e64 vcc, |v51|, s37
	v_max_f32_e32 v52, v43, v43
	s_nop 0
	v_cndmask_b32_e32 v49, v51, v47, vcc
	v_sub_f32_e32 v47, v16, v50
	v_sub_f32_e32 v49, v49, v53
	global_store_dwordx4 v[54:55], v[46:49], off
	s_nop 0
	v_lshlrev_b64 v[50:51], 11, v[60:61]
	v_max_f32_e32 v16, v42, v42
	v_lshl_add_u64 v[42:43], s[56:57], 0, v[50:51]
	v_med3_f32 v16, v16, s38, v194
	v_med3_f32 v50, v52, s38, v194
	v_lshl_add_u64 v[42:43], v[42:43], 0, s[4:5]
	v_mul_f32_e32 v16, 0xbfb8aa3b, v16
	v_mul_f32_e32 v50, 0xbfb8aa3b, v50
	v_lshl_add_u64 v[58:59], v[42:43], 0, v[168:169]
	v_exp_f32_e32 v16, v16
	v_exp_f32_e32 v42, v50
	v_exp_f32_e32 v43, v44
	v_exp_f32_e32 v44, v45
	v_add_f32_e32 v16, 1.0, v16
	v_add_f32_e32 v70, 1.0, v42
	v_add_f32_e32 v42, 1.0, v43
	v_add_f32_e32 v71, 1.0, v44
	v_rcp_f32_e32 v44, v16
	v_rcp_f32_e32 v50, v42
	v_mul_f32_e32 v43, v64, v65
	v_mul_f32_e32 v45, v68, v69
	v_cvt_pk_bf16_f32 v43, v43, v45
	v_mul_f32_e32 v16, v62, v63
	v_mul_f32_e32 v42, v66, v67
	v_cvt_pk_bf16_f32 v42, v16, v42
	v_mov_b64_e32 v[46:47], v[208:209]
	v_mov_b64_e32 v[48:49], v[210:211]
	v_mov_b32_e32 v45, v46
	v_mov_b32_e32 v51, v48
	v_pk_add_f32 v[52:53], v[44:45], 1.0 op_sel_hi:[1,0] neg_lo:[1,0] neg_hi:[1,0]
	v_pk_add_f32 v[60:61], v[50:51], 1.0 op_sel_hi:[1,0] neg_lo:[1,0] neg_hi:[1,0]
	v_fma_f32 v16, v44, v53, v46
	v_rcp_f32_e32 v46, v70
	v_fma_f32 v44, v50, v61, v48
	v_rcp_f32_e32 v48, v71
	v_cmp_gt_f32_e32 vcc, s31, v16
	v_cmp_gt_f32_e64 s[46:47], s31, v44
	v_mul_f32_e32 v52, v52, v53
	v_cndmask_b32_e64 v45, 0, 32, vcc
	v_cndmask_b32_e64 v50, 0, 32, s[46:47]
	v_ldexp_f32 v16, v16, v45
	v_ldexp_f32 v44, v44, v50
	v_log_f32_e32 v16, v16
	v_log_f32_e32 v62, v44
	v_pk_add_f32 v[44:45], v[46:47], 1.0 op_sel_hi:[1,0] neg_lo:[1,0] neg_hi:[1,0]
	v_pk_add_f32 v[50:51], v[48:49], 1.0 op_sel_hi:[1,0] neg_lo:[1,0] neg_hi:[1,0]
	v_fma_f32 v46, v46, v45, v47
	v_mul_f32_e32 v53, v60, v61
	v_cndmask_b32_e32 v60, 0, v191, vcc
	v_fmac_f32_e32 v49, v48, v51
	v_cmp_gt_f32_e32 vcc, s31, v46
	v_cndmask_b32_e64 v61, 0, v191, s[46:47]
	v_cmp_gt_f32_e64 s[46:47], s31, v49
	v_cndmask_b32_e64 v47, 0, 32, vcc
	v_mul_f32_e32 v44, v44, v45
	v_mul_f32_e32 v45, v50, v51
	v_cndmask_b32_e64 v48, 0, 32, s[46:47]
	v_mul_f32_e32 v50, 0x3f317217, v16
	v_ldexp_f32 v46, v46, v47
	v_cvt_pk_bf16_f32 v44, v52, v44
	v_mul_f32_e32 v51, 0x3f317217, v62
	v_ldexp_f32 v48, v49, v48
	v_fma_f32 v50, v16, s36, -v50
; __device__ __forceinline__ unsigned cvt_pk_bf16(float lo, float hi) { unsigned r; asm("v_cvt_pk_bf16_f32 %0, %1, %2" : "=v"(r) : "v"(lo), "v"(hi)); return r; }
;     __device__ __forceinline__ void operator()(const f32x4 (&acc)[2][2][4][2], const Unit& u, int wr, int wc, int fr, int fq) const {
;     ...
;                 } else if (type == 4) {
;                     float* rp = (float*)base + (size_t)row * ld + col0 + cl; bf16_t* kp = (bf16_t*)(proj + (size_t)MP * 10240) + (size_t)row * ld + col0 + cl;
; #pragma unroll
;                     for (int bj = 0; bj < 2; ++bj) { f32x4 lfv[2], kkv[2];
; #pragma unroll
;                         for (int n = 0; n < 2; ++n) { const f32x4 lbq = *(const f32x4*)(lbp + col0 + cl + bj * 128 + 4 * n);
; #pragma unroll
;                             for (int e = 0; e < 4; ++e) { const float z = fminf(fmaxf(acc[ai][bj][m][n][e], -30.f), 30.f); const float sg = __builtin_amdgcn_rcpf(1.f + __expf(-z)); const float oml = 1.f - lbq[e];
;                                 lfv[n][e] = __logf(lbq[e] + oml * sg); kkv[n][e] = oml * (1.f - sg); }
;                             *(f32x4*)(rp + bj * 128 + 4 * n) = lfv[n]; }
;                         u32x4 w; w.x = cvt_pk_bf16(kkv[0][0], kkv[0][1]); w.y = cvt_pk_bf16(kkv[0][2], kkv[0][3]); w.z = cvt_pk_bf16(kkv[1][0], kkv[1][1]); w.w = cvt_pk_bf16(kkv[1][2], kkv[1][3]);
;                         *(u32x4*)(kp + bj * 128) = w; }
	v_log_f32_e32 v52, v46
	v_fma_f32 v46, v62, s36, -v51
	v_log_f32_e32 v51, v48
	v_fmac_f32_e32 v50, 0x3377d1cf, v16
	v_cndmask_b32_e32 v47, 0, v191, vcc
	v_fmac_f32_e32 v46, 0x3377d1cf, v62
	v_fmac_f32_e32 v50, 0x3f317217, v16
	v_cmp_lt_f32_e64 vcc, |v16|, s37
	v_fmac_f32_e32 v46, 0x3f317217, v62
	v_cndmask_b32_e64 v49, 0, v191, s[46:47]
	v_cndmask_b32_e32 v16, v16, v50, vcc
	v_cmp_lt_f32_e64 vcc, |v62|, s37
	v_mul_f32_e32 v50, 0x3f317217, v51
	v_fma_f32 v50, v51, s36, -v50
	v_cndmask_b32_e32 v48, v62, v46, vcc
	v_sub_f32_e32 v46, v16, v60
	v_mul_f32_e32 v16, 0x3f317217, v52
	v_fma_f32 v16, v52, s36, -v16
	v_fmac_f32_e32 v16, 0x3377d1cf, v52
	v_fmac_f32_e32 v50, 0x3377d1cf, v51
	v_fmac_f32_e32 v16, 0x3f317217, v52
	v_cmp_lt_f32_e64 vcc, |v52|, s37
	v_fmac_f32_e32 v50, 0x3f317217, v51
	v_sub_f32_e32 v48, v48, v61
	v_cndmask_b32_e32 v16, v52, v16, vcc
	v_cmp_lt_f32_e64 vcc, |v51|, s37
	v_sub_f32_e32 v47, v16, v47
	v_cvt_pk_bf16_f32 v45, v53, v45
	v_max_f32_e32 v16, v38, v38
	v_cndmask_b32_e32 v50, v51, v50, vcc
	v_sub_f32_e32 v49, v50, v49
	global_store_dwordx4 v[54:55], v[46:49], off offset:16
	global_store_dwordx4 v[58:59], v[42:45], off
	s_nop 0
	v_max_f32_e32 v38, v39, v39
	v_max_f32_e32 v39, v40, v40
	v_med3_f32 v16, v16, s38, v194
	v_max_f32_e32 v40, v41, v41
	v_med3_f32 v38, v38, s38, v194
	v_med3_f32 v39, v39, s38, v194
	v_mul_f32_e32 v16, 0xbfb8aa3b, v16
	v_med3_f32 v40, v40, s38, v194
	v_mul_f32_e32 v38, 0xbfb8aa3b, v38
	v_mul_f32_e32 v39, 0xbfb8aa3b, v39
	v_exp_f32_e32 v16, v16
	v_mul_f32_e32 v40, 0xbfb8aa3b, v40
	v_exp_f32_e32 v38, v38
	v_exp_f32_e32 v39, v39
	v_exp_f32_e32 v40, v40
	v_add_f32_e32 v16, 1.0, v16
	v_add_f32_e32 v50, 1.0, v38
	v_add_f32_e32 v39, 1.0, v39
	v_rcp_f32_e32 v38, v16
	v_add_f32_e32 v51, 1.0, v40
	v_rcp_f32_e32 v40, v39
	v_mov_b64_e32 v[42:43], v[212:213]
	v_mov_b64_e32 v[44:45], v[214:215]
	v_mov_b32_e32 v39, v42
	v_mov_b32_e32 v41, v44
	v_pk_add_f32 v[46:47], v[38:39], 1.0 op_sel_hi:[1,0] neg_lo:[1,0] neg_hi:[1,0]
	v_pk_add_f32 v[48:49], v[40:41], 1.0 op_sel_hi:[1,0] neg_lo:[1,0] neg_hi:[1,0]
	v_fma_f32 v16, v38, v47, v42
	v_rcp_f32_e32 v42, v50
	v_fma_f32 v38, v40, v49, v44
	v_rcp_f32_e32 v44, v51
	v_cmp_gt_f32_e32 vcc, s31, v16
	v_cmp_gt_f32_e64 s[46:47], s31, v38
	v_pk_add_f32 v[50:51], v[42:43], 1.0 op_sel_hi:[1,0] neg_lo:[1,0] neg_hi:[1,0]
	v_cndmask_b32_e64 v39, 0, 32, vcc
	v_cndmask_b32_e64 v40, 0, 32, s[46:47]
	v_ldexp_f32 v16, v16, v39
	v_ldexp_f32 v38, v38, v40
	v_log_f32_e32 v16, v16
	v_log_f32_e32 v38, v38
	v_pk_add_f32 v[52:53], v[44:45], 1.0 op_sel_hi:[1,0] neg_lo:[1,0] neg_hi:[1,0]
	v_fma_f32 v41, v42, v51, v43
	v_cndmask_b32_e32 v39, 0, v191, vcc
	v_fmac_f32_e32 v45, v44, v53
	v_cmp_gt_f32_e32 vcc, s31, v41
	v_cndmask_b32_e64 v40, 0, v191, s[46:47]
	v_cmp_gt_f32_e64 s[46:47], s31, v45
	v_cndmask_b32_e64 v42, 0, 32, vcc
	v_mul_f32_e32 v44, 0x3f317217, v16
	v_cndmask_b32_e64 v43, 0, 32, s[46:47]
	v_ldexp_f32 v41, v41, v42
	v_mul_f32_e32 v60, 0x3f317217, v38
	v_ldexp_f32 v43, v45, v43
	v_fma_f32 v44, v16, s36, -v44
	v_log_f32_e32 v41, v41
	v_fma_f32 v60, v38, s36, -v60
	v_log_f32_e32 v43, v43
	v_fmac_f32_e32 v44, 0x3377d1cf, v16
	v_cndmask_b32_e32 v42, 0, v191, vcc
	v_fmac_f32_e32 v60, 0x3377d1cf, v38
	v_fmac_f32_e32 v44, 0x3f317217, v16
	v_cmp_lt_f32_e64 vcc, |v16|, s37
	v_fmac_f32_e32 v60, 0x3f317217, v38
	v_cndmask_b32_e64 v45, 0, v191, s[46:47]
	v_cndmask_b32_e32 v16, v16, v44, vcc
	v_cmp_lt_f32_e64 vcc, |v38|, s37
	s_nop 1
	v_cndmask_b32_e32 v44, v38, v60, vcc
	v_sub_f32_e32 v38, v16, v39
	v_mul_f32_e32 v16, 0x3f317217, v41
	v_mul_f32_e32 v39, 0x3f317217, v43
	v_fma_f32 v16, v41, s36, -v16
	v_fma_f32 v39, v43, s36, -v39
	v_fmac_f32_e32 v16, 0x3377d1cf, v41
; __device__ __forceinline__ unsigned cvt_pk_bf16(float lo, float hi) { unsigned r; asm("v_cvt_pk_bf16_f32 %0, %1, %2" : "=v"(r) : "v"(lo), "v"(hi)); return r; }
;     __device__ __forceinline__ void operator()(const f32x4 (&acc)[2][2][4][2], const Unit& u, int wr, int wc, int fr, int fq) const {
;     ...
;                 } else if (type == 4) {
;                     float* rp = (float*)base + (size_t)row * ld + col0 + cl; bf16_t* kp = (bf16_t*)(proj + (size_t)MP * 10240) + (size_t)row * ld + col0 + cl;
; #pragma unroll
;                     for (int bj = 0; bj < 2; ++bj) { f32x4 lfv[2], kkv[2];
; #pragma unroll
;                         for (int n = 0; n < 2; ++n) { const f32x4 lbq = *(const f32x4*)(lbp + col0 + cl + bj * 128 + 4 * n);
; #pragma unroll
;                             for (int e = 0; e < 4; ++e) { const float z = fminf(fmaxf(acc[ai][bj][m][n][e], -30.f), 30.f); const float sg = __builtin_amdgcn_rcpf(1.f + __expf(-z)); const float oml = 1.f - lbq[e];
;                                 lfv[n][e] = __logf(lbq[e] + oml * sg); kkv[n][e] = oml * (1.f - sg); }
;                             *(f32x4*)(rp + bj * 128 + 4 * n) = lfv[n]; }
;                         u32x4 w; w.x = cvt_pk_bf16(kkv[0][0], kkv[0][1]); w.y = cvt_pk_bf16(kkv[0][2], kkv[0][3]); w.z = cvt_pk_bf16(kkv[1][0], kkv[1][1]); w.w = cvt_pk_bf16(kkv[1][2], kkv[1][3]);
;                         *(u32x4*)(kp + bj * 128) = w; }
	v_fmac_f32_e32 v39, 0x3377d1cf, v43
	v_fmac_f32_e32 v16, 0x3f317217, v41
	v_cmp_lt_f32_e64 vcc, |v41|, s37
	v_fmac_f32_e32 v39, 0x3f317217, v43
	v_sub_f32_e32 v40, v44, v40
	v_cndmask_b32_e32 v16, v41, v16, vcc
	v_cmp_lt_f32_e64 vcc, |v43|, s37
	s_nop 1
	v_cndmask_b32_e32 v41, v43, v39, vcc
	v_sub_f32_e32 v39, v16, v42
	v_sub_f32_e32 v41, v41, v45
	global_store_dwordx4 v[54:55], v[38:41], off offset:512
	s_nop 0
	v_max_f32_e32 v16, v34, v34
	v_max_f32_e32 v34, v35, v35
	v_max_f32_e32 v35, v36, v36
	v_max_f32_e32 v36, v37, v37
	v_med3_f32 v16, v16, s38, v194
	v_med3_f32 v35, v35, s38, v194
	v_med3_f32 v34, v34, s38, v194
	v_med3_f32 v36, v36, s38, v194
	v_mul_f32_e32 v16, 0xbfb8aa3b, v16
	v_mul_f32_e32 v35, 0xbfb8aa3b, v35
	v_mul_f32_e32 v34, 0xbfb8aa3b, v34
	v_mul_f32_e32 v36, 0xbfb8aa3b, v36
	v_exp_f32_e32 v16, v16
	v_exp_f32_e32 v35, v35
	v_exp_f32_e32 v34, v34
	v_exp_f32_e32 v36, v36
	v_add_f32_e32 v16, 1.0, v16
	v_add_f32_e32 v35, 1.0, v35
	v_add_f32_e32 v56, 1.0, v34
	v_add_f32_e32 v57, 1.0, v36
	v_rcp_f32_e32 v34, v16
	v_rcp_f32_e32 v36, v35
	v_mul_f32_e32 v35, v48, v49
	v_mul_f32_e32 v37, v50, v51
	v_mul_f32_e32 v16, v46, v47
	v_mul_f32_e32 v42, v52, v53
	v_cvt_pk_bf16_f32 v50, v16, v37
	v_cvt_pk_bf16_f32 v51, v35, v42
	v_mov_b64_e32 v[38:39], v[216:217]
	v_mov_b64_e32 v[40:41], v[218:219]
	v_mov_b32_e32 v35, v38
	v_mov_b32_e32 v37, v40
	v_pk_add_f32 v[42:43], v[34:35], 1.0 op_sel_hi:[1,0] neg_lo:[1,0] neg_hi:[1,0]
	v_pk_add_f32 v[44:45], v[36:37], 1.0 op_sel_hi:[1,0] neg_lo:[1,0] neg_hi:[1,0]
	v_fma_f32 v16, v34, v43, v38
	v_rcp_f32_e32 v38, v56
	v_fma_f32 v34, v36, v45, v40
	v_rcp_f32_e32 v40, v57
	v_cmp_gt_f32_e32 vcc, s31, v16
	v_cmp_gt_f32_e64 s[46:47], s31, v34
	v_mul_f32_e32 v42, v42, v43
	v_cndmask_b32_e64 v35, 0, 32, vcc
	v_cndmask_b32_e64 v36, 0, 32, s[46:47]
	v_ldexp_f32 v16, v16, v35
	v_ldexp_f32 v34, v34, v36
	v_log_f32_e32 v16, v16
	v_log_f32_e32 v46, v34
	v_pk_add_f32 v[34:35], v[38:39], 1.0 op_sel_hi:[1,0] neg_lo:[1,0] neg_hi:[1,0]
	v_pk_add_f32 v[36:37], v[40:41], 1.0 op_sel_hi:[1,0] neg_lo:[1,0] neg_hi:[1,0]
	v_fma_f32 v38, v38, v35, v39
	v_mul_f32_e32 v43, v44, v45
	v_cndmask_b32_e32 v44, 0, v191, vcc
	v_fmac_f32_e32 v41, v40, v37
	v_cmp_gt_f32_e32 vcc, s31, v38
	v_cndmask_b32_e64 v45, 0, v191, s[46:47]
	v_mul_f32_e32 v34, v34, v35
	v_cndmask_b32_e64 v35, 0, 32, vcc
	v_cmp_gt_f32_e64 s[46:47], s31, v41
	v_mul_f32_e32 v39, v36, v37
	v_cvt_pk_bf16_f32 v52, v42, v34
	v_mul_f32_e32 v34, 0x3f317217, v16
	v_cndmask_b32_e64 v36, 0, 32, s[46:47]
	v_ldexp_f32 v35, v38, v35
	v_ldexp_f32 v36, v41, v36
	v_fma_f32 v34, v16, s36, -v34
	v_log_f32_e32 v35, v35
	v_mul_f32_e32 v38, 0x3f317217, v46
	v_log_f32_e32 v41, v36
	v_fmac_f32_e32 v34, 0x3377d1cf, v16
	v_cndmask_b32_e32 v37, 0, v191, vcc
	v_fma_f32 v38, v46, s36, -v38
	v_fmac_f32_e32 v34, 0x3f317217, v16
	v_cmp_lt_f32_e64 vcc, |v16|, s37
	v_fmac_f32_e32 v38, 0x3377d1cf, v46
	v_fmac_f32_e32 v38, 0x3f317217, v46
	v_cndmask_b32_e32 v16, v16, v34, vcc
	v_cmp_lt_f32_e64 vcc, |v46|, s37
	v_sub_f32_e32 v34, v16, v44
	v_mul_f32_e32 v16, 0x3f317217, v35
	v_cndmask_b32_e32 v36, v46, v38, vcc
	v_mul_f32_e32 v38, 0x3f317217, v41
	v_fma_f32 v16, v35, s36, -v16
	v_fma_f32 v38, v41, s36, -v38
	v_fmac_f32_e32 v16, 0x3377d1cf, v35
	v_fmac_f32_e32 v38, 0x3377d1cf, v41
	v_fmac_f32_e32 v16, 0x3f317217, v35
	v_cmp_lt_f32_e64 vcc, |v35|, s37
	v_fmac_f32_e32 v38, 0x3f317217, v41
	v_cndmask_b32_e64 v40, 0, v191, s[46:47]
	v_cndmask_b32_e32 v16, v35, v16, vcc
	v_cmp_lt_f32_e64 vcc, |v41|, s37
	v_sub_f32_e32 v36, v36, v45
	v_sub_f32_e32 v35, v16, v37
	v_cndmask_b32_e32 v38, v41, v38, vcc
	v_sub_f32_e32 v37, v38, v40
	global_store_dwordx4 v[54:55], v[34:37], off offset:528
	v_cvt_pk_bf16_f32 v53, v43, v39

; __device__ __forceinline__ unsigned cvt_pk_bf16(float lo, float hi) { unsigned r; asm("v_cvt_pk_bf16_f32 %0, %1, %2" : "=v"(r) : "v"(lo), "v"(hi)); return r; }
;     __device__ __forceinline__ void operator()(const f32x4 (&acc)[2][2][4][2], const Unit& u, int wr, int wc, int fr, int fq) const {
;     ...
;                 } else if (type == 4) {
;                     float* rp = (float*)base + (size_t)row * ld + col0 + cl; bf16_t* kp = (bf16_t*)(proj + (size_t)MP * 10240) + (size_t)row * ld + col0 + cl;
; #pragma unroll
;                     for (int bj = 0; bj < 2; ++bj) { f32x4 lfv[2], kkv[2];
; #pragma unroll
;                         for (int n = 0; n < 2; ++n) { const f32x4 lbq = *(const f32x4*)(lbp + col0 + cl + bj * 128 + 4 * n);
; #pragma unroll
;                             for (int e = 0; e < 4; ++e) { const float z = fminf(fmaxf(acc[ai][bj][m][n][e], -30.f), 30.f); const float sg = __builtin_amdgcn_rcpf(1.f + __expf(-z)); const float oml = 1.f - lbq[e];
;                                 lfv[n][e] = __logf(lbq[e] + oml * sg); kkv[n][e] = oml * (1.f - sg); }
;                             *(f32x4*)(rp + bj * 128 + 4 * n) = lfv[n]; }
;                         u32x4 w; w.x = cvt_pk_bf16(kkv[0][0], kkv[0][1]); w.y = cvt_pk_bf16(kkv[0][2], kkv[0][3]); w.z = cvt_pk_bf16(kkv[1][0], kkv[1][1]); w.w = cvt_pk_bf16(kkv[1][2], kkv[1][3]);
;                         *(u32x4*)(kp + bj * 128) = w; }
.LBB0_752:
	s_and_b64 vcc, exec, s[18:19]
	s_cbranch_vccz .LBB0_754
	s_lshl_b32 s18, s59, 2
	s_mov_b32 s19, s12
	v_lshl_add_u64 v[34:35], v[144:145], 0, s[18:19]
	s_nop 0
	v_lshlrev_b64 v[42:43], 12, v[40:41]
	v_max_f32_e32 v16, v30, v30
	v_max_f32_e32 v44, v31, v31
	v_max_f32_e32 v32, v32, v32
	v_lshl_add_u64 v[30:31], v[174:175], 0, v[42:43]
	v_med3_f32 v16, v16, s38, v194
	v_med3_f32 v42, v44, s38, v194
	v_med3_f32 v32, v32, s38, v194
	v_mul_f32_e32 v16, 0xbfb8aa3b, v16
	v_mul_f32_e32 v42, 0xbfb8aa3b, v42
	v_mul_f32_e32 v32, 0xbfb8aa3b, v32
	v_exp_f32_e32 v16, v16
	v_exp_f32_e32 v42, v42
	v_exp_f32_e32 v32, v32
	v_max_f32_e32 v33, v33, v33
	v_med3_f32 v33, v33, s38, v194
	v_mul_f32_e32 v33, 0xbfb8aa3b, v33
	v_exp_f32_e32 v33, v33
	v_add_f32_e32 v16, 1.0, v16
	v_add_f32_e32 v44, 1.0, v42
	v_add_f32_e32 v42, 1.0, v32
	v_rcp_f32_e32 v32, v16
	v_rcp_f32_e32 v42, v42
	v_add_f32_e32 v45, 1.0, v33
	v_max_f32_e32 v28, v28, v28
	s_mov_b32 s5, s12
	v_max_f32_e32 v29, v29, v29
	v_med3_f32 v28, v28, s38, v194
	v_mov_b32_e32 v169, v17
	v_med3_f32 v29, v29, s38, v194
	v_mul_f32_e32 v28, 0xbfb8aa3b, v28
	v_mul_f32_e32 v29, 0xbfb8aa3b, v29
	v_mov_b64_e32 v[36:37], v[204:205]
	v_mov_b64_e32 v[38:39], v[206:207]
	v_mov_b32_e32 v33, v36
	v_mov_b32_e32 v43, v38
	v_pk_add_f32 v[46:47], v[32:33], 1.0 op_sel_hi:[1,0] neg_lo:[1,0] neg_hi:[1,0]
	v_pk_add_f32 v[48:49], v[42:43], 1.0 op_sel_hi:[1,0] neg_lo:[1,0] neg_hi:[1,0]
	v_fma_f32 v16, v32, v47, v36
	v_rcp_f32_e32 v36, v44
	v_fma_f32 v32, v42, v49, v38
	v_rcp_f32_e32 v38, v45
	v_cmp_gt_f32_e32 vcc, s31, v16
	v_cmp_gt_f32_e64 s[46:47], s31, v32
	v_pk_add_f32 v[50:51], v[38:39], 1.0 op_sel_hi:[1,0] neg_lo:[1,0] neg_hi:[1,0]
	v_cndmask_b32_e64 v33, 0, 32, vcc
	v_cndmask_b32_e64 v42, 0, 32, s[46:47]
	v_ldexp_f32 v16, v16, v33
	v_ldexp_f32 v32, v32, v42
	v_log_f32_e32 v16, v16
	v_log_f32_e32 v44, v32
	v_pk_add_f32 v[32:33], v[36:37], 1.0 op_sel_hi:[1,0] neg_lo:[1,0] neg_hi:[1,0]
	v_cndmask_b32_e32 v43, 0, v191, vcc
	v_fma_f32 v36, v36, v33, v37
	v_fmac_f32_e32 v39, v38, v51
	v_cmp_gt_f32_e32 vcc, s31, v36
	v_cndmask_b32_e64 v42, 0, v191, s[46:47]
	v_cmp_gt_f32_e64 s[46:47], s31, v39
	v_cndmask_b32_e64 v37, 0, 32, vcc
	v_mul_f32_e32 v45, 0x3f317217, v16
	v_cndmask_b32_e64 v38, 0, 32, s[46:47]
	v_ldexp_f32 v36, v36, v37
	v_mul_f32_e32 v52, 0x3f317217, v44
	v_ldexp_f32 v38, v39, v38
	v_fma_f32 v45, v16, s36, -v45
	v_log_f32_e32 v53, v36
	v_fma_f32 v36, v44, s36, -v52
	v_log_f32_e32 v52, v38
	v_fmac_f32_e32 v45, 0x3377d1cf, v16
	v_cndmask_b32_e32 v37, 0, v191, vcc
	v_fmac_f32_e32 v36, 0x3377d1cf, v44
	v_fmac_f32_e32 v45, 0x3f317217, v16
	v_cmp_lt_f32_e64 vcc, |v16|, s37
	v_fmac_f32_e32 v36, 0x3f317217, v44
	v_cndmask_b32_e64 v39, 0, v191, s[46:47]
	v_cndmask_b32_e32 v16, v16, v45, vcc
	v_cmp_lt_f32_e64 vcc, |v44|, s37
	s_nop 1
	v_cndmask_b32_e32 v38, v44, v36, vcc
	v_sub_f32_e32 v36, v16, v43
	v_mul_f32_e32 v16, 0x3f317217, v53
	v_sub_f32_e32 v38, v38, v42
	v_mul_f32_e32 v42, 0x3f317217, v52
	v_fma_f32 v16, v53, s36, -v16
	v_fma_f32 v42, v52, s36, -v42
	v_fmac_f32_e32 v16, 0x3377d1cf, v53
	v_fmac_f32_e32 v42, 0x3377d1cf, v52
	v_fmac_f32_e32 v16, 0x3f317217, v53
	v_cmp_lt_f32_e64 vcc, |v53|, s37
	v_fmac_f32_e32 v42, 0x3f317217, v52
	s_nop 0
	v_cndmask_b32_e32 v16, v53, v16, vcc
	v_cmp_lt_f32_e64 vcc, |v52|, s37
	v_sub_f32_e32 v37, v16, v37
	v_max_f32_e32 v16, v26, v26
	v_cndmask_b32_e32 v42, v52, v42, vcc
	v_sub_f32_e32 v39, v42, v39
	global_store_dwordx4 v[30:31], v[36:39], off
	s_nop 0
	v_med3_f32 v16, v16, s38, v194
	v_lshlrev_b64 v[36:37], 11, v[40:41]
	v_max_f32_e32 v38, v27, v27
	v_lshl_add_u64 v[26:27], s[56:57], 0, v[36:37]
	v_med3_f32 v36, v38, s38, v194
	v_lshl_add_u64 v[26:27], v[26:27], 0, s[4:5]
	v_mul_f32_e32 v16, 0xbfb8aa3b, v16
	v_mul_f32_e32 v36, 0xbfb8aa3b, v36
	v_lshl_add_u64 v[38:39], v[26:27], 0, v[168:169]
	v_exp_f32_e32 v16, v16
	v_exp_f32_e32 v26, v36
	v_exp_f32_e32 v27, v28
	v_exp_f32_e32 v28, v29
	v_add_f32_e32 v16, 1.0, v16
	v_add_f32_e32 v52, 1.0, v26
	v_add_f32_e32 v26, 1.0, v27
	v_add_f32_e32 v53, 1.0, v28
	v_rcp_f32_e32 v28, v16
	v_rcp_f32_e32 v36, v26
	v_mul_f32_e32 v27, v48, v49
	v_mul_f32_e32 v29, v50, v51
	v_cvt_pk_bf16_f32 v27, v27, v29
	v_mul_f32_e32 v16, v46, v47
	v_mul_f32_e32 v26, v32, v33
	v_cvt_pk_bf16_f32 v26, v16, v26
	v_mov_b64_e32 v[42:43], v[208:209]
	v_mov_b64_e32 v[44:45], v[210:211]
	v_mov_b32_e32 v29, v42
	v_mov_b32_e32 v37, v44
	v_pk_add_f32 v[32:33], v[28:29], 1.0 op_sel_hi:[1,0] neg_lo:[1,0] neg_hi:[1,0]
	v_pk_add_f32 v[40:41], v[36:37], 1.0 op_sel_hi:[1,0] neg_lo:[1,0] neg_hi:[1,0]
	v_fma_f32 v16, v28, v33, v42
	v_rcp_f32_e32 v42, v52
	v_fma_f32 v28, v36, v41, v44
	v_rcp_f32_e32 v44, v53
	v_cmp_gt_f32_e32 vcc, s31, v16
	v_cmp_gt_f32_e64 s[46:47], s31, v28
	v_mul_f32_e32 v37, v32, v33
	v_cndmask_b32_e64 v29, 0, 32, vcc
	v_cndmask_b32_e64 v32, 0, 32, s[46:47]
	v_ldexp_f32 v16, v16, v29
	v_ldexp_f32 v28, v28, v32
	v_log_f32_e32 v16, v16
	v_log_f32_e32 v46, v28
	v_pk_add_f32 v[28:29], v[42:43], 1.0 op_sel_hi:[1,0] neg_lo:[1,0] neg_hi:[1,0]
	v_pk_add_f32 v[32:33], v[44:45], 1.0 op_sel_hi:[1,0] neg_lo:[1,0] neg_hi:[1,0]
	v_fma_f32 v42, v42, v29, v43
	v_mul_f32_e32 v36, v40, v41
	v_cndmask_b32_e32 v40, 0, v191, vcc
	v_fmac_f32_e32 v45, v44, v33
	v_cmp_gt_f32_e32 vcc, s31, v42
	v_cndmask_b32_e64 v41, 0, v191, s[46:47]
	v_mul_f32_e32 v28, v28, v29
	v_mul_f32_e32 v29, v32, v33
	v_cndmask_b32_e64 v32, 0, 32, vcc
	v_cmp_gt_f32_e64 s[46:47], s31, v45
	v_cvt_pk_bf16_f32 v29, v36, v29
	v_mul_f32_e32 v36, 0x3f317217, v16
	v_ldexp_f32 v32, v42, v32
	v_cndmask_b32_e64 v33, 0, 32, s[46:47]
	v_mul_f32_e32 v42, 0x3f317217, v46
	v_ldexp_f32 v33, v45, v33
	v_fma_f32 v36, v16, s36, -v36
; __device__ __forceinline__ unsigned cvt_pk_bf16(float lo, float hi) { unsigned r; asm("v_cvt_pk_bf16_f32 %0, %1, %2" : "=v"(r) : "v"(lo), "v"(hi)); return r; }
;     __device__ __forceinline__ void operator()(const f32x4 (&acc)[2][2][4][2], const Unit& u, int wr, int wc, int fr, int fq) const {
;     ...
;                 } else if (type == 4) {
;                     float* rp = (float*)base + (size_t)row * ld + col0 + cl; bf16_t* kp = (bf16_t*)(proj + (size_t)MP * 10240) + (size_t)row * ld + col0 + cl;
; #pragma unroll
;                     for (int bj = 0; bj < 2; ++bj) { f32x4 lfv[2], kkv[2];
; #pragma unroll
;                         for (int n = 0; n < 2; ++n) { const f32x4 lbq = *(const f32x4*)(lbp + col0 + cl + bj * 128 + 4 * n);
; #pragma unroll
;                             for (int e = 0; e < 4; ++e) { const float z = fminf(fmaxf(acc[ai][bj][m][n][e], -30.f), 30.f); const float sg = __builtin_amdgcn_rcpf(1.f + __expf(-z)); const float oml = 1.f - lbq[e];
;                                 lfv[n][e] = __logf(lbq[e] + oml * sg); kkv[n][e] = oml * (1.f - sg); }
;                             *(f32x4*)(rp + bj * 128 + 4 * n) = lfv[n]; }
;                         u32x4 w; w.x = cvt_pk_bf16(kkv[0][0], kkv[0][1]); w.y = cvt_pk_bf16(kkv[0][2], kkv[0][3]); w.z = cvt_pk_bf16(kkv[1][0], kkv[1][1]); w.w = cvt_pk_bf16(kkv[1][2], kkv[1][3]);
;                         *(u32x4*)(kp + bj * 128) = w; }
	v_log_f32_e32 v32, v32
	v_fma_f32 v42, v46, s36, -v42
	v_log_f32_e32 v33, v33
	v_fmac_f32_e32 v36, 0x3377d1cf, v16
	v_cvt_pk_bf16_f32 v28, v37, v28
	v_cndmask_b32_e32 v37, 0, v191, vcc
	v_fmac_f32_e32 v42, 0x3377d1cf, v46
	v_fmac_f32_e32 v36, 0x3f317217, v16
	v_cmp_lt_f32_e64 vcc, |v16|, s37
	v_fmac_f32_e32 v42, 0x3f317217, v46
	v_cndmask_b32_e64 v43, 0, v191, s[46:47]
	v_cndmask_b32_e32 v16, v16, v36, vcc
	v_cmp_lt_f32_e64 vcc, |v46|, s37
	v_sub_f32_e32 v40, v16, v40
	v_mul_f32_e32 v16, 0x3f317217, v32
	v_cndmask_b32_e32 v36, v46, v42, vcc
	v_sub_f32_e32 v42, v36, v41
	v_mul_f32_e32 v36, 0x3f317217, v33
	v_fma_f32 v16, v32, s36, -v16
	v_fma_f32 v36, v33, s36, -v36
	v_fmac_f32_e32 v16, 0x3377d1cf, v32
	v_fmac_f32_e32 v36, 0x3377d1cf, v33
	v_fmac_f32_e32 v16, 0x3f317217, v32
	v_cmp_lt_f32_e64 vcc, |v32|, s37
	v_fmac_f32_e32 v36, 0x3f317217, v33
	s_nop 0
	v_cndmask_b32_e32 v16, v32, v16, vcc
	v_cmp_lt_f32_e64 vcc, |v33|, s37
	v_sub_f32_e32 v41, v16, v37
	v_max_f32_e32 v16, v22, v22
	v_cndmask_b32_e32 v32, v33, v36, vcc
	v_sub_f32_e32 v43, v32, v43
	global_store_dwordx4 v[30:31], v[40:43], off offset:16
	global_store_dwordx4 v[38:39], v[26:29], off
	s_nop 0
	v_max_f32_e32 v22, v23, v23
	v_max_f32_e32 v23, v24, v24
	v_med3_f32 v16, v16, s38, v194
	v_max_f32_e32 v24, v25, v25
	v_med3_f32 v22, v22, s38, v194
	v_med3_f32 v23, v23, s38, v194
	v_mul_f32_e32 v16, 0xbfb8aa3b, v16
	v_med3_f32 v24, v24, s38, v194
	v_mul_f32_e32 v22, 0xbfb8aa3b, v22
	v_mul_f32_e32 v23, 0xbfb8aa3b, v23
	v_exp_f32_e32 v16, v16
	v_mul_f32_e32 v24, 0xbfb8aa3b, v24
	v_exp_f32_e32 v22, v22
	v_exp_f32_e32 v23, v23
	v_exp_f32_e32 v24, v24
	v_add_f32_e32 v16, 1.0, v16
	v_add_f32_e32 v40, 1.0, v22
	v_add_f32_e32 v23, 1.0, v23
	v_rcp_f32_e32 v22, v16
	v_add_f32_e32 v41, 1.0, v24
	v_rcp_f32_e32 v24, v23
	v_mov_b64_e32 v[26:27], v[212:213]
	v_mov_b64_e32 v[28:29], v[214:215]
	v_mov_b32_e32 v23, v26
	v_mov_b32_e32 v25, v28
	v_pk_add_f32 v[32:33], v[22:23], 1.0 op_sel_hi:[1,0] neg_lo:[1,0] neg_hi:[1,0]
	v_pk_add_f32 v[36:37], v[24:25], 1.0 op_sel_hi:[1,0] neg_lo:[1,0] neg_hi:[1,0]
	v_fma_f32 v16, v22, v33, v26
	v_rcp_f32_e32 v26, v40
	v_fma_f32 v22, v24, v37, v28
	v_rcp_f32_e32 v28, v41
	v_cmp_gt_f32_e32 vcc, s31, v16
	v_cmp_gt_f32_e64 s[46:47], s31, v22
	v_pk_add_f32 v[40:41], v[26:27], 1.0 op_sel_hi:[1,0] neg_lo:[1,0] neg_hi:[1,0]
	v_cndmask_b32_e64 v23, 0, 32, vcc
	v_cndmask_b32_e64 v24, 0, 32, s[46:47]
	v_ldexp_f32 v16, v16, v23
	v_ldexp_f32 v22, v22, v24
	v_log_f32_e32 v16, v16
	v_log_f32_e32 v22, v22
	v_pk_add_f32 v[42:43], v[28:29], 1.0 op_sel_hi:[1,0] neg_lo:[1,0] neg_hi:[1,0]
	v_fma_f32 v25, v26, v41, v27
	v_cndmask_b32_e32 v23, 0, v191, vcc
	v_fmac_f32_e32 v29, v28, v43
	v_cmp_gt_f32_e32 vcc, s31, v25
	v_cndmask_b32_e64 v24, 0, v191, s[46:47]
	v_cmp_gt_f32_e64 s[46:47], s31, v29
	v_cndmask_b32_e64 v26, 0, 32, vcc
	v_mul_f32_e32 v28, 0x3f317217, v16
	v_cndmask_b32_e64 v27, 0, 32, s[46:47]
	v_ldexp_f32 v25, v25, v26
	v_mul_f32_e32 v44, 0x3f317217, v22
	v_ldexp_f32 v27, v29, v27
	v_fma_f32 v28, v16, s36, -v28
	v_log_f32_e32 v25, v25
	v_fma_f32 v44, v22, s36, -v44
	v_log_f32_e32 v27, v27
	v_fmac_f32_e32 v28, 0x3377d1cf, v16
	v_cndmask_b32_e32 v26, 0, v191, vcc
	v_fmac_f32_e32 v44, 0x3377d1cf, v22
	v_fmac_f32_e32 v28, 0x3f317217, v16
	v_cmp_lt_f32_e64 vcc, |v16|, s37
	v_fmac_f32_e32 v44, 0x3f317217, v22
	v_cndmask_b32_e64 v29, 0, v191, s[46:47]
	v_cndmask_b32_e32 v16, v16, v28, vcc
	v_cmp_lt_f32_e64 vcc, |v22|, s37
	s_nop 1
	v_cndmask_b32_e32 v28, v22, v44, vcc
	v_sub_f32_e32 v22, v16, v23
	v_mul_f32_e32 v16, 0x3f317217, v25
	v_mul_f32_e32 v23, 0x3f317217, v27
	v_fma_f32 v16, v25, s36, -v16
	v_fma_f32 v23, v27, s36, -v23
	v_fmac_f32_e32 v16, 0x3377d1cf, v25
; __device__ __forceinline__ unsigned cvt_pk_bf16(float lo, float hi) { unsigned r; asm("v_cvt_pk_bf16_f32 %0, %1, %2" : "=v"(r) : "v"(lo), "v"(hi)); return r; }
;     __device__ __forceinline__ void operator()(const f32x4 (&acc)[2][2][4][2], const Unit& u, int wr, int wc, int fr, int fq) const {
;     ...
;                 } else if (type == 4) {
;                     float* rp = (float*)base + (size_t)row * ld + col0 + cl; bf16_t* kp = (bf16_t*)(proj + (size_t)MP * 10240) + (size_t)row * ld + col0 + cl;
; #pragma unroll
;                     for (int bj = 0; bj < 2; ++bj) { f32x4 lfv[2], kkv[2];
; #pragma unroll
;                         for (int n = 0; n < 2; ++n) { const f32x4 lbq = *(const f32x4*)(lbp + col0 + cl + bj * 128 + 4 * n);
; #pragma unroll
;                             for (int e = 0; e < 4; ++e) { const float z = fminf(fmaxf(acc[ai][bj][m][n][e], -30.f), 30.f); const float sg = __builtin_amdgcn_rcpf(1.f + __expf(-z)); const float oml = 1.f - lbq[e];
;                                 lfv[n][e] = __logf(lbq[e] + oml * sg); kkv[n][e] = oml * (1.f - sg); }
;                             *(f32x4*)(rp + bj * 128 + 4 * n) = lfv[n]; }
;                         u32x4 w; w.x = cvt_pk_bf16(kkv[0][0], kkv[0][1]); w.y = cvt_pk_bf16(kkv[0][2], kkv[0][3]); w.z = cvt_pk_bf16(kkv[1][0], kkv[1][1]); w.w = cvt_pk_bf16(kkv[1][2], kkv[1][3]);
;                         *(u32x4*)(kp + bj * 128) = w; }
	v_fmac_f32_e32 v23, 0x3377d1cf, v27
	v_fmac_f32_e32 v16, 0x3f317217, v25
	v_cmp_lt_f32_e64 vcc, |v25|, s37
	v_fmac_f32_e32 v23, 0x3f317217, v27
	v_sub_f32_e32 v24, v28, v24
	v_cndmask_b32_e32 v16, v25, v16, vcc
	v_cmp_lt_f32_e64 vcc, |v27|, s37
	s_nop 1
	v_cndmask_b32_e32 v25, v27, v23, vcc
	v_sub_f32_e32 v23, v16, v26
	v_sub_f32_e32 v25, v25, v29
	global_store_dwordx4 v[30:31], v[22:25], off offset:512
	s_nop 0
	v_max_f32_e32 v16, v18, v18
	v_max_f32_e32 v18, v19, v19
	v_max_f32_e32 v19, v20, v20
	v_max_f32_e32 v20, v21, v21
	v_med3_f32 v16, v16, s38, v194
	v_med3_f32 v19, v19, s38, v194
	v_med3_f32 v18, v18, s38, v194
	v_med3_f32 v20, v20, s38, v194
	v_mul_f32_e32 v16, 0xbfb8aa3b, v16
	v_mul_f32_e32 v19, 0xbfb8aa3b, v19
	v_mul_f32_e32 v18, 0xbfb8aa3b, v18
	v_mul_f32_e32 v20, 0xbfb8aa3b, v20
	v_exp_f32_e32 v16, v16
	v_exp_f32_e32 v19, v19
	v_exp_f32_e32 v18, v18
	v_exp_f32_e32 v20, v20
	v_add_f32_e32 v16, 1.0, v16
	v_add_f32_e32 v19, 1.0, v19
	v_add_f32_e32 v44, 1.0, v18
	v_add_f32_e32 v45, 1.0, v20
	v_rcp_f32_e32 v18, v16
	v_rcp_f32_e32 v20, v19
	v_mul_f32_e32 v19, v36, v37
	v_mul_f32_e32 v21, v40, v41
	v_mul_f32_e32 v16, v32, v33
	v_mul_f32_e32 v26, v42, v43
	v_cvt_pk_bf16_f32 v34, v16, v21
	v_cvt_pk_bf16_f32 v35, v19, v26
	v_mov_b64_e32 v[22:23], v[216:217]
	v_mov_b64_e32 v[24:25], v[218:219]
	v_mov_b32_e32 v19, v22
	v_mov_b32_e32 v21, v24
	v_pk_add_f32 v[26:27], v[18:19], 1.0 op_sel_hi:[1,0] neg_lo:[1,0] neg_hi:[1,0]
	v_pk_add_f32 v[28:29], v[20:21], 1.0 op_sel_hi:[1,0] neg_lo:[1,0] neg_hi:[1,0]
	v_fma_f32 v16, v18, v27, v22
	v_rcp_f32_e32 v22, v44
	v_fma_f32 v18, v20, v29, v24
	v_rcp_f32_e32 v24, v45
	v_cmp_gt_f32_e32 vcc, s31, v16
	v_cmp_gt_f32_e64 s[46:47], s31, v18
	v_mul_f32_e32 v26, v26, v27
	v_cndmask_b32_e64 v19, 0, 32, vcc
	v_cndmask_b32_e64 v20, 0, 32, s[46:47]
	v_ldexp_f32 v16, v16, v19
	v_ldexp_f32 v18, v18, v20
	v_log_f32_e32 v16, v16
	v_log_f32_e32 v32, v18
	v_pk_add_f32 v[18:19], v[22:23], 1.0 op_sel_hi:[1,0] neg_lo:[1,0] neg_hi:[1,0]
	v_pk_add_f32 v[20:21], v[24:25], 1.0 op_sel_hi:[1,0] neg_lo:[1,0] neg_hi:[1,0]
	v_fma_f32 v22, v22, v19, v23
	v_mul_f32_e32 v27, v28, v29
	v_cndmask_b32_e32 v28, 0, v191, vcc
	v_fmac_f32_e32 v25, v24, v21
	v_cmp_gt_f32_e32 vcc, s31, v22
	v_cndmask_b32_e64 v29, 0, v191, s[46:47]
	v_mul_f32_e32 v18, v18, v19
	v_cndmask_b32_e64 v19, 0, 32, vcc
	v_cmp_gt_f32_e64 s[46:47], s31, v25
	v_mul_f32_e32 v23, v20, v21
	v_cvt_pk_bf16_f32 v36, v26, v18
	v_mul_f32_e32 v18, 0x3f317217, v16
	v_cndmask_b32_e64 v20, 0, 32, s[46:47]
	v_ldexp_f32 v19, v22, v19
	v_ldexp_f32 v20, v25, v20
	v_fma_f32 v18, v16, s36, -v18
	v_log_f32_e32 v19, v19
	v_mul_f32_e32 v22, 0x3f317217, v32
	v_log_f32_e32 v25, v20
	v_fmac_f32_e32 v18, 0x3377d1cf, v16
	v_cndmask_b32_e32 v21, 0, v191, vcc
	v_fma_f32 v22, v32, s36, -v22
	v_fmac_f32_e32 v18, 0x3f317217, v16
	v_cmp_lt_f32_e64 vcc, |v16|, s37
	v_fmac_f32_e32 v22, 0x3377d1cf, v32
	v_fmac_f32_e32 v22, 0x3f317217, v32
	v_cndmask_b32_e32 v16, v16, v18, vcc
	v_cmp_lt_f32_e64 vcc, |v32|, s37
	v_sub_f32_e32 v18, v16, v28
	v_mul_f32_e32 v16, 0x3f317217, v19
	v_cndmask_b32_e32 v20, v32, v22, vcc
	v_mul_f32_e32 v22, 0x3f317217, v25
	v_fma_f32 v16, v19, s36, -v16
	v_fma_f32 v22, v25, s36, -v22
	v_fmac_f32_e32 v16, 0x3377d1cf, v19
	v_fmac_f32_e32 v22, 0x3377d1cf, v25
	v_fmac_f32_e32 v16, 0x3f317217, v19
	v_cmp_lt_f32_e64 vcc, |v19|, s37
	v_fmac_f32_e32 v22, 0x3f317217, v25
	v_cndmask_b32_e64 v24, 0, v191, s[46:47]
	v_cndmask_b32_e32 v16, v19, v16, vcc
	v_cmp_lt_f32_e64 vcc, |v25|, s37
	v_sub_f32_e32 v20, v20, v29
	v_sub_f32_e32 v19, v16, v21
	v_cndmask_b32_e32 v22, v25, v22, vcc
	v_sub_f32_e32 v21, v22, v24
	global_store_dwordx4 v[30:31], v[18:21], off offset:528
	v_cvt_pk_bf16_f32 v37, v27, v23

; __device__ __forceinline__ unsigned cvt_pk_bf16(float lo, float hi) { unsigned r; asm("v_cvt_pk_bf16_f32 %0, %1, %2" : "=v"(r) : "v"(lo), "v"(hi)); return r; }
;     __device__ __forceinline__ void operator()(const f32x4 (&acc)[2][2][4][2], const Unit& u, int wr, int wc, int fr, int fq) const {
;     ...
;                 } else if (type == 4) {
;                     float* rp = (float*)base + (size_t)row * ld + col0 + cl; bf16_t* kp = (bf16_t*)(proj + (size_t)MP * 10240) + (size_t)row * ld + col0 + cl;
; #pragma unroll
;                     for (int bj = 0; bj < 2; ++bj) { f32x4 lfv[2], kkv[2];
; #pragma unroll
;                         for (int n = 0; n < 2; ++n) { const f32x4 lbq = *(const f32x4*)(lbp + col0 + cl + bj * 128 + 4 * n);
; #pragma unroll
;                             for (int e = 0; e < 4; ++e) { const float z = fminf(fmaxf(acc[ai][bj][m][n][e], -30.f), 30.f); const float sg = __builtin_amdgcn_rcpf(1.f + __expf(-z)); const float oml = 1.f - lbq[e];
;                                 lfv[n][e] = __logf(lbq[e] + oml * sg); kkv[n][e] = oml * (1.f - sg); }
;                             *(f32x4*)(rp + bj * 128 + 4 * n) = lfv[n]; }
;                         u32x4 w; w.x = cvt_pk_bf16(kkv[0][0], kkv[0][1]); w.y = cvt_pk_bf16(kkv[0][2], kkv[0][3]); w.z = cvt_pk_bf16(kkv[1][0], kkv[1][1]); w.w = cvt_pk_bf16(kkv[1][2], kkv[1][3]);
;                         *(u32x4*)(kp + bj * 128) = w; }
.LBB0_760:
	s_and_b64 vcc, exec, s[18:19]
	s_cbranch_vccz .LBB0_679
	v_lshlrev_b64 v[18:19], 12, v[26:27]
	v_lshl_add_u64 v[24:25], v[174:175], 0, v[18:19]
	v_lshlrev_b64 v[18:19], 11, v[26:27]
	v_lshl_add_u64 v[18:19], s[56:57], 0, v[18:19]
	s_mov_b32 s5, s12
	v_lshl_add_u64 v[18:19], v[18:19], 0, s[4:5]
	s_lshl_b32 s4, s59, 2
	v_mov_b32_e32 v169, v17
	v_lshl_add_u64 v[26:27], v[144:145], 0, s[4:5]
	v_lshl_add_u64 v[22:23], v[18:19], 0, v[168:169]
	s_nop 0
	v_max_f32_e32 v12, v12, v12
	v_med3_f32 v12, v12, s38, v194
	v_mul_f32_e32 v12, 0xbfb8aa3b, v12
	v_exp_f32_e32 v12, v12
	v_max_f32_e32 v13, v13, v13
	v_med3_f32 v13, v13, s38, v194
	v_mul_f32_e32 v13, 0xbfb8aa3b, v13
	v_add_f32_e32 v12, 1.0, v12
	v_rcp_f32_e32 v28, v12
	v_exp_f32_e32 v13, v13
	v_max_f32_e32 v14, v14, v14
	v_med3_f32 v14, v14, s38, v194
	v_mul_f32_e32 v14, 0xbfb8aa3b, v14
	v_add_f32_e32 v13, 1.0, v13
	v_exp_f32_e32 v14, v14
	v_max_f32_e32 v15, v15, v15
	v_med3_f32 v15, v15, s38, v194
	v_mul_f32_e32 v15, 0xbfb8aa3b, v15
	v_add_f32_e32 v14, 1.0, v14
	v_exp_f32_e32 v15, v15
	v_max_f32_e32 v8, v8, v8
	v_med3_f32 v8, v8, s38, v194
	v_mul_f32_e32 v8, 0xbfb8aa3b, v8
	v_add_f32_e32 v15, 1.0, v15
	v_exp_f32_e32 v8, v8
	v_max_f32_e32 v9, v9, v9
	v_med3_f32 v9, v9, s38, v194
	v_mul_f32_e32 v9, 0xbfb8aa3b, v9
	v_add_f32_e32 v8, 1.0, v8
	v_exp_f32_e32 v9, v9
	v_max_f32_e32 v10, v10, v10
	v_med3_f32 v10, v10, s38, v194
	v_mul_f32_e32 v10, 0xbfb8aa3b, v10
	v_add_f32_e32 v9, 1.0, v9
	v_exp_f32_e32 v10, v10
	v_max_f32_e32 v11, v11, v11
	v_med3_f32 v11, v11, s38, v194
	v_mul_f32_e32 v11, 0xbfb8aa3b, v11
	v_add_f32_e32 v10, 1.0, v10
	v_exp_f32_e32 v11, v11
	v_max_f32_e32 v4, v4, v4
	v_med3_f32 v4, v4, s38, v194
	v_mul_f32_e32 v4, 0xbfb8aa3b, v4
	v_add_f32_e32 v11, 1.0, v11
	v_exp_f32_e32 v4, v4
	v_max_f32_e32 v5, v5, v5
	v_med3_f32 v5, v5, s38, v194
	v_mul_f32_e32 v5, 0xbfb8aa3b, v5
	v_add_f32_e32 v4, 1.0, v4
	v_exp_f32_e32 v5, v5
	v_max_f32_e32 v6, v6, v6
	v_med3_f32 v6, v6, s38, v194
	v_mul_f32_e32 v6, 0xbfb8aa3b, v6
	v_add_f32_e32 v5, 1.0, v5
	v_exp_f32_e32 v6, v6
	v_max_f32_e32 v7, v7, v7
	v_med3_f32 v7, v7, s38, v194
	v_mul_f32_e32 v7, 0xbfb8aa3b, v7
	v_add_f32_e32 v6, 1.0, v6
	v_exp_f32_e32 v7, v7
	v_max_f32_e32 v0, v0, v0
	v_med3_f32 v0, v0, s38, v194
	v_mul_f32_e32 v0, 0xbfb8aa3b, v0
	v_add_f32_e32 v7, 1.0, v7
	v_exp_f32_e32 v0, v0
	v_max_f32_e32 v1, v1, v1
	v_med3_f32 v1, v1, s38, v194
	v_mul_f32_e32 v1, 0xbfb8aa3b, v1
	v_add_f32_e32 v0, 1.0, v0
	v_exp_f32_e32 v1, v1
	v_max_f32_e32 v2, v2, v2
	v_med3_f32 v2, v2, s38, v194
	v_mul_f32_e32 v2, 0xbfb8aa3b, v2
	v_add_f32_e32 v1, 1.0, v1
	v_exp_f32_e32 v2, v2
	v_max_f32_e32 v3, v3, v3
	v_med3_f32 v3, v3, s38, v194
	v_mul_f32_e32 v3, 0xbfb8aa3b, v3
	v_add_f32_e32 v2, 1.0, v2
	v_mov_b64_e32 v[18:19], v[204:205]
	v_mov_b64_e32 v[20:21], v[206:207]
	v_mov_b32_e32 v29, v18
	v_pk_add_f32 v[30:31], v[28:29], 1.0 op_sel_hi:[1,0] neg_lo:[1,0] neg_hi:[1,0]
	v_exp_f32_e32 v3, v3
	v_fma_f32 v12, v28, v31, v18
	v_cmp_gt_f32_e32 vcc, s31, v12
	v_rcp_f32_e32 v18, v13
	v_add_f32_e32 v3, 1.0, v3
	v_cndmask_b32_e64 v16, 0, 32, vcc
	v_ldexp_f32 v12, v12, v16
	v_log_f32_e32 v12, v12
	v_pk_add_f32 v[28:29], v[18:19], 1.0 op_sel_hi:[1,0] neg_lo:[1,0] neg_hi:[1,0]
	v_mul_f32_e32 v16, 0x3f317217, v12
	v_fma_f32 v16, v12, s36, -v16
	v_fmac_f32_e32 v16, 0x3377d1cf, v12
	v_fmac_f32_e32 v16, 0x3f317217, v12
	v_cmp_lt_f32_e64 s[42:43], |v12|, s37
	v_fma_f32 v13, v18, v29, v19
	s_nop 0
	v_cndmask_b32_e64 v12, v12, v16, s[42:43]
	v_cndmask_b32_e32 v16, 0, v191, vcc
	v_cmp_gt_f32_e32 vcc, s31, v13
	v_sub_f32_e32 v12, v12, v16
	v_mul_f32_e32 v16, v30, v31
	v_cndmask_b32_e64 v18, 0, 32, vcc
	v_ldexp_f32 v13, v13, v18
	v_log_f32_e32 v13, v13
	s_nop 0
	v_mul_f32_e32 v18, 0x3f317217, v13
	v_fma_f32 v18, v13, s36, -v18
	v_fmac_f32_e32 v18, 0x3377d1cf, v13
	v_fmac_f32_e32 v18, 0x3f317217, v13
	v_cmp_lt_f32_e64 s[42:43], |v13|, s37
	s_nop 1
	v_cndmask_b32_e64 v13, v13, v18, s[42:43]
	v_cndmask_b32_e32 v18, 0, v191, vcc
	v_sub_f32_e32 v13, v13, v18
	v_mul_f32_e32 v18, v28, v29
	v_rcp_f32_e32 v28, v14
	v_mov_b32_e32 v29, v20
	v_pk_add_f32 v[30:31], v[28:29], 1.0 op_sel_hi:[1,0] neg_lo:[1,0] neg_hi:[1,0]
	s_nop 0
	v_fma_f32 v14, v28, v31, v20
	v_cmp_gt_f32_e32 vcc, s31, v14
	v_rcp_f32_e32 v20, v15
	s_nop 0
	v_cndmask_b32_e64 v19, 0, 32, vcc
	v_ldexp_f32 v14, v14, v19
	v_log_f32_e32 v14, v14
	v_pk_add_f32 v[28:29], v[20:21], 1.0 op_sel_hi:[1,0] neg_lo:[1,0] neg_hi:[1,0]
	v_mul_f32_e32 v19, 0x3f317217, v14
	v_fma_f32 v19, v14, s36, -v19
	v_fmac_f32_e32 v19, 0x3377d1cf, v14
	v_fmac_f32_e32 v19, 0x3f317217, v14
	v_cmp_lt_f32_e64 s[42:43], |v14|, s37
	v_fmac_f32_e32 v21, v20, v29
	s_nop 0
	v_cndmask_b32_e64 v14, v14, v19, s[42:43]
	v_cndmask_b32_e32 v19, 0, v191, vcc
	v_cmp_gt_f32_e32 vcc, s31, v21
	v_sub_f32_e32 v14, v14, v19
	v_mul_f32_e32 v19, v30, v31
	v_cndmask_b32_e64 v15, 0, 32, vcc
	v_ldexp_f32 v15, v21, v15
	v_log_f32_e32 v15, v15
	v_mul_f32_e32 v21, v28, v29
	v_rcp_f32_e32 v28, v8
	v_mul_f32_e32 v20, 0x3f317217, v15
	v_fma_f32 v20, v15, s36, -v20
	v_fmac_f32_e32 v20, 0x3377d1cf, v15
	v_fmac_f32_e32 v20, 0x3f317217, v15
	v_cmp_lt_f32_e64 s[42:43], |v15|, s37
	s_nop 1
	v_cndmask_b32_e64 v15, v15, v20, s[42:43]
	v_cndmask_b32_e32 v20, 0, v191, vcc
	v_sub_f32_e32 v15, v15, v20
	global_store_dwordx4 v[24:25], v[12:15], off
	s_nop 0
	v_mov_b64_e32 v[12:13], v[208:209]
	v_mov_b64_e32 v[14:15], v[210:211]
	v_mov_b32_e32 v29, v12
	v_pk_add_f32 v[30:31], v[28:29], 1.0 op_sel_hi:[1,0] neg_lo:[1,0] neg_hi:[1,0]
	s_nop 0
	v_fma_f32 v8, v28, v31, v12
	v_cmp_gt_f32_e32 vcc, s31, v8
	v_mul_f32_e32 v20, v30, v31
	s_nop 0
	v_cndmask_b32_e64 v12, 0, 32, vcc
	v_ldexp_f32 v8, v8, v12
; __device__ __forceinline__ unsigned cvt_pk_bf16(float lo, float hi) { unsigned r; asm("v_cvt_pk_bf16_f32 %0, %1, %2" : "=v"(r) : "v"(lo), "v"(hi)); return r; }
;     __device__ __forceinline__ void operator()(const f32x4 (&acc)[2][2][4][2], const Unit& u, int wr, int wc, int fr, int fq) const {
;     ...
;                 } else if (type == 4) {
;                     float* rp = (float*)base + (size_t)row * ld + col0 + cl; bf16_t* kp = (bf16_t*)(proj + (size_t)MP * 10240) + (size_t)row * ld + col0 + cl;
; #pragma unroll
;                     for (int bj = 0; bj < 2; ++bj) { f32x4 lfv[2], kkv[2];
; #pragma unroll
;                         for (int n = 0; n < 2; ++n) { const f32x4 lbq = *(const f32x4*)(lbp + col0 + cl + bj * 128 + 4 * n);
; #pragma unroll
;                             for (int e = 0; e < 4; ++e) { const float z = fminf(fmaxf(acc[ai][bj][m][n][e], -30.f), 30.f); const float sg = __builtin_amdgcn_rcpf(1.f + __expf(-z)); const float oml = 1.f - lbq[e];
;                                 lfv[n][e] = __logf(lbq[e] + oml * sg); kkv[n][e] = oml * (1.f - sg); }
;                             *(f32x4*)(rp + bj * 128 + 4 * n) = lfv[n]; }
;                         u32x4 w; w.x = cvt_pk_bf16(kkv[0][0], kkv[0][1]); w.y = cvt_pk_bf16(kkv[0][2], kkv[0][3]); w.z = cvt_pk_bf16(kkv[1][0], kkv[1][1]); w.w = cvt_pk_bf16(kkv[1][2], kkv[1][3]);
;                         *(u32x4*)(kp + bj * 128) = w; }
	v_log_f32_e32 v8, v8
	s_nop 0
	v_mul_f32_e32 v12, 0x3f317217, v8
	v_fma_f32 v12, v8, s36, -v12
	v_fmac_f32_e32 v12, 0x3377d1cf, v8
	v_fmac_f32_e32 v12, 0x3f317217, v8
	v_cmp_lt_f32_e64 s[42:43], |v8|, s37
	s_nop 1
	v_cndmask_b32_e64 v8, v8, v12, s[42:43]
	v_cndmask_b32_e32 v12, 0, v191, vcc
	v_sub_f32_e32 v8, v8, v12
	v_rcp_f32_e32 v12, v9
	s_nop 0
	v_pk_add_f32 v[28:29], v[12:13], 1.0 op_sel_hi:[1,0] neg_lo:[1,0] neg_hi:[1,0]
	s_nop 0
	v_fma_f32 v9, v12, v29, v13
	v_cmp_gt_f32_e32 vcc, s31, v9
	v_mov_b32_e32 v13, v14
	v_mul_f32_e32 v30, v28, v29
	v_cndmask_b32_e64 v12, 0, 32, vcc
	v_ldexp_f32 v9, v9, v12
	v_log_f32_e32 v9, v9
	s_nop 0
	v_mul_f32_e32 v12, 0x3f317217, v9
	v_fma_f32 v12, v9, s36, -v12
	v_fmac_f32_e32 v12, 0x3377d1cf, v9
	v_fmac_f32_e32 v12, 0x3f317217, v9
	v_cmp_lt_f32_e64 s[42:43], |v9|, s37
	s_nop 1
	v_cndmask_b32_e64 v9, v9, v12, s[42:43]
	v_cndmask_b32_e32 v12, 0, v191, vcc
	v_sub_f32_e32 v9, v9, v12
	v_rcp_f32_e32 v12, v10
	s_nop 0
	v_pk_add_f32 v[28:29], v[12:13], 1.0 op_sel_hi:[1,0] neg_lo:[1,0] neg_hi:[1,0]
	s_nop 0
	v_fma_f32 v10, v12, v29, v14
	v_cmp_gt_f32_e32 vcc, s31, v10
	v_rcp_f32_e32 v14, v11
	v_mul_f32_e32 v28, v28, v29
	v_cndmask_b32_e64 v12, 0, 32, vcc
	v_ldexp_f32 v10, v10, v12
	v_log_f32_e32 v10, v10
	s_nop 0
	v_mul_f32_e32 v12, 0x3f317217, v10
	v_fma_f32 v12, v10, s36, -v12
	v_fmac_f32_e32 v12, 0x3377d1cf, v10
	v_fmac_f32_e32 v12, 0x3f317217, v10
	v_cmp_lt_f32_e64 s[42:43], |v10|, s37
	s_nop 1
	v_cndmask_b32_e64 v10, v10, v12, s[42:43]
	v_cndmask_b32_e32 v12, 0, v191, vcc
	v_sub_f32_e32 v10, v10, v12
	v_pk_add_f32 v[12:13], v[14:15], 1.0 op_sel_hi:[1,0] neg_lo:[1,0] neg_hi:[1,0]
	s_nop 0
	v_fmac_f32_e32 v15, v14, v13
	v_cmp_gt_f32_e32 vcc, s31, v15
	v_mul_f32_e32 v12, v12, v13
	s_nop 0
	v_cndmask_b32_e64 v11, 0, 32, vcc
	v_ldexp_f32 v11, v15, v11
	v_log_f32_e32 v11, v11
	s_nop 0
	v_mul_f32_e32 v14, 0x3f317217, v11
	v_fma_f32 v14, v11, s36, -v14
	v_fmac_f32_e32 v14, 0x3377d1cf, v11
	v_fmac_f32_e32 v14, 0x3f317217, v11
	v_cmp_lt_f32_e64 s[42:43], |v11|, s37
	s_nop 1
	v_cndmask_b32_e64 v11, v11, v14, s[42:43]
	v_cndmask_b32_e32 v14, 0, v191, vcc
	v_sub_f32_e32 v11, v11, v14
	global_store_dwordx4 v[24:25], v[8:11], off offset:16
	s_nop 1
	v_cvt_pk_bf16_f32 v8, v16, v18
	v_cvt_pk_bf16_f32 v9, v19, v21
	v_cvt_pk_bf16_f32 v10, v20, v30
	v_cvt_pk_bf16_f32 v11, v28, v12
	global_store_dwordx4 v[22:23], v[8:11], off
	s_nop 0
	v_rcp_f32_e32 v12, v4
	v_mov_b64_e32 v[8:9], v[212:213]
	v_mov_b64_e32 v[10:11], v[214:215]
	v_mov_b32_e32 v13, v8
	v_pk_add_f32 v[14:15], v[12:13], 1.0 op_sel_hi:[1,0] neg_lo:[1,0] neg_hi:[1,0]
	s_nop 0
	v_fma_f32 v4, v12, v15, v8
	v_cmp_gt_f32_e32 vcc, s31, v4
	v_mul_f32_e32 v12, v14, v15
	s_nop 0
	v_cndmask_b32_e64 v8, 0, 32, vcc
	v_ldexp_f32 v4, v4, v8
	v_log_f32_e32 v4, v4
	s_nop 0
	v_mul_f32_e32 v8, 0x3f317217, v4
	v_fma_f32 v8, v4, s36, -v8
	v_fmac_f32_e32 v8, 0x3377d1cf, v4
	v_fmac_f32_e32 v8, 0x3f317217, v4
	v_cmp_lt_f32_e64 s[42:43], |v4|, s37
	s_nop 1
	v_cndmask_b32_e64 v4, v4, v8, s[42:43]
	v_cndmask_b32_e32 v8, 0, v191, vcc
	v_sub_f32_e32 v4, v4, v8
	v_rcp_f32_e32 v8, v5
	s_nop 0
	v_pk_add_f32 v[14:15], v[8:9], 1.0 op_sel_hi:[1,0] neg_lo:[1,0] neg_hi:[1,0]
	s_nop 0
	v_fma_f32 v5, v8, v15, v9
	v_cmp_gt_f32_e32 vcc, s31, v5
	s_nop 1
	v_cndmask_b32_e64 v8, 0, 32, vcc
	v_ldexp_f32 v5, v5, v8
	v_log_f32_e32 v5, v5
	s_nop 0
	v_mul_f32_e32 v8, 0x3f317217, v5
	v_fma_f32 v8, v5, s36, -v8
	v_fmac_f32_e32 v8, 0x3377d1cf, v5
	v_fmac_f32_e32 v8, 0x3f317217, v5
	v_cmp_lt_f32_e64 s[42:43], |v5|, s37
	s_nop 1
	v_cndmask_b32_e64 v5, v5, v8, s[42:43]
	v_cndmask_b32_e32 v8, 0, v191, vcc
	v_sub_f32_e32 v5, v5, v8
	v_mul_f32_e32 v8, v14, v15
	v_rcp_f32_e32 v14, v6
	v_mov_b32_e32 v15, v10
	v_pk_add_f32 v[18:19], v[14:15], 1.0 op_sel_hi:[1,0] neg_lo:[1,0] neg_hi:[1,0]
; __device__ __forceinline__ unsigned cvt_pk_bf16(float lo, float hi) { unsigned r; asm("v_cvt_pk_bf16_f32 %0, %1, %2" : "=v"(r) : "v"(lo), "v"(hi)); return r; }
;     __device__ __forceinline__ void operator()(const f32x4 (&acc)[2][2][4][2], const Unit& u, int wr, int wc, int fr, int fq) const {
;     ...
;                 } else if (type == 4) {
;                     float* rp = (float*)base + (size_t)row * ld + col0 + cl; bf16_t* kp = (bf16_t*)(proj + (size_t)MP * 10240) + (size_t)row * ld + col0 + cl;
; #pragma unroll
;                     for (int bj = 0; bj < 2; ++bj) { f32x4 lfv[2], kkv[2];
; #pragma unroll
;                         for (int n = 0; n < 2; ++n) { const f32x4 lbq = *(const f32x4*)(lbp + col0 + cl + bj * 128 + 4 * n);
; #pragma unroll
;                             for (int e = 0; e < 4; ++e) { const float z = fminf(fmaxf(acc[ai][bj][m][n][e], -30.f), 30.f); const float sg = __builtin_amdgcn_rcpf(1.f + __expf(-z)); const float oml = 1.f - lbq[e];
;                                 lfv[n][e] = __logf(lbq[e] + oml * sg); kkv[n][e] = oml * (1.f - sg); }
;                             *(f32x4*)(rp + bj * 128 + 4 * n) = lfv[n]; }
;                         u32x4 w; w.x = cvt_pk_bf16(kkv[0][0], kkv[0][1]); w.y = cvt_pk_bf16(kkv[0][2], kkv[0][3]); w.z = cvt_pk_bf16(kkv[1][0], kkv[1][1]); w.w = cvt_pk_bf16(kkv[1][2], kkv[1][3]);
;                         *(u32x4*)(kp + bj * 128) = w; }
	s_nop 0
	v_fma_f32 v6, v14, v19, v10
	v_cmp_gt_f32_e32 vcc, s31, v6
	v_rcp_f32_e32 v10, v7
	s_nop 0
	v_cndmask_b32_e64 v9, 0, 32, vcc
	v_ldexp_f32 v6, v6, v9
	v_log_f32_e32 v6, v6
	v_pk_add_f32 v[14:15], v[10:11], 1.0 op_sel_hi:[1,0] neg_lo:[1,0] neg_hi:[1,0]
	v_mul_f32_e32 v9, 0x3f317217, v6
	v_fma_f32 v9, v6, s36, -v9
	v_fmac_f32_e32 v9, 0x3377d1cf, v6
	v_fmac_f32_e32 v9, 0x3f317217, v6
	v_cmp_lt_f32_e64 s[42:43], |v6|, s37
	v_fmac_f32_e32 v11, v10, v15
	s_nop 0
	v_cndmask_b32_e64 v6, v6, v9, s[42:43]
	v_cndmask_b32_e32 v9, 0, v191, vcc
	v_cmp_gt_f32_e32 vcc, s31, v11
	v_sub_f32_e32 v6, v6, v9
	v_mul_f32_e32 v9, v18, v19
	v_cndmask_b32_e64 v7, 0, 32, vcc
	v_ldexp_f32 v7, v11, v7
	v_log_f32_e32 v7, v7
	v_mul_f32_e32 v11, v14, v15
	v_rcp_f32_e32 v14, v0
	v_mul_f32_e32 v10, 0x3f317217, v7
	v_fma_f32 v10, v7, s36, -v10
	v_fmac_f32_e32 v10, 0x3377d1cf, v7
	v_fmac_f32_e32 v10, 0x3f317217, v7
	v_cmp_lt_f32_e64 s[42:43], |v7|, s37
	s_nop 1
	v_cndmask_b32_e64 v7, v7, v10, s[42:43]
	v_cndmask_b32_e32 v10, 0, v191, vcc
	v_sub_f32_e32 v7, v7, v10
	global_store_dwordx4 v[24:25], v[4:7], off offset:512
	s_nop 0
	v_mov_b64_e32 v[4:5], v[216:217]
	v_mov_b64_e32 v[6:7], v[218:219]
	v_mov_b32_e32 v15, v4
	v_pk_add_f32 v[18:19], v[14:15], 1.0 op_sel_hi:[1,0] neg_lo:[1,0] neg_hi:[1,0]
	s_nop 0
	v_fma_f32 v0, v14, v19, v4
	v_cmp_gt_f32_e32 vcc, s31, v0
	v_mul_f32_e32 v10, v18, v19
	v_cvt_pk_bf16_f32 v18, v12, v8
	v_cvt_pk_bf16_f32 v19, v9, v11
	s_nop 0
	v_cndmask_b32_e64 v4, 0, 32, vcc
	v_ldexp_f32 v0, v0, v4
	v_log_f32_e32 v0, v0
	s_nop 0
	v_mul_f32_e32 v4, 0x3f317217, v0
	v_fma_f32 v4, v0, s36, -v4
	v_fmac_f32_e32 v4, 0x3377d1cf, v0
	v_fmac_f32_e32 v4, 0x3f317217, v0
	v_cmp_lt_f32_e64 s[42:43], |v0|, s37
	s_nop 1
	v_cndmask_b32_e64 v0, v0, v4, s[42:43]
	v_cndmask_b32_e32 v4, 0, v191, vcc
	v_sub_f32_e32 v0, v0, v4
	v_rcp_f32_e32 v4, v1
	s_nop 0
	v_pk_add_f32 v[14:15], v[4:5], 1.0 op_sel_hi:[1,0] neg_lo:[1,0] neg_hi:[1,0]
	s_nop 0
	v_fma_f32 v1, v4, v15, v5
	v_cmp_gt_f32_e32 vcc, s31, v1
	v_mov_b32_e32 v5, v6
	v_mul_f32_e32 v13, v14, v15
	v_cndmask_b32_e64 v4, 0, 32, vcc
	v_ldexp_f32 v1, v1, v4
	v_log_f32_e32 v1, v1
	v_cvt_pk_bf16_f32 v20, v10, v13
	s_nop 0
	v_mul_f32_e32 v4, 0x3f317217, v1
	v_fma_f32 v4, v1, s36, -v4
	v_fmac_f32_e32 v4, 0x3377d1cf, v1
	v_fmac_f32_e32 v4, 0x3f317217, v1
	v_cmp_lt_f32_e64 s[42:43], |v1|, s37
	s_nop 1
	v_cndmask_b32_e64 v1, v1, v4, s[42:43]
	v_cndmask_b32_e32 v4, 0, v191, vcc
	v_sub_f32_e32 v1, v1, v4
	v_rcp_f32_e32 v4, v2
	s_nop 0
	v_pk_add_f32 v[14:15], v[4:5], 1.0 op_sel_hi:[1,0] neg_lo:[1,0] neg_hi:[1,0]
	s_nop 0
	v_fma_f32 v2, v4, v15, v6
	v_cmp_gt_f32_e32 vcc, s31, v2
	v_rcp_f32_e32 v6, v3
	s_nop 0
	v_cndmask_b32_e64 v4, 0, 32, vcc
	v_ldexp_f32 v2, v2, v4
	v_log_f32_e32 v2, v2
	s_nop 0
	v_mul_f32_e32 v4, 0x3f317217, v2
	v_fma_f32 v4, v2, s36, -v4
	v_fmac_f32_e32 v4, 0x3377d1cf, v2
	v_fmac_f32_e32 v4, 0x3f317217, v2
	v_cmp_lt_f32_e64 s[42:43], |v2|, s37
	s_nop 1
	v_cndmask_b32_e64 v2, v2, v4, s[42:43]
	v_cndmask_b32_e32 v4, 0, v191, vcc
	v_sub_f32_e32 v2, v2, v4
	v_mul_f32_e32 v4, v14, v15
	v_pk_add_f32 v[14:15], v[6:7], 1.0 op_sel_hi:[1,0] neg_lo:[1,0] neg_hi:[1,0]
	s_nop 0
	v_fmac_f32_e32 v7, v6, v15
	v_cmp_gt_f32_e32 vcc, s31, v7
	s_nop 1
	v_cndmask_b32_e64 v3, 0, 32, vcc
	v_ldexp_f32 v3, v7, v3
	v_log_f32_e32 v3, v3
	s_nop 0
	v_mul_f32_e32 v5, 0x3f317217, v3
	v_fma_f32 v5, v3, s36, -v5
	v_fmac_f32_e32 v5, 0x3377d1cf, v3
	v_fmac_f32_e32 v5, 0x3f317217, v3
	v_cmp_lt_f32_e64 s[42:43], |v3|, s37
	s_nop 1
	v_cndmask_b32_e64 v3, v3, v5, s[42:43]
	v_cndmask_b32_e32 v5, 0, v191, vcc
	v_sub_f32_e32 v3, v3, v5
	v_mul_f32_e32 v5, v14, v15
	global_store_dwordx4 v[24:25], v[0:3], off offset:528
	v_cvt_pk_bf16_f32 v21, v4, v5
	s_branch .LBB0_679

; __device__ __forceinline__ unsigned xb_ld(unsigned* p)              { return __hip_atomic_load(p, __ATOMIC_RELAXED, __HIP_MEMORY_SCOPE_AGENT); }
; __device__ __forceinline__ void xcd_barrier_complete(unsigned* bar, unsigned x, unsigned& nloc, unsigned& nx) {
;     ...
;     for (;;) {
;         sum = 0u; cnt = 0u; mine = 0u;
; #pragma unroll
;         for (unsigned j = 0; j < 16; ++j) { const unsigned c = xb_ld(&bar[XB_XCNT(j)]); sum += c; cnt += (c > 0u) ? 1u : 0u; mine = (j == x) ? c : mine; }
;         if (sum == G) break;
;         __builtin_amdgcn_s_sleep(1);
;         if ((++sp & 255u) == 0u) { if (xb_ld(&bar[XB_TMO])) break; if (sp > XB_SPIN_CAP) { atomicAdd(&bar[XB_TMO], 1u); break; } }
;     }
.LBB0_991:
	v_readlane_b32 s2, v253, 11
	v_readlane_b32 s3, v253, 12
	s_mov_b64 s[4:5], -1
	s_waitcnt lgkmcnt(0)
	s_nop 2
	global_load_dword v0, v17, s[2:3] sc1
	v_readlane_b32 s2, v253, 13
	v_readlane_b32 s3, v253, 14
	s_nop 4
	global_load_dword v1, v17, s[2:3] sc1
	v_readlane_b32 s2, v253, 15
	v_readlane_b32 s3, v253, 16
	s_nop 0
	s_nop 0
	s_nop 2
	global_load_dword v2, v17, s[2:3] sc1
	v_readlane_b32 s2, v253, 17
	v_readlane_b32 s3, v253, 18
	s_nop 0
	s_nop 0
	s_nop 2
	global_load_dword v3, v17, s[2:3] sc1
	v_readlane_b32 s2, v253, 19
	v_readlane_b32 s3, v253, 20
	s_nop 0
	s_nop 0
	s_nop 2
	global_load_dword v4, v17, s[2:3] sc1
	v_readlane_b32 s2, v253, 21
	v_readlane_b32 s3, v253, 22
	s_nop 0
	s_nop 0
	s_nop 2
	global_load_dword v5, v17, s[2:3] sc1
	v_readlane_b32 s2, v253, 23
	v_readlane_b32 s3, v253, 24
	s_nop 0
	s_nop 0
	s_nop 2
	global_load_dword v6, v17, s[2:3] sc1
	v_readlane_b32 s2, v253, 25
	v_readlane_b32 s3, v253, 26
	s_nop 0
	s_nop 0
	s_nop 2
	global_load_dword v7, v17, s[2:3] sc1
	v_readlane_b32 s2, v253, 27
	v_readlane_b32 s3, v253, 28
	s_nop 0
	s_nop 0
	s_nop 2
	global_load_dword v8, v17, s[2:3] sc1
	v_readlane_b32 s2, v253, 29
	v_readlane_b32 s3, v253, 30
	s_nop 0
	s_nop 0
	s_nop 2
	global_load_dword v9, v17, s[2:3] sc1
	v_readlane_b32 s2, v253, 31
	v_readlane_b32 s3, v253, 32
	s_nop 0
	s_nop 0
	s_nop 2
	global_load_dword v10, v17, s[2:3] sc1
	v_readlane_b32 s2, v253, 33
	v_readlane_b32 s3, v253, 34
	s_nop 0
	s_nop 0
	s_nop 2
	global_load_dword v11, v17, s[2:3] sc1
	v_readlane_b32 s2, v253, 35
	v_readlane_b32 s3, v253, 36
	s_nop 0
	s_nop 0
	s_nop 2
	global_load_dword v12, v17, s[2:3] sc1
	v_readlane_b32 s2, v253, 37
	v_readlane_b32 s3, v253, 38
	s_nop 0
	s_nop 0
	s_nop 2
	global_load_dword v13, v17, s[2:3] sc1
	v_readlane_b32 s2, v253, 39
	v_readlane_b32 s3, v253, 40
	s_nop 0
	s_nop 0
	s_nop 2
	global_load_dword v14, v17, s[2:3] sc1
	v_readlane_b32 s2, v253, 41
	v_readlane_b32 s3, v253, 42
	s_nop 0
	s_nop 0
	s_nop 2
	global_load_dword v15, v17, s[2:3] sc1
	s_mov_b64 s[2:3], -1
	s_waitcnt vmcnt(0)
	v_add_u32_e32 v16, v1, v0
	v_add_u32_e32 v16, v16, v2
	v_add_u32_e32 v16, v16, v3
	v_add_u32_e32 v16, v16, v4
	v_add_u32_e32 v16, v16, v5
	v_add_u32_e32 v16, v16, v6
	v_add_u32_e32 v16, v16, v7
	v_add_u32_e32 v16, v16, v8
	v_add_u32_e32 v16, v16, v9
	v_add_u32_e32 v16, v16, v10
	v_add_u32_e32 v16, v16, v11
	v_add_u32_e32 v16, v16, v12
	v_add_u32_e32 v16, v16, v13
	v_add_u32_e32 v16, v16, v14
	v_add_u32_e32 v16, v16, v15
	v_cmp_eq_u32_e32 vcc, s67, v16
	s_cbranch_vccnz .LBB0_990
	s_and_b32 s2, s22, 0xff
	s_cmp_eq_u32 s2, 0
	s_mov_b64 s[2:3], -1
	s_mov_b64 s[18:19], -1
	s_sleep 1
	s_cbranch_scc1 .LBB0_995
	s_and_b64 vcc, exec, s[18:19]
	s_cbranch_vccz .LBB0_990
